# 8-phase GEMM main loops: cluster-end barrier hoisted above the last MFMA only (k=1, trailing MFMA at priority 2)
# baseline (speedup 1.0000x reference)
.LBB0_114:
	ds_read_b128 v[152:155], v148
	ds_read_b128 v[156:159], v148 offset:1024
	ds_read_b128 v[160:163], v148 offset:2048
	ds_read_b128 v[164:167], v148 offset:3072
	s_add_u32 s38, s36, 0xfff80080
	s_addc_u32 s39, s37, -1
	s_cmp_eq_u32 s63, 28
	s_cselect_b32 s41, s4, s39
	s_cselect_b32 s40, s5, s38
	s_cselect_b32 s39, s23, s29
	s_cselect_b32 s38, s26, s27
	v_lshl_add_u64 v[188:189], s[36:37], 0, v[138:139]
	s_add_i32 m0, s19, 0xc000
	ds_read_b128 v[168:171], v149
	ds_read_b128 v[172:175], v149 offset:1024
	ds_read_b128 v[176:179], v149 offset:2048
	ds_read_b128 v[180:183], v149 offset:3072
	ds_read_b128 v[184:187], v149 offset:4096
	ds_read_b128 v[192:195], v149 offset:5120
	ds_read_b128 v[196:199], v149 offset:6144
	ds_read_b128 v[200:203], v149 offset:7168
	global_load_lds_dwordx4 v[188:189], off
	v_lshl_add_u64 v[188:189], s[36:37], 0, v[140:141]
	s_add_i32 m0, s19, 0xe000
	s_nop 0
	global_load_lds_dwordx4 v[188:189], off
	s_waitcnt lgkmcnt(8)
	s_barrier
	s_waitcnt lgkmcnt(0)
	s_setprio 1
	s_waitcnt lgkmcnt(0)
	v_mfma_f32_16x16x32_bf16 v[126:129], v[152:155], v[168:171], v[126:129]
	v_mfma_f32_16x16x32_bf16 v[122:125], v[160:163], v[168:171], v[122:125]
	v_mfma_f32_16x16x32_bf16 v[118:121], v[152:155], v[176:179], v[118:121]
	v_mfma_f32_16x16x32_bf16 v[114:117], v[160:163], v[176:179], v[114:117]
	v_mfma_f32_16x16x32_bf16 v[102:105], v[152:155], v[184:187], v[102:105]
	v_mfma_f32_16x16x32_bf16 v[98:101], v[160:163], v[184:187], v[98:101]
	v_mfma_f32_16x16x32_bf16 v[86:89], v[152:155], v[196:199], v[86:89]
	v_mfma_f32_16x16x32_bf16 v[82:85], v[160:163], v[196:199], v[82:85]
	v_mfma_f32_16x16x32_bf16 v[126:129], v[156:159], v[172:175], v[126:129]
	v_mfma_f32_16x16x32_bf16 v[122:125], v[164:167], v[172:175], v[122:125]
	v_mfma_f32_16x16x32_bf16 v[118:121], v[156:159], v[180:183], v[118:121]
	v_mfma_f32_16x16x32_bf16 v[114:117], v[164:167], v[180:183], v[114:117]
	v_mfma_f32_16x16x32_bf16 v[102:105], v[156:159], v[192:195], v[102:105]
	v_mfma_f32_16x16x32_bf16 v[98:101], v[164:167], v[192:195], v[98:101]
	v_mfma_f32_16x16x32_bf16 v[86:89], v[156:159], v[200:203], v[86:89]
	s_setprio 2
	s_barrier
	v_mfma_f32_16x16x32_bf16 v[82:85], v[164:167], v[200:203], v[82:85]
	s_setprio 0
	s_add_i32 s64, s57, s47
	v_lshl_add_u64 v[188:189], s[38:39], 0, v[132:133]
	s_mov_b32 m0, s64
	ds_read_b128 v[204:207], v150
	ds_read_b128 v[208:211], v150 offset:1024
	ds_read_b128 v[212:215], v150 offset:2048
	ds_read_b128 v[216:219], v150 offset:3072
	global_load_lds_dwordx4 v[188:189], off
	v_lshl_add_u64 v[220:221], s[38:39], 0, v[136:137]
	s_add_i32 m0, s64, 0x2000
	s_nop 0
	global_load_lds_dwordx4 v[220:221], off
	s_barrier
	s_waitcnt lgkmcnt(0)
	s_setprio 1
	s_waitcnt lgkmcnt(0)
	v_mfma_f32_16x16x32_bf16 v[110:113], v[204:207], v[168:171], v[110:113]
	v_mfma_f32_16x16x32_bf16 v[106:109], v[212:215], v[168:171], v[106:109]
	v_mfma_f32_16x16x32_bf16 v[94:97], v[204:207], v[176:179], v[94:97]
	v_mfma_f32_16x16x32_bf16 v[90:93], v[212:215], v[176:179], v[90:93]
	v_mfma_f32_16x16x32_bf16 v[78:81], v[204:207], v[184:187], v[78:81]
	v_mfma_f32_16x16x32_bf16 v[74:77], v[212:215], v[184:187], v[74:77]
	v_mfma_f32_16x16x32_bf16 v[70:73], v[204:207], v[196:199], v[70:73]
	v_mfma_f32_16x16x32_bf16 v[66:69], v[212:215], v[196:199], v[66:69]
	v_mfma_f32_16x16x32_bf16 v[110:113], v[208:211], v[172:175], v[110:113]
	v_mfma_f32_16x16x32_bf16 v[106:109], v[216:219], v[172:175], v[106:109]
	v_mfma_f32_16x16x32_bf16 v[94:97], v[208:211], v[180:183], v[94:97]
	v_mfma_f32_16x16x32_bf16 v[90:93], v[216:219], v[180:183], v[90:93]
	v_mfma_f32_16x16x32_bf16 v[78:81], v[208:211], v[192:195], v[78:81]
	v_mfma_f32_16x16x32_bf16 v[74:77], v[216:219], v[192:195], v[74:77]
	v_mfma_f32_16x16x32_bf16 v[70:73], v[208:211], v[200:203], v[70:73]
	s_setprio 2
	s_mov_b32 m0, s19
	v_lshl_add_u64 v[222:223], s[40:41], 0, v[130:131]
	s_barrier
	v_mfma_f32_16x16x32_bf16 v[66:69], v[216:219], v[200:203], v[66:69]
	s_setprio 0
	ds_read_b128 v[168:171], v149 offset:16384
	ds_read_b128 v[172:175], v149 offset:17408
	ds_read_b128 v[176:179], v149 offset:18432
	ds_read_b128 v[180:183], v149 offset:19456
	ds_read_b128 v[184:187], v149 offset:20480
	ds_read_b128 v[192:195], v149 offset:21504
	ds_read_b128 v[196:199], v149 offset:22528
	ds_read_b128 v[200:203], v149 offset:23552
	global_load_lds_dwordx4 v[222:223], off
	v_lshl_add_u64 v[224:225], s[40:41], 0, v[134:135]
	s_mov_b32 m0, s21
	s_nop 0
	global_load_lds_dwordx4 v[224:225], off
	s_barrier
	s_waitcnt lgkmcnt(0)
	s_setprio 1
	s_waitcnt lgkmcnt(0)
	v_mfma_f32_16x16x32_bf16 v[62:65], v[152:155], v[168:171], v[62:65]
	v_mfma_f32_16x16x32_bf16 v[58:61], v[160:163], v[168:171], v[58:61]
	v_mfma_f32_16x16x32_bf16 v[54:57], v[152:155], v[176:179], v[54:57]
	v_mfma_f32_16x16x32_bf16 v[50:53], v[160:163], v[176:179], v[50:53]
	v_mfma_f32_16x16x32_bf16 v[38:41], v[152:155], v[184:187], v[38:41]
	v_mfma_f32_16x16x32_bf16 v[34:37], v[160:163], v[184:187], v[34:37]
	v_mfma_f32_16x16x32_bf16 v[22:25], v[152:155], v[196:199], v[22:25]
	v_mfma_f32_16x16x32_bf16 v[18:21], v[160:163], v[196:199], v[18:21]
	v_mfma_f32_16x16x32_bf16 v[62:65], v[156:159], v[172:175], v[62:65]
	v_mfma_f32_16x16x32_bf16 v[58:61], v[164:167], v[172:175], v[58:61]
	v_mfma_f32_16x16x32_bf16 v[54:57], v[156:159], v[180:183], v[54:57]
	v_mfma_f32_16x16x32_bf16 v[50:53], v[164:167], v[180:183], v[50:53]
	v_mfma_f32_16x16x32_bf16 v[38:41], v[156:159], v[192:195], v[38:41]
	v_mfma_f32_16x16x32_bf16 v[34:37], v[164:167], v[192:195], v[34:37]
	v_mfma_f32_16x16x32_bf16 v[22:25], v[156:159], v[200:203], v[22:25]
	s_setprio 2
	s_barrier
	v_mfma_f32_16x16x32_bf16 v[18:21], v[164:167], v[200:203], v[18:21]
	s_setprio 0
	s_add_u32 s64, s38, 0x80000
	s_addc_u32 s65, s39, 0
	s_add_i32 s66, s58, s47
	v_lshl_add_u64 v[152:153], s[64:65], 0, v[132:133]
	s_mov_b32 m0, s66
	s_nop 0
	global_load_lds_dwordx4 v[152:153], off
	v_lshl_add_u64 v[152:153], s[64:65], 0, v[136:137]
	s_add_i32 m0, s66, 0x2000
	s_nop 0
	global_load_lds_dwordx4 v[152:153], off
	s_waitcnt vmcnt(6)
	s_barrier
	s_setprio 1
	v_mfma_f32_16x16x32_bf16 v[46:49], v[204:207], v[168:171], v[46:49]
	v_mfma_f32_16x16x32_bf16 v[42:45], v[212:215], v[168:171], v[42:45]
	v_mfma_f32_16x16x32_bf16 v[30:33], v[204:207], v[176:179], v[30:33]
	v_mfma_f32_16x16x32_bf16 v[26:29], v[212:215], v[176:179], v[26:29]
	v_mfma_f32_16x16x32_bf16 v[14:17], v[204:207], v[184:187], v[14:17]
	v_mfma_f32_16x16x32_bf16 v[10:13], v[212:215], v[184:187], v[10:13]
	v_mfma_f32_16x16x32_bf16 v[6:9], v[204:207], v[196:199], v[6:9]
	v_mfma_f32_16x16x32_bf16 v[2:5], v[212:215], v[196:199], v[2:5]
	v_mfma_f32_16x16x32_bf16 v[46:49], v[208:211], v[172:175], v[46:49]
	v_mfma_f32_16x16x32_bf16 v[42:45], v[216:219], v[172:175], v[42:45]
	v_mfma_f32_16x16x32_bf16 v[30:33], v[208:211], v[180:183], v[30:33]
	v_mfma_f32_16x16x32_bf16 v[26:29], v[216:219], v[180:183], v[26:29]
	v_mfma_f32_16x16x32_bf16 v[14:17], v[208:211], v[192:195], v[14:17]
	v_mfma_f32_16x16x32_bf16 v[10:13], v[216:219], v[192:195], v[10:13]
	v_mfma_f32_16x16x32_bf16 v[6:9], v[208:211], v[200:203], v[6:9]
	s_setprio 2
	s_add_i32 s64, 0, 0x18000
	v_add_u32_e32 v151, s64, v146
	s_barrier
	v_mfma_f32_16x16x32_bf16 v[2:5], v[216:219], v[200:203], v[2:5]
	s_setprio 0
	ds_read_b128 v[152:155], v151
	ds_read_b128 v[156:159], v151 offset:1024
	ds_read_b128 v[160:163], v151 offset:2048
	ds_read_b128 v[164:167], v151 offset:3072
	s_add_u32 s40, s40, 0x80000
	s_addc_u32 s41, s41, 0
	s_mov_b32 m0, s48
	v_lshl_add_u64 v[204:205], s[40:41], 0, v[130:131]
	ds_read_b128 v[168:171], v149 offset:32768
	ds_read_b128 v[172:175], v149 offset:33792
	ds_read_b128 v[176:179], v149 offset:34816
	ds_read_b128 v[180:183], v149 offset:35840
	ds_read_b128 v[184:187], v149 offset:36864
	ds_read_b128 v[192:195], v149 offset:37888
	ds_read_b128 v[196:199], v149 offset:38912
	ds_read_b128 v[200:203], v149 offset:39936
	global_load_lds_dwordx4 v[204:205], off
	v_lshl_add_u64 v[204:205], s[40:41], 0, v[134:135]
	s_mov_b32 m0, s49
	s_nop 0
	global_load_lds_dwordx4 v[204:205], off
	s_waitcnt lgkmcnt(8)
	s_barrier
	s_waitcnt lgkmcnt(0)
	s_setprio 1
	s_waitcnt lgkmcnt(0)
	v_mfma_f32_16x16x32_bf16 v[126:129], v[152:155], v[168:171], v[126:129]
	v_mfma_f32_16x16x32_bf16 v[122:125], v[160:163], v[168:171], v[122:125]
	v_mfma_f32_16x16x32_bf16 v[118:121], v[152:155], v[176:179], v[118:121]
	v_mfma_f32_16x16x32_bf16 v[114:117], v[160:163], v[176:179], v[114:117]
	v_mfma_f32_16x16x32_bf16 v[102:105], v[152:155], v[184:187], v[102:105]
	v_mfma_f32_16x16x32_bf16 v[98:101], v[160:163], v[184:187], v[98:101]
	v_mfma_f32_16x16x32_bf16 v[86:89], v[152:155], v[196:199], v[86:89]
	v_mfma_f32_16x16x32_bf16 v[82:85], v[160:163], v[196:199], v[82:85]
	v_mfma_f32_16x16x32_bf16 v[126:129], v[156:159], v[172:175], v[126:129]
	v_mfma_f32_16x16x32_bf16 v[122:125], v[164:167], v[172:175], v[122:125]
	v_mfma_f32_16x16x32_bf16 v[118:121], v[156:159], v[180:183], v[118:121]
	v_mfma_f32_16x16x32_bf16 v[114:117], v[164:167], v[180:183], v[114:117]
	v_mfma_f32_16x16x32_bf16 v[102:105], v[156:159], v[192:195], v[102:105]
	v_mfma_f32_16x16x32_bf16 v[98:101], v[164:167], v[192:195], v[98:101]
	v_mfma_f32_16x16x32_bf16 v[86:89], v[156:159], v[200:203], v[86:89]
	s_setprio 2
	s_barrier
	v_mfma_f32_16x16x32_bf16 v[82:85], v[164:167], v[200:203], v[82:85]
	s_setprio 0
	s_add_i32 s40, 0, 0x1c000
	s_add_i32 s41, s64, s47
	v_add_u32_e32 v151, s40, v146
	v_lshl_add_u64 v[188:189], v[188:189], 0, s[10:11]
	s_mov_b32 m0, s41
	ds_read_b128 v[204:207], v151
	ds_read_b128 v[208:211], v151 offset:1024
	ds_read_b128 v[212:215], v151 offset:2048
	ds_read_b128 v[216:219], v151 offset:3072
	global_load_lds_dwordx4 v[188:189], off
	v_lshl_add_u64 v[188:189], v[220:221], 0, s[10:11]
	s_add_i32 m0, s41, 0x2000
	s_nop 0
	global_load_lds_dwordx4 v[188:189], off
	s_barrier
	s_waitcnt lgkmcnt(0)
	s_setprio 1
	s_waitcnt lgkmcnt(0)
	v_mfma_f32_16x16x32_bf16 v[110:113], v[204:207], v[168:171], v[110:113]
	v_mfma_f32_16x16x32_bf16 v[106:109], v[212:215], v[168:171], v[106:109]
	v_mfma_f32_16x16x32_bf16 v[94:97], v[204:207], v[176:179], v[94:97]
	v_mfma_f32_16x16x32_bf16 v[90:93], v[212:215], v[176:179], v[90:93]
	v_mfma_f32_16x16x32_bf16 v[78:81], v[204:207], v[184:187], v[78:81]
	v_mfma_f32_16x16x32_bf16 v[74:77], v[212:215], v[184:187], v[74:77]
	v_mfma_f32_16x16x32_bf16 v[70:73], v[204:207], v[196:199], v[70:73]
	v_mfma_f32_16x16x32_bf16 v[66:69], v[212:215], v[196:199], v[66:69]
	v_mfma_f32_16x16x32_bf16 v[110:113], v[208:211], v[172:175], v[110:113]
	v_mfma_f32_16x16x32_bf16 v[106:109], v[216:219], v[172:175], v[106:109]
	v_mfma_f32_16x16x32_bf16 v[94:97], v[208:211], v[180:183], v[94:97]
	v_mfma_f32_16x16x32_bf16 v[90:93], v[216:219], v[180:183], v[90:93]
	v_mfma_f32_16x16x32_bf16 v[78:81], v[208:211], v[192:195], v[78:81]
	v_mfma_f32_16x16x32_bf16 v[74:77], v[216:219], v[192:195], v[74:77]
	v_mfma_f32_16x16x32_bf16 v[70:73], v[208:211], v[200:203], v[70:73]
	s_setprio 2
	s_mov_b32 m0, s53
	v_lshl_add_u64 v[188:189], v[222:223], 0, s[10:11]
	s_barrier
	v_mfma_f32_16x16x32_bf16 v[66:69], v[216:219], v[200:203], v[66:69]
	s_setprio 0
	ds_read_b128 v[168:171], v149 offset:49152
	ds_read_b128 v[172:175], v149 offset:50176
	ds_read_b128 v[176:179], v149 offset:51200
	ds_read_b128 v[180:183], v149 offset:52224
	ds_read_b128 v[184:187], v149 offset:53248
	ds_read_b128 v[192:195], v149 offset:54272
	ds_read_b128 v[196:199], v149 offset:55296
	ds_read_b128 v[200:203], v149 offset:56320
	global_load_lds_dwordx4 v[188:189], off
	v_lshl_add_u64 v[188:189], v[224:225], 0, s[10:11]
	s_mov_b32 m0, s54
	s_nop 0
	global_load_lds_dwordx4 v[188:189], off
	s_barrier
	s_waitcnt lgkmcnt(0)
	s_setprio 1
	s_waitcnt lgkmcnt(0)
	v_mfma_f32_16x16x32_bf16 v[62:65], v[152:155], v[168:171], v[62:65]
	v_mfma_f32_16x16x32_bf16 v[58:61], v[160:163], v[168:171], v[58:61]
	v_mfma_f32_16x16x32_bf16 v[54:57], v[152:155], v[176:179], v[54:57]
	v_mfma_f32_16x16x32_bf16 v[50:53], v[160:163], v[176:179], v[50:53]
	v_mfma_f32_16x16x32_bf16 v[38:41], v[152:155], v[184:187], v[38:41]
	v_mfma_f32_16x16x32_bf16 v[34:37], v[160:163], v[184:187], v[34:37]
	v_mfma_f32_16x16x32_bf16 v[22:25], v[152:155], v[196:199], v[22:25]
	v_mfma_f32_16x16x32_bf16 v[18:21], v[160:163], v[196:199], v[18:21]
	v_mfma_f32_16x16x32_bf16 v[62:65], v[156:159], v[172:175], v[62:65]
	v_mfma_f32_16x16x32_bf16 v[58:61], v[164:167], v[172:175], v[58:61]
	v_mfma_f32_16x16x32_bf16 v[54:57], v[156:159], v[180:183], v[54:57]
	v_mfma_f32_16x16x32_bf16 v[50:53], v[164:167], v[180:183], v[50:53]
	v_mfma_f32_16x16x32_bf16 v[38:41], v[156:159], v[192:195], v[38:41]
	v_mfma_f32_16x16x32_bf16 v[34:37], v[164:167], v[192:195], v[34:37]
	v_mfma_f32_16x16x32_bf16 v[22:25], v[156:159], v[200:203], v[22:25]
	s_setprio 2
	s_barrier
	v_mfma_f32_16x16x32_bf16 v[18:21], v[164:167], v[200:203], v[18:21]
	s_setprio 0
	s_add_u32 s38, s38, 0x80080
	s_addc_u32 s39, s39, 0
	s_add_i32 s40, s40, s47
	v_lshl_add_u64 v[152:153], s[38:39], 0, v[132:133]
	s_mov_b32 m0, s40
	s_nop 0
	global_load_lds_dwordx4 v[152:153], off
	v_lshl_add_u64 v[152:153], s[38:39], 0, v[136:137]
	s_add_i32 m0, s40, 0x2000
	s_nop 0
	global_load_lds_dwordx4 v[152:153], off
	s_waitcnt vmcnt(6)
	s_barrier
	s_setprio 1
	v_mfma_f32_16x16x32_bf16 v[46:49], v[204:207], v[168:171], v[46:49]
	v_mfma_f32_16x16x32_bf16 v[42:45], v[212:215], v[168:171], v[42:45]
	v_mfma_f32_16x16x32_bf16 v[30:33], v[204:207], v[176:179], v[30:33]
	v_mfma_f32_16x16x32_bf16 v[26:29], v[212:215], v[176:179], v[26:29]
	v_mfma_f32_16x16x32_bf16 v[14:17], v[204:207], v[184:187], v[14:17]
	v_mfma_f32_16x16x32_bf16 v[10:13], v[212:215], v[184:187], v[10:13]
	v_mfma_f32_16x16x32_bf16 v[6:9], v[204:207], v[196:199], v[6:9]
	v_mfma_f32_16x16x32_bf16 v[2:5], v[212:215], v[196:199], v[2:5]
	v_mfma_f32_16x16x32_bf16 v[46:49], v[208:211], v[172:175], v[46:49]
	v_mfma_f32_16x16x32_bf16 v[42:45], v[216:219], v[172:175], v[42:45]
	v_mfma_f32_16x16x32_bf16 v[30:33], v[208:211], v[180:183], v[30:33]
	v_mfma_f32_16x16x32_bf16 v[26:29], v[216:219], v[180:183], v[26:29]
	v_mfma_f32_16x16x32_bf16 v[14:17], v[208:211], v[192:195], v[14:17]
	v_mfma_f32_16x16x32_bf16 v[10:13], v[216:219], v[192:195], v[10:13]
	v_mfma_f32_16x16x32_bf16 v[6:9], v[208:211], v[200:203], v[6:9]
	s_setprio 2
	s_add_i32 s63, s63, 2
	s_add_u32 s36, s36, 0x100
	s_addc_u32 s37, s37, 0
	s_add_u32 s27, s27, 0x100
	s_addc_u32 s29, s29, 0
	s_cmp_gt_u32 s63, 29
	s_barrier
	v_mfma_f32_16x16x32_bf16 v[2:5], v[216:219], v[200:203], v[2:5]
	s_setprio 0
	s_cbranch_scc0 .LBB0_114
	s_ashr_i32 s4, s18, 31
	s_lshr_b32 s4, s4, 29
	s_add_i32 s4, s18, s4
	s_lshl_b32 s5, s20, 8
	s_ashr_i32 s4, s4, 3
	s_and_b32 s5, s5, 0x3f00
	v_add_u32_e32 v152, s5, v1
	s_lshl_b32 s5, s4, 11
	s_lshl_b32 s18, s18, 8
	s_sub_i32 s5, s18, s5
	v_or_b32_e32 v154, s5, v147
	s_ashr_i32 s5, s4, 31
	s_lshl_b64 s[4:5], s[4:5], 26
	s_add_u32 s4, s51, s4
	s_addc_u32 s5, s52, s5
	v_ashrrev_i32_e32 v155, 31, v154
	v_ashrrev_i32_e32 v153, 31, v152
	v_lshl_add_u64 v[154:155], v[154:155], 1, s[4:5]
	v_lshlrev_b64 v[156:157], 12, v[152:153]
	v_lshl_add_u64 v[156:157], v[154:155], 0, v[156:157]
	v_cvt_pk_bf16_f32 v62, v62, v63
	v_cvt_pk_bf16_f32 v63, v64, v65
	v_cvt_pk_bf16_f32 v64, v58, v59
	v_add_co_u32_e32 v58, vcc, s59, v156
	v_cvt_pk_bf16_f32 v70, v70, v71
	v_cvt_pk_bf16_f32 v71, v72, v73
	v_cvt_pk_bf16_f32 v72, v66, v67
	v_lshl_add_u64 v[66:67], v[156:157], 0, s[8:9]
	v_addc_co_u32_e32 v59, vcc, 0, v157, vcc
	v_cvt_pk_bf16_f32 v46, v46, v47
	v_cvt_pk_bf16_f32 v47, v48, v49
	v_cvt_pk_bf16_f32 v48, v42, v43
	v_cvt_pk_bf16_f32 v49, v44, v45
	global_store_dwordx4 v[66:67], v[46:49], off offset:256
	v_cvt_pk_bf16_f32 v110, v110, v111
	v_cvt_pk_bf16_f32 v111, v112, v113
	v_add_co_u32_e32 v48, vcc, s60, v156
	v_cvt_pk_bf16_f32 v112, v106, v107
	v_or_b32_e32 v106, 16, v152
	v_lshl_add_u64 v[46:47], v[156:157], 0, s[12:13]
	v_addc_co_u32_e32 v49, vcc, 0, v157, vcc
	v_cvt_pk_bf16_f32 v30, v30, v31
	v_cvt_pk_bf16_f32 v31, v32, v33
	v_cvt_pk_bf16_f32 v32, v26, v27
	v_cvt_pk_bf16_f32 v33, v28, v29
	v_ashrrev_i32_e32 v107, 31, v106
	v_cvt_pk_bf16_f32 v94, v94, v95
	v_cvt_pk_bf16_f32 v95, v96, v97
	v_cvt_pk_bf16_f32 v96, v90, v91
	v_or_b32_e32 v90, 32, v152
	global_store_dwordx4 v[46:47], v[30:33], off offset:256
	v_cvt_pk_bf16_f32 v113, v108, v109
	v_lshlrev_b64 v[106:107], 12, v[106:107]
	v_add_co_u32_e32 v32, vcc, s61, v156
	v_ashrrev_i32_e32 v91, 31, v90
	v_cvt_pk_bf16_f32 v78, v78, v79
	v_cvt_pk_bf16_f32 v79, v80, v81
	v_cvt_pk_bf16_f32 v80, v74, v75
	v_or_b32_e32 v74, 48, v152
	v_lshl_add_u64 v[30:31], v[156:157], 0, s[14:15]
	v_addc_co_u32_e32 v33, vcc, 0, v157, vcc
	v_cvt_pk_bf16_f32 v14, v14, v15
	v_cvt_pk_bf16_f32 v15, v16, v17
	v_cvt_pk_bf16_f32 v16, v10, v11
	v_cvt_pk_bf16_f32 v17, v12, v13
	global_store_dwordx4 v[156:157], v[110:113], off offset:256
	v_cvt_pk_bf16_f32 v97, v92, v93
	v_lshlrev_b64 v[90:91], 12, v[90:91]
	v_lshl_add_u64 v[110:111], v[154:155], 0, v[106:107]
	v_ashrrev_i32_e32 v75, 31, v74
	global_store_dwordx4 v[30:31], v[14:17], off offset:256
	global_store_dwordx4 v[110:111], v[94:97], off offset:256
	v_cvt_pk_bf16_f32 v81, v76, v77
	v_add_co_u32_e32 v16, vcc, s62, v156
	v_lshl_add_u64 v[94:95], v[154:155], 0, v[90:91]
	v_lshlrev_b64 v[74:75], 12, v[74:75]
	v_addc_co_u32_e32 v17, vcc, 0, v157, vcc
	v_cvt_pk_bf16_f32 v126, v126, v127
	v_cvt_pk_bf16_f32 v127, v128, v129
	v_cvt_pk_bf16_f32 v128, v122, v123
	v_cvt_pk_bf16_f32 v129, v124, v125
	v_cvt_pk_bf16_f32 v106, v118, v119
	v_cvt_pk_bf16_f32 v107, v120, v121
	v_cvt_pk_bf16_f32 v108, v114, v115
	v_cvt_pk_bf16_f32 v109, v116, v117
	v_cvt_pk_bf16_f32 v90, v102, v103
	v_cvt_pk_bf16_f32 v91, v104, v105
	v_cvt_pk_bf16_f32 v92, v98, v99
	v_cvt_pk_bf16_f32 v93, v100, v101
	global_store_dwordx4 v[94:95], v[78:81], off offset:256
	v_cvt_pk_bf16_f32 v76, v82, v83
	v_cvt_pk_bf16_f32 v77, v84, v85
	v_lshl_add_u64 v[78:79], v[154:155], 0, v[74:75]
	v_cvt_pk_bf16_f32 v74, v86, v87
	v_cvt_pk_bf16_f32 v75, v88, v89
	v_cvt_pk_bf16_f32 v73, v68, v69
	v_cvt_pk_bf16_f32 v65, v60, v61
	v_cvt_pk_bf16_f32 v42, v54, v55
	v_cvt_pk_bf16_f32 v43, v56, v57
	v_cvt_pk_bf16_f32 v44, v50, v51
	v_cvt_pk_bf16_f32 v45, v52, v53
	v_cvt_pk_bf16_f32 v26, v38, v39
	v_cvt_pk_bf16_f32 v27, v40, v41
	v_cvt_pk_bf16_f32 v28, v34, v35
	v_cvt_pk_bf16_f32 v29, v36, v37
	v_lshl_add_u64 v[14:15], v[156:157], 0, s[16:17]
	v_cvt_pk_bf16_f32 v10, v22, v23
	v_cvt_pk_bf16_f32 v11, v24, v25
	v_cvt_pk_bf16_f32 v12, v18, v19
	v_cvt_pk_bf16_f32 v13, v20, v21
	v_cvt_pk_bf16_f32 v6, v6, v7
	v_cvt_pk_bf16_f32 v7, v8, v9
	v_cvt_pk_bf16_f32 v8, v2, v3
	v_cvt_pk_bf16_f32 v9, v4, v5
	s_and_b64 vcc, exec, s[6:7]
	s_mov_b32 s18, s28
	s_mov_b32 s20, s22
	s_mov_b64 s[38:39], s[34:35]
	s_mov_b64 s[36:37], s[30:31]
	global_store_dwordx4 v[156:157], v[126:129], off
	global_store_dwordx4 v[110:111], v[106:109], off
	global_store_dwordx4 v[94:95], v[90:93], off
	global_store_dwordx4 v[78:79], v[74:77], off
	global_store_dwordx4 v[78:79], v[70:73], off offset:256
	global_store_dwordx4 v[58:59], v[62:65], off
	global_store_dwordx4 v[48:49], v[42:45], off
	global_store_dwordx4 v[32:33], v[26:29], off
	global_store_dwordx4 v[16:17], v[10:13], off
	global_store_dwordx4 v[14:15], v[6:9], off offset:256
	s_cbranch_vccz .LBB0_107
	s_waitcnt vmcnt(0)
	s_cmpk_gt_u32 s3, 0xff
	s_cbranch_scc1 .LBB0_118
	s_barrier

.LBB0_320:
	ds_read_b128 v[152:155], v149
	ds_read_b128 v[156:159], v149 offset:1024
	ds_read_b128 v[160:163], v149 offset:2048
	ds_read_b128 v[164:167], v149 offset:3072
	s_add_u32 s38, s36, 0xfff80080
	s_addc_u32 s39, s37, -1
	s_cmp_eq_u32 s27, 28
	s_cselect_b32 s41, s4, s39
	s_cselect_b32 s40, s5, s38
	s_cselect_b32 s39, s9, s26
	s_cselect_b32 s38, s21, s23
	v_lshl_add_u64 v[188:189], s[36:37], 0, v[140:141]
	s_add_i32 m0, s35, 0xc000
	ds_read_b128 v[168:171], v150
	ds_read_b128 v[172:175], v150 offset:1024
	ds_read_b128 v[176:179], v150 offset:2048
	ds_read_b128 v[180:183], v150 offset:3072
	ds_read_b128 v[184:187], v150 offset:4096
	ds_read_b128 v[192:195], v150 offset:5120
	ds_read_b128 v[196:199], v150 offset:6144
	ds_read_b128 v[200:203], v150 offset:7168
	global_load_lds_dwordx4 v[188:189], off
	v_lshl_add_u64 v[188:189], s[36:37], 0, v[142:143]
	s_add_i32 m0, s35, 0xe000
	s_nop 0
	global_load_lds_dwordx4 v[188:189], off
	s_waitcnt lgkmcnt(8)
	s_barrier
	s_waitcnt lgkmcnt(0)
	s_setprio 1
	s_waitcnt lgkmcnt(0)
	v_mfma_f32_16x16x32_bf16 v[126:129], v[152:155], v[168:171], v[126:129]
	v_mfma_f32_16x16x32_bf16 v[122:125], v[160:163], v[168:171], v[122:125]
	v_mfma_f32_16x16x32_bf16 v[110:113], v[152:155], v[176:179], v[110:113]
	v_mfma_f32_16x16x32_bf16 v[106:109], v[160:163], v[176:179], v[106:109]
	v_mfma_f32_16x16x32_bf16 v[94:97], v[152:155], v[184:187], v[94:97]
	v_mfma_f32_16x16x32_bf16 v[90:93], v[160:163], v[184:187], v[90:93]
	v_mfma_f32_16x16x32_bf16 v[78:81], v[152:155], v[196:199], v[78:81]
	v_mfma_f32_16x16x32_bf16 v[74:77], v[160:163], v[196:199], v[74:77]
	v_mfma_f32_16x16x32_bf16 v[126:129], v[156:159], v[172:175], v[126:129]
	v_mfma_f32_16x16x32_bf16 v[122:125], v[164:167], v[172:175], v[122:125]
	v_mfma_f32_16x16x32_bf16 v[110:113], v[156:159], v[180:183], v[110:113]
	v_mfma_f32_16x16x32_bf16 v[106:109], v[164:167], v[180:183], v[106:109]
	v_mfma_f32_16x16x32_bf16 v[94:97], v[156:159], v[192:195], v[94:97]
	v_mfma_f32_16x16x32_bf16 v[90:93], v[164:167], v[192:195], v[90:93]
	v_mfma_f32_16x16x32_bf16 v[78:81], v[156:159], v[200:203], v[78:81]
	s_setprio 2
	s_barrier
	v_mfma_f32_16x16x32_bf16 v[74:77], v[164:167], v[200:203], v[74:77]
	s_setprio 0
	s_add_i32 s58, s56, s46
	v_lshl_add_u64 v[188:189], s[38:39], 0, v[132:133]
	s_mov_b32 m0, s58
	ds_read_b128 v[204:207], v151
	ds_read_b128 v[208:211], v151 offset:1024
	ds_read_b128 v[212:215], v151 offset:2048
	ds_read_b128 v[216:219], v151 offset:3072
	global_load_lds_dwordx4 v[188:189], off
	v_lshl_add_u64 v[220:221], s[38:39], 0, v[136:137]
	s_add_i32 m0, s58, 0x2000
	s_nop 0
	global_load_lds_dwordx4 v[220:221], off
	s_barrier
	s_waitcnt lgkmcnt(0)
	s_setprio 1
	s_waitcnt lgkmcnt(0)
	v_mfma_f32_16x16x32_bf16 v[118:121], v[204:207], v[168:171], v[118:121]
	v_mfma_f32_16x16x32_bf16 v[114:117], v[212:215], v[168:171], v[114:117]
	v_mfma_f32_16x16x32_bf16 v[102:105], v[204:207], v[176:179], v[102:105]
	v_mfma_f32_16x16x32_bf16 v[98:101], v[212:215], v[176:179], v[98:101]
	v_mfma_f32_16x16x32_bf16 v[86:89], v[204:207], v[184:187], v[86:89]
	v_mfma_f32_16x16x32_bf16 v[82:85], v[212:215], v[184:187], v[82:85]
	v_mfma_f32_16x16x32_bf16 v[70:73], v[204:207], v[196:199], v[70:73]
	v_mfma_f32_16x16x32_bf16 v[66:69], v[212:215], v[196:199], v[66:69]
	v_mfma_f32_16x16x32_bf16 v[118:121], v[208:211], v[172:175], v[118:121]
	v_mfma_f32_16x16x32_bf16 v[114:117], v[216:219], v[172:175], v[114:117]
	v_mfma_f32_16x16x32_bf16 v[102:105], v[208:211], v[180:183], v[102:105]
	v_mfma_f32_16x16x32_bf16 v[98:101], v[216:219], v[180:183], v[98:101]
	v_mfma_f32_16x16x32_bf16 v[86:89], v[208:211], v[192:195], v[86:89]
	v_mfma_f32_16x16x32_bf16 v[82:85], v[216:219], v[192:195], v[82:85]
	v_mfma_f32_16x16x32_bf16 v[70:73], v[208:211], v[200:203], v[70:73]
	s_setprio 2
	s_mov_b32 m0, s35
	v_lshl_add_u64 v[222:223], s[40:41], 0, v[130:131]
	s_barrier
	v_mfma_f32_16x16x32_bf16 v[66:69], v[216:219], v[200:203], v[66:69]
	s_setprio 0
	ds_read_b128 v[168:171], v150 offset:16384
	ds_read_b128 v[172:175], v150 offset:17408
	ds_read_b128 v[176:179], v150 offset:18432
	ds_read_b128 v[180:183], v150 offset:19456
	ds_read_b128 v[184:187], v150 offset:20480
	ds_read_b128 v[192:195], v150 offset:21504
	ds_read_b128 v[196:199], v150 offset:22528
	ds_read_b128 v[200:203], v150 offset:23552
	global_load_lds_dwordx4 v[222:223], off
	v_lshl_add_u64 v[224:225], s[40:41], 0, v[134:135]
	s_mov_b32 m0, s47
	s_nop 0
	global_load_lds_dwordx4 v[224:225], off
	s_barrier
	s_waitcnt lgkmcnt(0)
	s_setprio 1
	s_waitcnt lgkmcnt(0)
	v_mfma_f32_16x16x32_bf16 v[62:65], v[152:155], v[168:171], v[62:65]
	v_mfma_f32_16x16x32_bf16 v[58:61], v[160:163], v[168:171], v[58:61]
	v_mfma_f32_16x16x32_bf16 v[46:49], v[152:155], v[176:179], v[46:49]
	v_mfma_f32_16x16x32_bf16 v[42:45], v[160:163], v[176:179], v[42:45]
	v_mfma_f32_16x16x32_bf16 v[30:33], v[152:155], v[184:187], v[30:33]
	v_mfma_f32_16x16x32_bf16 v[26:29], v[160:163], v[184:187], v[26:29]
	v_mfma_f32_16x16x32_bf16 v[14:17], v[152:155], v[196:199], v[14:17]
	v_mfma_f32_16x16x32_bf16 v[10:13], v[160:163], v[196:199], v[10:13]
	v_mfma_f32_16x16x32_bf16 v[62:65], v[156:159], v[172:175], v[62:65]
	v_mfma_f32_16x16x32_bf16 v[58:61], v[164:167], v[172:175], v[58:61]
	v_mfma_f32_16x16x32_bf16 v[46:49], v[156:159], v[180:183], v[46:49]
	v_mfma_f32_16x16x32_bf16 v[42:45], v[164:167], v[180:183], v[42:45]
	v_mfma_f32_16x16x32_bf16 v[30:33], v[156:159], v[192:195], v[30:33]
	v_mfma_f32_16x16x32_bf16 v[26:29], v[164:167], v[192:195], v[26:29]
	v_mfma_f32_16x16x32_bf16 v[14:17], v[156:159], v[200:203], v[14:17]
	s_setprio 2
	s_barrier
	v_mfma_f32_16x16x32_bf16 v[10:13], v[164:167], v[200:203], v[10:13]
	s_setprio 0
	s_add_u32 s58, s38, 0x80000
	s_addc_u32 s59, s39, 0
	s_add_i32 s60, s57, s46
	v_lshl_add_u64 v[152:153], s[58:59], 0, v[132:133]
	s_mov_b32 m0, s60
	s_nop 0
	global_load_lds_dwordx4 v[152:153], off
	v_lshl_add_u64 v[152:153], s[58:59], 0, v[136:137]
	s_add_i32 m0, s60, 0x2000
	s_nop 0
	global_load_lds_dwordx4 v[152:153], off
	s_waitcnt vmcnt(6)
	s_barrier
	s_setprio 1
	v_mfma_f32_16x16x32_bf16 v[54:57], v[204:207], v[168:171], v[54:57]
	v_mfma_f32_16x16x32_bf16 v[50:53], v[212:215], v[168:171], v[50:53]
	v_mfma_f32_16x16x32_bf16 v[38:41], v[204:207], v[176:179], v[38:41]
	v_mfma_f32_16x16x32_bf16 v[34:37], v[212:215], v[176:179], v[34:37]
	v_mfma_f32_16x16x32_bf16 v[22:25], v[204:207], v[184:187], v[22:25]
	v_mfma_f32_16x16x32_bf16 v[18:21], v[212:215], v[184:187], v[18:21]
	v_mfma_f32_16x16x32_bf16 v[6:9], v[204:207], v[196:199], v[6:9]
	v_mfma_f32_16x16x32_bf16 v[2:5], v[212:215], v[196:199], v[2:5]
	v_mfma_f32_16x16x32_bf16 v[54:57], v[208:211], v[172:175], v[54:57]
	v_mfma_f32_16x16x32_bf16 v[50:53], v[216:219], v[172:175], v[50:53]
	v_mfma_f32_16x16x32_bf16 v[38:41], v[208:211], v[180:183], v[38:41]
	v_mfma_f32_16x16x32_bf16 v[34:37], v[216:219], v[180:183], v[34:37]
	v_mfma_f32_16x16x32_bf16 v[22:25], v[208:211], v[192:195], v[22:25]
	v_mfma_f32_16x16x32_bf16 v[18:21], v[216:219], v[192:195], v[18:21]
	v_mfma_f32_16x16x32_bf16 v[6:9], v[208:211], v[200:203], v[6:9]
	s_setprio 2
	s_add_i32 s58, 0, 0x18000
	v_add_u32_e32 v164, s58, v148
	s_barrier
	v_mfma_f32_16x16x32_bf16 v[2:5], v[216:219], v[200:203], v[2:5]
	s_setprio 0
	ds_read_b128 v[152:155], v164
	ds_read_b128 v[156:159], v164 offset:1024
	ds_read_b128 v[160:163], v164 offset:2048
	ds_read_b128 v[164:167], v164 offset:3072
	s_add_u32 s40, s40, 0x80000
	s_addc_u32 s41, s41, 0
	s_mov_b32 m0, s48
	v_lshl_add_u64 v[204:205], s[40:41], 0, v[130:131]
	ds_read_b128 v[168:171], v150 offset:32768
	ds_read_b128 v[172:175], v150 offset:33792
	ds_read_b128 v[176:179], v150 offset:34816
	ds_read_b128 v[180:183], v150 offset:35840
	ds_read_b128 v[184:187], v150 offset:36864
	ds_read_b128 v[192:195], v150 offset:37888
	ds_read_b128 v[196:199], v150 offset:38912
	ds_read_b128 v[200:203], v150 offset:39936
	global_load_lds_dwordx4 v[204:205], off
	v_lshl_add_u64 v[204:205], s[40:41], 0, v[134:135]
	s_mov_b32 m0, s49
	s_nop 0
	global_load_lds_dwordx4 v[204:205], off
	s_waitcnt lgkmcnt(8)
	s_barrier
	s_waitcnt lgkmcnt(0)
	s_setprio 1
	s_waitcnt lgkmcnt(0)
	v_mfma_f32_16x16x32_bf16 v[126:129], v[152:155], v[168:171], v[126:129]
	v_mfma_f32_16x16x32_bf16 v[122:125], v[160:163], v[168:171], v[122:125]
	v_mfma_f32_16x16x32_bf16 v[110:113], v[152:155], v[176:179], v[110:113]
	v_mfma_f32_16x16x32_bf16 v[106:109], v[160:163], v[176:179], v[106:109]
	v_mfma_f32_16x16x32_bf16 v[94:97], v[152:155], v[184:187], v[94:97]
	v_mfma_f32_16x16x32_bf16 v[90:93], v[160:163], v[184:187], v[90:93]
	v_mfma_f32_16x16x32_bf16 v[78:81], v[152:155], v[196:199], v[78:81]
	v_mfma_f32_16x16x32_bf16 v[74:77], v[160:163], v[196:199], v[74:77]
	v_mfma_f32_16x16x32_bf16 v[126:129], v[156:159], v[172:175], v[126:129]
	v_mfma_f32_16x16x32_bf16 v[122:125], v[164:167], v[172:175], v[122:125]
	v_mfma_f32_16x16x32_bf16 v[110:113], v[156:159], v[180:183], v[110:113]
	v_mfma_f32_16x16x32_bf16 v[106:109], v[164:167], v[180:183], v[106:109]
	v_mfma_f32_16x16x32_bf16 v[94:97], v[156:159], v[192:195], v[94:97]
	v_mfma_f32_16x16x32_bf16 v[90:93], v[164:167], v[192:195], v[90:93]
	v_mfma_f32_16x16x32_bf16 v[78:81], v[156:159], v[200:203], v[78:81]
	s_setprio 2
	s_barrier
	v_mfma_f32_16x16x32_bf16 v[74:77], v[164:167], v[200:203], v[74:77]
	s_setprio 0
	s_add_i32 s40, 0, 0x1c000
	s_add_i32 s41, s58, s46
	v_add_u32_e32 v191, s40, v148
	v_lshl_add_u64 v[188:189], v[188:189], 0, s[10:11]
	s_mov_b32 m0, s41
	ds_read_b128 v[204:207], v191
	ds_read_b128 v[208:211], v191 offset:1024
	ds_read_b128 v[212:215], v191 offset:2048
	ds_read_b128 v[216:219], v191 offset:3072
	global_load_lds_dwordx4 v[188:189], off
	v_lshl_add_u64 v[188:189], v[220:221], 0, s[10:11]
	s_add_i32 m0, s41, 0x2000
	s_nop 0
	global_load_lds_dwordx4 v[188:189], off
	s_barrier
	s_waitcnt lgkmcnt(0)
	s_setprio 1
	s_waitcnt lgkmcnt(0)
	v_mfma_f32_16x16x32_bf16 v[118:121], v[204:207], v[168:171], v[118:121]
	v_mfma_f32_16x16x32_bf16 v[114:117], v[212:215], v[168:171], v[114:117]
	v_mfma_f32_16x16x32_bf16 v[102:105], v[204:207], v[176:179], v[102:105]
	v_mfma_f32_16x16x32_bf16 v[98:101], v[212:215], v[176:179], v[98:101]
	v_mfma_f32_16x16x32_bf16 v[86:89], v[204:207], v[184:187], v[86:89]
	v_mfma_f32_16x16x32_bf16 v[82:85], v[212:215], v[184:187], v[82:85]
	v_mfma_f32_16x16x32_bf16 v[70:73], v[204:207], v[196:199], v[70:73]
	v_mfma_f32_16x16x32_bf16 v[66:69], v[212:215], v[196:199], v[66:69]
	v_mfma_f32_16x16x32_bf16 v[118:121], v[208:211], v[172:175], v[118:121]
	v_mfma_f32_16x16x32_bf16 v[114:117], v[216:219], v[172:175], v[114:117]
	v_mfma_f32_16x16x32_bf16 v[102:105], v[208:211], v[180:183], v[102:105]
	v_mfma_f32_16x16x32_bf16 v[98:101], v[216:219], v[180:183], v[98:101]
	v_mfma_f32_16x16x32_bf16 v[86:89], v[208:211], v[192:195], v[86:89]
	v_mfma_f32_16x16x32_bf16 v[82:85], v[216:219], v[192:195], v[82:85]
	v_mfma_f32_16x16x32_bf16 v[70:73], v[208:211], v[200:203], v[70:73]
	s_setprio 2
	s_mov_b32 m0, s52
	v_lshl_add_u64 v[188:189], v[222:223], 0, s[10:11]
	s_barrier
	v_mfma_f32_16x16x32_bf16 v[66:69], v[216:219], v[200:203], v[66:69]
	s_setprio 0
	ds_read_b128 v[168:171], v150 offset:49152
	ds_read_b128 v[172:175], v150 offset:50176
	ds_read_b128 v[176:179], v150 offset:51200
	ds_read_b128 v[180:183], v150 offset:52224
	ds_read_b128 v[184:187], v150 offset:53248
	ds_read_b128 v[192:195], v150 offset:54272
	ds_read_b128 v[196:199], v150 offset:55296
	ds_read_b128 v[200:203], v150 offset:56320
	global_load_lds_dwordx4 v[188:189], off
	v_lshl_add_u64 v[188:189], v[224:225], 0, s[10:11]
	s_mov_b32 m0, s53
	s_nop 0
	global_load_lds_dwordx4 v[188:189], off
	s_barrier
	s_waitcnt lgkmcnt(0)
	s_setprio 1
	s_waitcnt lgkmcnt(0)
	v_mfma_f32_16x16x32_bf16 v[62:65], v[152:155], v[168:171], v[62:65]
	v_mfma_f32_16x16x32_bf16 v[58:61], v[160:163], v[168:171], v[58:61]
	v_mfma_f32_16x16x32_bf16 v[46:49], v[152:155], v[176:179], v[46:49]
	v_mfma_f32_16x16x32_bf16 v[42:45], v[160:163], v[176:179], v[42:45]
	v_mfma_f32_16x16x32_bf16 v[30:33], v[152:155], v[184:187], v[30:33]
	v_mfma_f32_16x16x32_bf16 v[26:29], v[160:163], v[184:187], v[26:29]
	v_mfma_f32_16x16x32_bf16 v[14:17], v[152:155], v[196:199], v[14:17]
	v_mfma_f32_16x16x32_bf16 v[10:13], v[160:163], v[196:199], v[10:13]
	v_mfma_f32_16x16x32_bf16 v[62:65], v[156:159], v[172:175], v[62:65]
	v_mfma_f32_16x16x32_bf16 v[58:61], v[164:167], v[172:175], v[58:61]
	v_mfma_f32_16x16x32_bf16 v[46:49], v[156:159], v[180:183], v[46:49]
	v_mfma_f32_16x16x32_bf16 v[42:45], v[164:167], v[180:183], v[42:45]
	v_mfma_f32_16x16x32_bf16 v[30:33], v[156:159], v[192:195], v[30:33]
	v_mfma_f32_16x16x32_bf16 v[26:29], v[164:167], v[192:195], v[26:29]
	v_mfma_f32_16x16x32_bf16 v[14:17], v[156:159], v[200:203], v[14:17]
	s_setprio 2
	s_barrier
	v_mfma_f32_16x16x32_bf16 v[10:13], v[164:167], v[200:203], v[10:13]
	s_setprio 0
	s_add_u32 s38, s38, 0x80080
	s_addc_u32 s39, s39, 0
	s_add_i32 s40, s40, s46
	v_lshl_add_u64 v[152:153], s[38:39], 0, v[132:133]
	s_mov_b32 m0, s40
	s_nop 0
	global_load_lds_dwordx4 v[152:153], off
	v_lshl_add_u64 v[152:153], s[38:39], 0, v[136:137]
	s_add_i32 m0, s40, 0x2000
	s_nop 0
	global_load_lds_dwordx4 v[152:153], off
	s_waitcnt vmcnt(6)
	s_barrier
	s_setprio 1
	v_mfma_f32_16x16x32_bf16 v[54:57], v[204:207], v[168:171], v[54:57]
	v_mfma_f32_16x16x32_bf16 v[50:53], v[212:215], v[168:171], v[50:53]
	v_mfma_f32_16x16x32_bf16 v[38:41], v[204:207], v[176:179], v[38:41]
	v_mfma_f32_16x16x32_bf16 v[34:37], v[212:215], v[176:179], v[34:37]
	v_mfma_f32_16x16x32_bf16 v[22:25], v[204:207], v[184:187], v[22:25]
	v_mfma_f32_16x16x32_bf16 v[18:21], v[212:215], v[184:187], v[18:21]
	v_mfma_f32_16x16x32_bf16 v[6:9], v[204:207], v[196:199], v[6:9]
	v_mfma_f32_16x16x32_bf16 v[2:5], v[212:215], v[196:199], v[2:5]
	v_mfma_f32_16x16x32_bf16 v[54:57], v[208:211], v[172:175], v[54:57]
	v_mfma_f32_16x16x32_bf16 v[50:53], v[216:219], v[172:175], v[50:53]
	v_mfma_f32_16x16x32_bf16 v[38:41], v[208:211], v[180:183], v[38:41]
	v_mfma_f32_16x16x32_bf16 v[34:37], v[216:219], v[180:183], v[34:37]
	v_mfma_f32_16x16x32_bf16 v[22:25], v[208:211], v[192:195], v[22:25]
	v_mfma_f32_16x16x32_bf16 v[18:21], v[216:219], v[192:195], v[18:21]
	v_mfma_f32_16x16x32_bf16 v[6:9], v[208:211], v[200:203], v[6:9]
	s_setprio 2
	s_add_i32 s27, s27, 2
	s_add_u32 s36, s36, 0x100
	s_addc_u32 s37, s37, 0
	s_add_u32 s23, s23, 0x100
	s_addc_u32 s26, s26, 0
	s_cmp_gt_u32 s27, 29
	s_barrier
	v_mfma_f32_16x16x32_bf16 v[2:5], v[216:219], v[200:203], v[2:5]
	s_setprio 0
	s_cbranch_scc0 .LBB0_320
	s_cmp_lt_i32 s8, 2
	s_mov_b64 s[4:5], -1
	s_cbranch_scc1 .LBB0_325
	s_cmp_eq_u32 s8, 2
	v_mov_b32_e32 v158, v125
	v_mov_b32_e32 v157, v124
	v_mov_b32_e32 v155, v123
	v_mov_b32_e32 v153, v122
	v_mov_b32_e32 v159, v129
	v_mov_b32_e32 v156, v128
	v_mov_b32_e32 v154, v127
	v_mov_b32_e32 v152, v126
	s_cbranch_scc0 .LBB0_324
	v_mul_f32_e32 v158, 0xbfb8aa3b, v129
	v_mul_f32_e32 v152, 0xbfb8aa3b, v126
	v_mul_f32_e32 v153, 0xbfb8aa3b, v122
	v_mul_f32_e32 v154, 0xbfb8aa3b, v127
	v_mul_f32_e32 v155, 0xbfb8aa3b, v123
	v_mul_f32_e32 v156, 0xbfb8aa3b, v128
	v_mul_f32_e32 v157, 0xbfb8aa3b, v124
	v_exp_f32_e32 v158, v158
	v_mul_f32_e32 v159, 0xbfb8aa3b, v125
	v_exp_f32_e32 v152, v152
	v_exp_f32_e32 v153, v153
	v_exp_f32_e32 v154, v154
	v_exp_f32_e32 v155, v155
	v_exp_f32_e32 v156, v156
	v_exp_f32_e32 v157, v157
	v_exp_f32_e32 v160, v159
	v_add_f32_e32 v158, 1.0, v158
	v_add_f32_e32 v152, 1.0, v152
	v_add_f32_e32 v153, 1.0, v153
	v_add_f32_e32 v154, 1.0, v154
	v_add_f32_e32 v155, 1.0, v155
	v_add_f32_e32 v156, 1.0, v156
	v_add_f32_e32 v157, 1.0, v157
	v_rcp_f32_e32 v159, v158
	v_add_f32_e32 v158, 1.0, v160
	v_rcp_f32_e32 v152, v152
	v_rcp_f32_e32 v153, v153
	v_rcp_f32_e32 v154, v154
	v_rcp_f32_e32 v155, v155
	v_rcp_f32_e32 v156, v156
	v_rcp_f32_e32 v157, v157
	v_rcp_f32_e32 v158, v158

.LBB0_850:
	ds_read_b128 v[154:157], v150
	ds_read_b128 v[158:161], v150 offset:1024
	ds_read_b128 v[162:165], v150 offset:2048
	ds_read_b128 v[166:169], v150 offset:3072
	s_add_u32 s44, s42, 0xfff80080
	s_addc_u32 s45, s43, -1
	s_cmp_eq_u32 s62, 28
	s_cselect_b32 s47, s4, s45
	s_cselect_b32 s46, s5, s44
	s_cselect_b32 s45, s26, s31
	s_cselect_b32 s44, s27, s29
	v_lshl_add_u64 v[146:147], s[42:43], 0, v[138:139]
	s_add_i32 m0, s39, 0xc000
	ds_read_b128 v[170:173], v151
	ds_read_b128 v[174:177], v151 offset:1024
	ds_read_b128 v[178:181], v151 offset:2048
	ds_read_b128 v[182:185], v151 offset:3072
	ds_read_b128 v[186:189], v151 offset:4096
	ds_read_b128 v[192:195], v151 offset:5120
	ds_read_b128 v[196:199], v151 offset:6144
	ds_read_b128 v[200:203], v151 offset:7168
	global_load_lds_dwordx4 v[146:147], off
	v_lshl_add_u64 v[146:147], s[42:43], 0, v[140:141]
	s_add_i32 m0, s39, 0xe000
	s_nop 0
	global_load_lds_dwordx4 v[146:147], off
	s_waitcnt lgkmcnt(8)
	s_barrier
	s_waitcnt lgkmcnt(0)
	s_setprio 1
	s_waitcnt lgkmcnt(0)
	v_mfma_f32_16x16x32_bf16 v[126:129], v[154:157], v[170:173], v[126:129]
	v_mfma_f32_16x16x32_bf16 v[122:125], v[162:165], v[170:173], v[122:125]
	v_mfma_f32_16x16x32_bf16 v[110:113], v[154:157], v[178:181], v[110:113]
	v_mfma_f32_16x16x32_bf16 v[106:109], v[162:165], v[178:181], v[106:109]
	v_mfma_f32_16x16x32_bf16 v[94:97], v[154:157], v[186:189], v[94:97]
	v_mfma_f32_16x16x32_bf16 v[90:93], v[162:165], v[186:189], v[90:93]
	v_mfma_f32_16x16x32_bf16 v[78:81], v[154:157], v[196:199], v[78:81]
	v_mfma_f32_16x16x32_bf16 v[74:77], v[162:165], v[196:199], v[74:77]
	v_mfma_f32_16x16x32_bf16 v[126:129], v[158:161], v[174:177], v[126:129]
	v_mfma_f32_16x16x32_bf16 v[122:125], v[166:169], v[174:177], v[122:125]
	v_mfma_f32_16x16x32_bf16 v[110:113], v[158:161], v[182:185], v[110:113]
	v_mfma_f32_16x16x32_bf16 v[106:109], v[166:169], v[182:185], v[106:109]
	v_mfma_f32_16x16x32_bf16 v[94:97], v[158:161], v[192:195], v[94:97]
	v_mfma_f32_16x16x32_bf16 v[90:93], v[166:169], v[192:195], v[90:93]
	v_mfma_f32_16x16x32_bf16 v[78:81], v[158:161], v[200:203], v[78:81]
	s_setprio 2
	s_barrier
	v_mfma_f32_16x16x32_bf16 v[74:77], v[166:169], v[200:203], v[74:77]
	s_setprio 0
	s_add_i32 s63, s60, s52
	v_lshl_add_u64 v[146:147], s[44:45], 0, v[132:133]
	s_mov_b32 m0, s63
	ds_read_b128 v[204:207], v152
	ds_read_b128 v[208:211], v152 offset:1024
	ds_read_b128 v[212:215], v152 offset:2048
	ds_read_b128 v[216:219], v152 offset:3072
	global_load_lds_dwordx4 v[146:147], off
	v_lshl_add_u64 v[220:221], s[44:45], 0, v[136:137]
	s_add_i32 m0, s63, 0x2000
	s_nop 0
	global_load_lds_dwordx4 v[220:221], off
	s_barrier
	s_waitcnt lgkmcnt(0)
	s_setprio 1
	s_waitcnt lgkmcnt(0)
	v_mfma_f32_16x16x32_bf16 v[118:121], v[204:207], v[170:173], v[118:121]
	v_mfma_f32_16x16x32_bf16 v[114:117], v[212:215], v[170:173], v[114:117]
	v_mfma_f32_16x16x32_bf16 v[102:105], v[204:207], v[178:181], v[102:105]
	v_mfma_f32_16x16x32_bf16 v[98:101], v[212:215], v[178:181], v[98:101]
	v_mfma_f32_16x16x32_bf16 v[86:89], v[204:207], v[186:189], v[86:89]
	v_mfma_f32_16x16x32_bf16 v[82:85], v[212:215], v[186:189], v[82:85]
	v_mfma_f32_16x16x32_bf16 v[70:73], v[204:207], v[196:199], v[70:73]
	v_mfma_f32_16x16x32_bf16 v[66:69], v[212:215], v[196:199], v[66:69]
	v_mfma_f32_16x16x32_bf16 v[118:121], v[208:211], v[174:177], v[118:121]
	v_mfma_f32_16x16x32_bf16 v[114:117], v[216:219], v[174:177], v[114:117]
	v_mfma_f32_16x16x32_bf16 v[102:105], v[208:211], v[182:185], v[102:105]
	v_mfma_f32_16x16x32_bf16 v[98:101], v[216:219], v[182:185], v[98:101]
	v_mfma_f32_16x16x32_bf16 v[86:89], v[208:211], v[192:195], v[86:89]
	v_mfma_f32_16x16x32_bf16 v[82:85], v[216:219], v[192:195], v[82:85]
	v_mfma_f32_16x16x32_bf16 v[70:73], v[208:211], v[200:203], v[70:73]
	s_setprio 2
	s_mov_b32 m0, s39
	v_lshl_add_u64 v[222:223], s[46:47], 0, v[130:131]
	s_barrier
	v_mfma_f32_16x16x32_bf16 v[66:69], v[216:219], v[200:203], v[66:69]
	s_setprio 0
	ds_read_b128 v[170:173], v151 offset:16384
	ds_read_b128 v[174:177], v151 offset:17408
	ds_read_b128 v[178:181], v151 offset:18432
	ds_read_b128 v[182:185], v151 offset:19456
	ds_read_b128 v[186:189], v151 offset:20480
	ds_read_b128 v[192:195], v151 offset:21504
	ds_read_b128 v[196:199], v151 offset:22528
	ds_read_b128 v[200:203], v151 offset:23552
	global_load_lds_dwordx4 v[222:223], off
	v_lshl_add_u64 v[224:225], s[46:47], 0, v[134:135]
	s_mov_b32 m0, s41
	s_nop 0
	global_load_lds_dwordx4 v[224:225], off
	s_barrier
	s_waitcnt lgkmcnt(0)
	s_setprio 1
	s_waitcnt lgkmcnt(0)
	v_mfma_f32_16x16x32_bf16 v[62:65], v[154:157], v[170:173], v[62:65]
	v_mfma_f32_16x16x32_bf16 v[58:61], v[162:165], v[170:173], v[58:61]
	v_mfma_f32_16x16x32_bf16 v[46:49], v[154:157], v[178:181], v[46:49]
	v_mfma_f32_16x16x32_bf16 v[42:45], v[162:165], v[178:181], v[42:45]
	v_mfma_f32_16x16x32_bf16 v[30:33], v[154:157], v[186:189], v[30:33]
	v_mfma_f32_16x16x32_bf16 v[26:29], v[162:165], v[186:189], v[26:29]
	v_mfma_f32_16x16x32_bf16 v[14:17], v[154:157], v[196:199], v[14:17]
	v_mfma_f32_16x16x32_bf16 v[10:13], v[162:165], v[196:199], v[10:13]
	v_mfma_f32_16x16x32_bf16 v[62:65], v[158:161], v[174:177], v[62:65]
	v_mfma_f32_16x16x32_bf16 v[58:61], v[166:169], v[174:177], v[58:61]
	v_mfma_f32_16x16x32_bf16 v[46:49], v[158:161], v[182:185], v[46:49]
	v_mfma_f32_16x16x32_bf16 v[42:45], v[166:169], v[182:185], v[42:45]
	v_mfma_f32_16x16x32_bf16 v[30:33], v[158:161], v[192:195], v[30:33]
	v_mfma_f32_16x16x32_bf16 v[26:29], v[166:169], v[192:195], v[26:29]
	v_mfma_f32_16x16x32_bf16 v[14:17], v[158:161], v[200:203], v[14:17]
	s_setprio 2
	s_barrier
	v_mfma_f32_16x16x32_bf16 v[10:13], v[166:169], v[200:203], v[10:13]
	s_setprio 0
	s_add_u32 s64, s44, 0x80000
	s_addc_u32 s65, s45, 0
	s_add_i32 s63, s61, s52
	v_lshl_add_u64 v[154:155], s[64:65], 0, v[132:133]
	s_mov_b32 m0, s63
	s_nop 0
	global_load_lds_dwordx4 v[154:155], off
	v_lshl_add_u64 v[154:155], s[64:65], 0, v[136:137]
	s_add_i32 m0, s63, 0x2000
	s_nop 0
	global_load_lds_dwordx4 v[154:155], off
	s_waitcnt vmcnt(6)
	s_barrier
	s_setprio 1
	v_mfma_f32_16x16x32_bf16 v[54:57], v[204:207], v[170:173], v[54:57]
	v_mfma_f32_16x16x32_bf16 v[50:53], v[212:215], v[170:173], v[50:53]
	v_mfma_f32_16x16x32_bf16 v[38:41], v[204:207], v[178:181], v[38:41]
	v_mfma_f32_16x16x32_bf16 v[34:37], v[212:215], v[178:181], v[34:37]
	v_mfma_f32_16x16x32_bf16 v[22:25], v[204:207], v[186:189], v[22:25]
	v_mfma_f32_16x16x32_bf16 v[18:21], v[212:215], v[186:189], v[18:21]
	v_mfma_f32_16x16x32_bf16 v[6:9], v[204:207], v[196:199], v[6:9]
	v_mfma_f32_16x16x32_bf16 v[2:5], v[212:215], v[196:199], v[2:5]
	v_mfma_f32_16x16x32_bf16 v[54:57], v[208:211], v[174:177], v[54:57]
	v_mfma_f32_16x16x32_bf16 v[50:53], v[216:219], v[174:177], v[50:53]
	v_mfma_f32_16x16x32_bf16 v[38:41], v[208:211], v[182:185], v[38:41]
	v_mfma_f32_16x16x32_bf16 v[34:37], v[216:219], v[182:185], v[34:37]
	v_mfma_f32_16x16x32_bf16 v[22:25], v[208:211], v[192:195], v[22:25]
	v_mfma_f32_16x16x32_bf16 v[18:21], v[216:219], v[192:195], v[18:21]
	v_mfma_f32_16x16x32_bf16 v[6:9], v[208:211], v[200:203], v[6:9]
	s_setprio 2
	s_add_i32 s63, 0, 0x18000
	v_add_u32_e32 v153, s63, v148
	s_barrier
	v_mfma_f32_16x16x32_bf16 v[2:5], v[216:219], v[200:203], v[2:5]
	s_setprio 0
	ds_read_b128 v[154:157], v153
	ds_read_b128 v[158:161], v153 offset:1024
	ds_read_b128 v[162:165], v153 offset:2048
	ds_read_b128 v[166:169], v153 offset:3072
	s_add_u32 s46, s46, 0x80000
	s_addc_u32 s47, s47, 0
	s_mov_b32 m0, s53
	v_lshl_add_u64 v[204:205], s[46:47], 0, v[130:131]
	ds_read_b128 v[170:173], v151 offset:32768
	ds_read_b128 v[174:177], v151 offset:33792
	ds_read_b128 v[178:181], v151 offset:34816
	ds_read_b128 v[182:185], v151 offset:35840
	ds_read_b128 v[186:189], v151 offset:36864
	ds_read_b128 v[192:195], v151 offset:37888
	ds_read_b128 v[196:199], v151 offset:38912
	ds_read_b128 v[200:203], v151 offset:39936
	global_load_lds_dwordx4 v[204:205], off
	v_lshl_add_u64 v[204:205], s[46:47], 0, v[134:135]
	s_mov_b32 m0, s54
	s_nop 0
	global_load_lds_dwordx4 v[204:205], off
	s_waitcnt lgkmcnt(8)
	s_barrier
	s_waitcnt lgkmcnt(0)
	s_setprio 1
	s_waitcnt lgkmcnt(0)
	v_mfma_f32_16x16x32_bf16 v[126:129], v[154:157], v[170:173], v[126:129]
	v_mfma_f32_16x16x32_bf16 v[122:125], v[162:165], v[170:173], v[122:125]
	v_mfma_f32_16x16x32_bf16 v[110:113], v[154:157], v[178:181], v[110:113]
	v_mfma_f32_16x16x32_bf16 v[106:109], v[162:165], v[178:181], v[106:109]
	v_mfma_f32_16x16x32_bf16 v[94:97], v[154:157], v[186:189], v[94:97]
	v_mfma_f32_16x16x32_bf16 v[90:93], v[162:165], v[186:189], v[90:93]
	v_mfma_f32_16x16x32_bf16 v[78:81], v[154:157], v[196:199], v[78:81]
	v_mfma_f32_16x16x32_bf16 v[74:77], v[162:165], v[196:199], v[74:77]
	v_mfma_f32_16x16x32_bf16 v[126:129], v[158:161], v[174:177], v[126:129]
	v_mfma_f32_16x16x32_bf16 v[122:125], v[166:169], v[174:177], v[122:125]
	v_mfma_f32_16x16x32_bf16 v[110:113], v[158:161], v[182:185], v[110:113]
	v_mfma_f32_16x16x32_bf16 v[106:109], v[166:169], v[182:185], v[106:109]
	v_mfma_f32_16x16x32_bf16 v[94:97], v[158:161], v[192:195], v[94:97]
	v_mfma_f32_16x16x32_bf16 v[90:93], v[166:169], v[192:195], v[90:93]
	v_mfma_f32_16x16x32_bf16 v[78:81], v[158:161], v[200:203], v[78:81]
	s_setprio 2
	s_barrier
	v_mfma_f32_16x16x32_bf16 v[74:77], v[166:169], v[200:203], v[74:77]
	s_setprio 0
	s_add_i32 s46, 0, 0x1c000
	s_add_i32 s47, s63, s52
	v_add_u32_e32 v153, s46, v148
	v_lshl_add_u64 v[146:147], v[146:147], 0, s[12:13]
	s_mov_b32 m0, s47
	ds_read_b128 v[204:207], v153
	ds_read_b128 v[208:211], v153 offset:1024
	ds_read_b128 v[212:215], v153 offset:2048
	ds_read_b128 v[216:219], v153 offset:3072
	global_load_lds_dwordx4 v[146:147], off
	v_lshl_add_u64 v[146:147], v[220:221], 0, s[12:13]
	s_add_i32 m0, s47, 0x2000
	s_nop 0
	global_load_lds_dwordx4 v[146:147], off
	s_barrier
	s_waitcnt lgkmcnt(0)
	s_setprio 1
	s_waitcnt lgkmcnt(0)
	v_mfma_f32_16x16x32_bf16 v[118:121], v[204:207], v[170:173], v[118:121]
	v_mfma_f32_16x16x32_bf16 v[114:117], v[212:215], v[170:173], v[114:117]
	v_mfma_f32_16x16x32_bf16 v[102:105], v[204:207], v[178:181], v[102:105]
	v_mfma_f32_16x16x32_bf16 v[98:101], v[212:215], v[178:181], v[98:101]
	v_mfma_f32_16x16x32_bf16 v[86:89], v[204:207], v[186:189], v[86:89]
	v_mfma_f32_16x16x32_bf16 v[82:85], v[212:215], v[186:189], v[82:85]
	v_mfma_f32_16x16x32_bf16 v[70:73], v[204:207], v[196:199], v[70:73]
	v_mfma_f32_16x16x32_bf16 v[66:69], v[212:215], v[196:199], v[66:69]
	v_mfma_f32_16x16x32_bf16 v[118:121], v[208:211], v[174:177], v[118:121]
	v_mfma_f32_16x16x32_bf16 v[114:117], v[216:219], v[174:177], v[114:117]
	v_mfma_f32_16x16x32_bf16 v[102:105], v[208:211], v[182:185], v[102:105]
	v_mfma_f32_16x16x32_bf16 v[98:101], v[216:219], v[182:185], v[98:101]
	v_mfma_f32_16x16x32_bf16 v[86:89], v[208:211], v[192:195], v[86:89]
	v_mfma_f32_16x16x32_bf16 v[82:85], v[216:219], v[192:195], v[82:85]
	v_mfma_f32_16x16x32_bf16 v[70:73], v[208:211], v[200:203], v[70:73]
	s_setprio 2
	s_mov_b32 m0, s56
	v_lshl_add_u64 v[146:147], v[222:223], 0, s[12:13]
	s_barrier
	v_mfma_f32_16x16x32_bf16 v[66:69], v[216:219], v[200:203], v[66:69]
	s_setprio 0
	ds_read_b128 v[170:173], v151 offset:49152
	ds_read_b128 v[174:177], v151 offset:50176
	ds_read_b128 v[178:181], v151 offset:51200
	ds_read_b128 v[182:185], v151 offset:52224
	ds_read_b128 v[186:189], v151 offset:53248
	ds_read_b128 v[192:195], v151 offset:54272
	ds_read_b128 v[196:199], v151 offset:55296
	ds_read_b128 v[200:203], v151 offset:56320
	global_load_lds_dwordx4 v[146:147], off
	v_lshl_add_u64 v[146:147], v[224:225], 0, s[12:13]
	s_mov_b32 m0, s57
	s_nop 0
	global_load_lds_dwordx4 v[146:147], off
	s_barrier
	s_waitcnt lgkmcnt(0)
	s_setprio 1
	s_waitcnt lgkmcnt(0)
	v_mfma_f32_16x16x32_bf16 v[62:65], v[154:157], v[170:173], v[62:65]
	v_mfma_f32_16x16x32_bf16 v[58:61], v[162:165], v[170:173], v[58:61]
	v_mfma_f32_16x16x32_bf16 v[46:49], v[154:157], v[178:181], v[46:49]
	v_mfma_f32_16x16x32_bf16 v[42:45], v[162:165], v[178:181], v[42:45]
	v_mfma_f32_16x16x32_bf16 v[30:33], v[154:157], v[186:189], v[30:33]
	v_mfma_f32_16x16x32_bf16 v[26:29], v[162:165], v[186:189], v[26:29]
	v_mfma_f32_16x16x32_bf16 v[14:17], v[154:157], v[196:199], v[14:17]
	v_mfma_f32_16x16x32_bf16 v[10:13], v[162:165], v[196:199], v[10:13]
	v_mfma_f32_16x16x32_bf16 v[62:65], v[158:161], v[174:177], v[62:65]
	v_mfma_f32_16x16x32_bf16 v[58:61], v[166:169], v[174:177], v[58:61]
	v_mfma_f32_16x16x32_bf16 v[46:49], v[158:161], v[182:185], v[46:49]
	v_mfma_f32_16x16x32_bf16 v[42:45], v[166:169], v[182:185], v[42:45]
	v_mfma_f32_16x16x32_bf16 v[30:33], v[158:161], v[192:195], v[30:33]
	v_mfma_f32_16x16x32_bf16 v[26:29], v[166:169], v[192:195], v[26:29]
	v_mfma_f32_16x16x32_bf16 v[14:17], v[158:161], v[200:203], v[14:17]
	s_setprio 2
	s_barrier
	v_mfma_f32_16x16x32_bf16 v[10:13], v[166:169], v[200:203], v[10:13]
	s_setprio 0
	s_add_u32 s44, s44, 0x80080
	s_addc_u32 s45, s45, 0
	s_add_i32 s46, s46, s52
	v_lshl_add_u64 v[146:147], s[44:45], 0, v[132:133]
	s_mov_b32 m0, s46
	s_nop 0
	global_load_lds_dwordx4 v[146:147], off
	v_lshl_add_u64 v[146:147], s[44:45], 0, v[136:137]
	s_add_i32 m0, s46, 0x2000
	s_nop 0
	global_load_lds_dwordx4 v[146:147], off
	s_waitcnt vmcnt(6)
	s_barrier
	s_setprio 1
	v_mfma_f32_16x16x32_bf16 v[54:57], v[204:207], v[170:173], v[54:57]
	v_mfma_f32_16x16x32_bf16 v[50:53], v[212:215], v[170:173], v[50:53]
	v_mfma_f32_16x16x32_bf16 v[38:41], v[204:207], v[178:181], v[38:41]
	v_mfma_f32_16x16x32_bf16 v[34:37], v[212:215], v[178:181], v[34:37]
	v_mfma_f32_16x16x32_bf16 v[22:25], v[204:207], v[186:189], v[22:25]
	v_mfma_f32_16x16x32_bf16 v[18:21], v[212:215], v[186:189], v[18:21]
	v_mfma_f32_16x16x32_bf16 v[6:9], v[204:207], v[196:199], v[6:9]
	v_mfma_f32_16x16x32_bf16 v[2:5], v[212:215], v[196:199], v[2:5]
	v_mfma_f32_16x16x32_bf16 v[54:57], v[208:211], v[174:177], v[54:57]
	v_mfma_f32_16x16x32_bf16 v[50:53], v[216:219], v[174:177], v[50:53]
	v_mfma_f32_16x16x32_bf16 v[38:41], v[208:211], v[182:185], v[38:41]
	v_mfma_f32_16x16x32_bf16 v[34:37], v[216:219], v[182:185], v[34:37]
	v_mfma_f32_16x16x32_bf16 v[22:25], v[208:211], v[192:195], v[22:25]
	v_mfma_f32_16x16x32_bf16 v[18:21], v[216:219], v[192:195], v[18:21]
	v_mfma_f32_16x16x32_bf16 v[6:9], v[208:211], v[200:203], v[6:9]
	s_setprio 2
	s_add_i32 s62, s62, 2
	s_add_u32 s42, s42, 0x100
	s_addc_u32 s43, s43, 0
	s_add_u32 s29, s29, 0x100
	s_addc_u32 s31, s31, 0
	s_cmp_gt_u32 s62, 29
	s_barrier
	v_mfma_f32_16x16x32_bf16 v[2:5], v[216:219], v[200:203], v[2:5]
	s_setprio 0
	s_cbranch_scc0 .LBB0_850
	s_lshl_b32 s4, s40, 8
	s_and_b32 s4, s4, 0x3f00
	v_add_u32_e32 v162, s4, v1
	s_ashr_i32 s4, s38, 31
	s_lshr_b32 s4, s4, 29
	s_add_i32 s4, s38, s4
	s_and_b32 s4, s4, 0xfffff8
	s_sub_i32 s4, s38, s4
	v_lshl_or_b32 v164, s4, 8, v149
	v_ashrrev_i32_e32 v163, 31, v162
	v_ashrrev_i32_e32 v165, 31, v164
	v_lshlrev_b32_e32 v146, 13, v162
	v_lshl_add_u32 v146, v164, 2, v146
	v_lshlrev_b32_e32 v147, 12, v162
	v_lshl_add_u32 v147, v164, 1, v147
	s_add_u32 s64, s8, 0x0
	s_addc_u32 s65, s9, 0
	global_load_dwordx4 v[176:179], v146, s[64:65]
	global_load_dwordx4 v[180:183], v146, s[64:65] offset:16
	s_add_u32 s64, s8, 0x200
	s_addc_u32 s65, s9, 0
	global_load_dwordx4 v[184:187], v146, s[64:65]
	global_load_dwordx4 v[192:195], v146, s[64:65] offset:16
	s_add_u32 s64, s8, 0x20000
	s_addc_u32 s65, s9, 0
	global_load_dwordx4 v[196:199], v146, s[64:65]
	global_load_dwordx4 v[200:203], v146, s[64:65] offset:16
	s_add_u32 s64, s8, 0x20200
	s_addc_u32 s65, s9, 0
	global_load_dwordx4 v[204:207], v146, s[64:65]
	global_load_dwordx4 v[208:211], v146, s[64:65] offset:16
	s_add_u32 s64, s8, 0x40000
	s_addc_u32 s65, s9, 0
	global_load_dwordx4 v[212:215], v146, s[64:65]
	global_load_dwordx4 v[216:219], v146, s[64:65] offset:16
	s_add_u32 s64, s8, 0x40200
	s_addc_u32 s65, s9, 0
	global_load_dwordx4 v[220:223], v146, s[64:65]
	global_load_dwordx4 v[224:227], v146, s[64:65] offset:16
	s_add_u32 s64, s8, 0x60000
	s_addc_u32 s65, s9, 0
	global_load_dwordx4 v[228:231], v146, s[64:65]
	global_load_dwordx4 v[232:235], v146, s[64:65] offset:16
	s_add_u32 s64, s8, 0x60200
	s_addc_u32 s65, s9, 0
	global_load_dwordx4 v[236:239], v146, s[64:65]
	global_load_dwordx4 v[240:243], v146, s[64:65] offset:16
	s_waitcnt vmcnt(14)
	v_pk_fma_f32 v[176:177], v[176:177], s[14:15], v[126:127] op_sel_hi:[1,0,1]
	v_pk_fma_f32 v[178:179], v[178:179], s[14:15], v[128:129] op_sel_hi:[1,0,1]
	v_pk_fma_f32 v[180:181], v[180:181], s[14:15], v[122:123] op_sel_hi:[1,0,1]
	v_pk_fma_f32 v[182:183], v[182:183], s[14:15], v[124:125] op_sel_hi:[1,0,1]
	v_cvt_pk_bf16_f32 v176, v176, v177
	v_cvt_pk_bf16_f32 v177, v178, v179
	v_cvt_pk_bf16_f32 v178, v180, v181
	v_cvt_pk_bf16_f32 v179, v182, v183
	s_add_u32 s66, s10, 0x0
	s_addc_u32 s67, s11, 0
	global_store_dwordx4 v147, v[176:179], s[66:67]
	s_waitcnt vmcnt(13)
	v_pk_fma_f32 v[184:185], v[184:185], s[14:15], v[118:119] op_sel_hi:[1,0,1]
	v_pk_fma_f32 v[186:187], v[186:187], s[14:15], v[120:121] op_sel_hi:[1,0,1]
	v_pk_fma_f32 v[192:193], v[192:193], s[14:15], v[114:115] op_sel_hi:[1,0,1]
	v_pk_fma_f32 v[194:195], v[194:195], s[14:15], v[116:117] op_sel_hi:[1,0,1]
	v_cvt_pk_bf16_f32 v184, v184, v185
	v_cvt_pk_bf16_f32 v185, v186, v187
	v_cvt_pk_bf16_f32 v186, v192, v193
	v_cvt_pk_bf16_f32 v187, v194, v195
	s_add_u32 s66, s10, 0x100
	s_addc_u32 s67, s11, 0
	global_store_dwordx4 v147, v[184:187], s[66:67]
	s_waitcnt vmcnt(12)
	v_pk_fma_f32 v[196:197], v[196:197], s[14:15], v[110:111] op_sel_hi:[1,0,1]
	v_pk_fma_f32 v[198:199], v[198:199], s[14:15], v[112:113] op_sel_hi:[1,0,1]
	v_pk_fma_f32 v[200:201], v[200:201], s[14:15], v[106:107] op_sel_hi:[1,0,1]
	v_pk_fma_f32 v[202:203], v[202:203], s[14:15], v[108:109] op_sel_hi:[1,0,1]
	v_cvt_pk_bf16_f32 v196, v196, v197
	v_cvt_pk_bf16_f32 v197, v198, v199
	v_cvt_pk_bf16_f32 v198, v200, v201
	v_cvt_pk_bf16_f32 v199, v202, v203
	s_add_u32 s66, s10, 0x10000
	s_addc_u32 s67, s11, 0
	global_store_dwordx4 v147, v[196:199], s[66:67]
	s_waitcnt vmcnt(11)
	v_pk_fma_f32 v[204:205], v[204:205], s[14:15], v[102:103] op_sel_hi:[1,0,1]
	v_pk_fma_f32 v[206:207], v[206:207], s[14:15], v[104:105] op_sel_hi:[1,0,1]
	v_pk_fma_f32 v[208:209], v[208:209], s[14:15], v[98:99] op_sel_hi:[1,0,1]
	v_pk_fma_f32 v[210:211], v[210:211], s[14:15], v[100:101] op_sel_hi:[1,0,1]
	v_cvt_pk_bf16_f32 v204, v204, v205
	v_cvt_pk_bf16_f32 v205, v206, v207
	v_cvt_pk_bf16_f32 v206, v208, v209
	v_cvt_pk_bf16_f32 v207, v210, v211
	s_add_u32 s66, s10, 0x10100
	s_addc_u32 s67, s11, 0
	global_store_dwordx4 v147, v[204:207], s[66:67]
	s_waitcnt vmcnt(10)
	v_pk_fma_f32 v[212:213], v[212:213], s[14:15], v[94:95] op_sel_hi:[1,0,1]
	v_pk_fma_f32 v[214:215], v[214:215], s[14:15], v[96:97] op_sel_hi:[1,0,1]
	v_pk_fma_f32 v[216:217], v[216:217], s[14:15], v[90:91] op_sel_hi:[1,0,1]
	v_pk_fma_f32 v[218:219], v[218:219], s[14:15], v[92:93] op_sel_hi:[1,0,1]
	v_cvt_pk_bf16_f32 v212, v212, v213
	v_cvt_pk_bf16_f32 v213, v214, v215
	v_cvt_pk_bf16_f32 v214, v216, v217
	v_cvt_pk_bf16_f32 v215, v218, v219
	s_add_u32 s66, s10, 0x20000
	s_addc_u32 s67, s11, 0
	global_store_dwordx4 v147, v[212:215], s[66:67]
	s_waitcnt vmcnt(9)
	v_pk_fma_f32 v[220:221], v[220:221], s[14:15], v[86:87] op_sel_hi:[1,0,1]
	v_pk_fma_f32 v[222:223], v[222:223], s[14:15], v[88:89] op_sel_hi:[1,0,1]
	v_pk_fma_f32 v[224:225], v[224:225], s[14:15], v[82:83] op_sel_hi:[1,0,1]
	v_pk_fma_f32 v[226:227], v[226:227], s[14:15], v[84:85] op_sel_hi:[1,0,1]
	v_cvt_pk_bf16_f32 v220, v220, v221
	v_cvt_pk_bf16_f32 v221, v222, v223
	v_cvt_pk_bf16_f32 v222, v224, v225
	v_cvt_pk_bf16_f32 v223, v226, v227
	s_add_u32 s66, s10, 0x20100
	s_addc_u32 s67, s11, 0
	global_store_dwordx4 v147, v[220:223], s[66:67]
	s_waitcnt vmcnt(8)
	v_pk_fma_f32 v[228:229], v[228:229], s[14:15], v[78:79] op_sel_hi:[1,0,1]
	v_pk_fma_f32 v[230:231], v[230:231], s[14:15], v[80:81] op_sel_hi:[1,0,1]
	v_pk_fma_f32 v[232:233], v[232:233], s[14:15], v[74:75] op_sel_hi:[1,0,1]
	v_pk_fma_f32 v[234:235], v[234:235], s[14:15], v[76:77] op_sel_hi:[1,0,1]
	v_cvt_pk_bf16_f32 v228, v228, v229
	v_cvt_pk_bf16_f32 v229, v230, v231
	v_cvt_pk_bf16_f32 v230, v232, v233
	v_cvt_pk_bf16_f32 v231, v234, v235
	s_add_u32 s66, s10, 0x30000
	s_addc_u32 s67, s11, 0
	global_store_dwordx4 v147, v[228:231], s[66:67]
	s_waitcnt vmcnt(7)
	v_pk_fma_f32 v[236:237], v[236:237], s[14:15], v[70:71] op_sel_hi:[1,0,1]
	v_pk_fma_f32 v[238:239], v[238:239], s[14:15], v[72:73] op_sel_hi:[1,0,1]
	v_pk_fma_f32 v[240:241], v[240:241], s[14:15], v[66:67] op_sel_hi:[1,0,1]
	v_pk_fma_f32 v[242:243], v[242:243], s[14:15], v[68:69] op_sel_hi:[1,0,1]
	v_cvt_pk_bf16_f32 v236, v236, v237
	v_cvt_pk_bf16_f32 v237, v238, v239
	v_cvt_pk_bf16_f32 v238, v240, v241
	v_cvt_pk_bf16_f32 v239, v242, v243
	s_add_u32 s66, s10, 0x30100
	s_addc_u32 s67, s11, 0
	global_store_dwordx4 v147, v[236:239], s[66:67]
	s_add_u32 s64, s8, 0x100000
	s_addc_u32 s65, s9, 0
	global_load_dwordx4 v[176:179], v146, s[64:65]
	global_load_dwordx4 v[180:183], v146, s[64:65] offset:16
	s_add_u32 s64, s8, 0x100200
	s_addc_u32 s65, s9, 0
	global_load_dwordx4 v[184:187], v146, s[64:65]
	global_load_dwordx4 v[192:195], v146, s[64:65] offset:16
	s_add_u32 s64, s8, 0x120000
	s_addc_u32 s65, s9, 0
	global_load_dwordx4 v[196:199], v146, s[64:65]
	global_load_dwordx4 v[200:203], v146, s[64:65] offset:16
	s_add_u32 s64, s8, 0x120200
	s_addc_u32 s65, s9, 0
	global_load_dwordx4 v[204:207], v146, s[64:65]
	global_load_dwordx4 v[208:211], v146, s[64:65] offset:16
	s_add_u32 s64, s8, 0x140000
	s_addc_u32 s65, s9, 0
	global_load_dwordx4 v[212:215], v146, s[64:65]
	global_load_dwordx4 v[216:219], v146, s[64:65] offset:16
	s_add_u32 s64, s8, 0x140200
	s_addc_u32 s65, s9, 0
	global_load_dwordx4 v[220:223], v146, s[64:65]
	global_load_dwordx4 v[224:227], v146, s[64:65] offset:16
	s_add_u32 s64, s8, 0x160000
	s_addc_u32 s65, s9, 0
	global_load_dwordx4 v[228:231], v146, s[64:65]
	global_load_dwordx4 v[232:235], v146, s[64:65] offset:16
	s_add_u32 s64, s8, 0x160200
	s_addc_u32 s65, s9, 0
	global_load_dwordx4 v[236:239], v146, s[64:65]
	global_load_dwordx4 v[240:243], v146, s[64:65] offset:16
	s_waitcnt vmcnt(14)
	v_pk_fma_f32 v[176:177], v[176:177], s[14:15], v[62:63] op_sel_hi:[1,0,1]
	v_pk_fma_f32 v[178:179], v[178:179], s[14:15], v[64:65] op_sel_hi:[1,0,1]
	v_pk_fma_f32 v[180:181], v[180:181], s[14:15], v[58:59] op_sel_hi:[1,0,1]
	v_pk_fma_f32 v[182:183], v[182:183], s[14:15], v[60:61] op_sel_hi:[1,0,1]
	v_cvt_pk_bf16_f32 v176, v176, v177
	v_cvt_pk_bf16_f32 v177, v178, v179
	v_cvt_pk_bf16_f32 v178, v180, v181
	v_cvt_pk_bf16_f32 v179, v182, v183
	s_add_u32 s66, s10, 0x80000
	s_addc_u32 s67, s11, 0
	global_store_dwordx4 v147, v[176:179], s[66:67]
	s_waitcnt vmcnt(13)
	v_pk_fma_f32 v[184:185], v[184:185], s[14:15], v[54:55] op_sel_hi:[1,0,1]
	v_pk_fma_f32 v[186:187], v[186:187], s[14:15], v[56:57] op_sel_hi:[1,0,1]
	v_pk_fma_f32 v[192:193], v[192:193], s[14:15], v[50:51] op_sel_hi:[1,0,1]
	v_pk_fma_f32 v[194:195], v[194:195], s[14:15], v[52:53] op_sel_hi:[1,0,1]
	v_cvt_pk_bf16_f32 v184, v184, v185
	v_cvt_pk_bf16_f32 v185, v186, v187
	v_cvt_pk_bf16_f32 v186, v192, v193
	v_cvt_pk_bf16_f32 v187, v194, v195
	s_add_u32 s66, s10, 0x80100
	s_addc_u32 s67, s11, 0
	global_store_dwordx4 v147, v[184:187], s[66:67]
	s_waitcnt vmcnt(12)
	v_pk_fma_f32 v[196:197], v[196:197], s[14:15], v[46:47] op_sel_hi:[1,0,1]
	v_pk_fma_f32 v[198:199], v[198:199], s[14:15], v[48:49] op_sel_hi:[1,0,1]
	v_pk_fma_f32 v[200:201], v[200:201], s[14:15], v[42:43] op_sel_hi:[1,0,1]
	v_pk_fma_f32 v[202:203], v[202:203], s[14:15], v[44:45] op_sel_hi:[1,0,1]
	v_cvt_pk_bf16_f32 v196, v196, v197
	v_cvt_pk_bf16_f32 v197, v198, v199
	v_cvt_pk_bf16_f32 v198, v200, v201
	v_cvt_pk_bf16_f32 v199, v202, v203
	s_add_u32 s66, s10, 0x90000
	s_addc_u32 s67, s11, 0
	global_store_dwordx4 v147, v[196:199], s[66:67]
	s_waitcnt vmcnt(11)
	v_pk_fma_f32 v[204:205], v[204:205], s[14:15], v[38:39] op_sel_hi:[1,0,1]
	v_pk_fma_f32 v[206:207], v[206:207], s[14:15], v[40:41] op_sel_hi:[1,0,1]
	v_pk_fma_f32 v[208:209], v[208:209], s[14:15], v[34:35] op_sel_hi:[1,0,1]
	v_pk_fma_f32 v[210:211], v[210:211], s[14:15], v[36:37] op_sel_hi:[1,0,1]
	v_cvt_pk_bf16_f32 v204, v204, v205
	v_cvt_pk_bf16_f32 v205, v206, v207
	v_cvt_pk_bf16_f32 v206, v208, v209
	v_cvt_pk_bf16_f32 v207, v210, v211
	s_add_u32 s66, s10, 0x90100
	s_addc_u32 s67, s11, 0
	global_store_dwordx4 v147, v[204:207], s[66:67]
	s_waitcnt vmcnt(10)
	v_pk_fma_f32 v[212:213], v[212:213], s[14:15], v[30:31] op_sel_hi:[1,0,1]
	v_pk_fma_f32 v[214:215], v[214:215], s[14:15], v[32:33] op_sel_hi:[1,0,1]
	v_pk_fma_f32 v[216:217], v[216:217], s[14:15], v[26:27] op_sel_hi:[1,0,1]
	v_pk_fma_f32 v[218:219], v[218:219], s[14:15], v[28:29] op_sel_hi:[1,0,1]
	v_cvt_pk_bf16_f32 v212, v212, v213
	v_cvt_pk_bf16_f32 v213, v214, v215
	v_cvt_pk_bf16_f32 v214, v216, v217
	v_cvt_pk_bf16_f32 v215, v218, v219
	s_add_u32 s66, s10, 0xa0000
	s_addc_u32 s67, s11, 0
	global_store_dwordx4 v147, v[212:215], s[66:67]
	s_waitcnt vmcnt(9)
	v_pk_fma_f32 v[220:221], v[220:221], s[14:15], v[22:23] op_sel_hi:[1,0,1]
	v_pk_fma_f32 v[222:223], v[222:223], s[14:15], v[24:25] op_sel_hi:[1,0,1]
	v_pk_fma_f32 v[224:225], v[224:225], s[14:15], v[18:19] op_sel_hi:[1,0,1]
	v_pk_fma_f32 v[226:227], v[226:227], s[14:15], v[20:21] op_sel_hi:[1,0,1]
	v_cvt_pk_bf16_f32 v220, v220, v221
	v_cvt_pk_bf16_f32 v221, v222, v223
	v_cvt_pk_bf16_f32 v222, v224, v225
	v_cvt_pk_bf16_f32 v223, v226, v227
	s_add_u32 s66, s10, 0xa0100
	s_addc_u32 s67, s11, 0
	global_store_dwordx4 v147, v[220:223], s[66:67]
	s_waitcnt vmcnt(8)
	v_pk_fma_f32 v[228:229], v[228:229], s[14:15], v[14:15] op_sel_hi:[1,0,1]
	v_pk_fma_f32 v[230:231], v[230:231], s[14:15], v[16:17] op_sel_hi:[1,0,1]
	v_pk_fma_f32 v[232:233], v[232:233], s[14:15], v[10:11] op_sel_hi:[1,0,1]
	v_pk_fma_f32 v[234:235], v[234:235], s[14:15], v[12:13] op_sel_hi:[1,0,1]
	v_cvt_pk_bf16_f32 v228, v228, v229
	v_cvt_pk_bf16_f32 v229, v230, v231
	v_cvt_pk_bf16_f32 v230, v232, v233
	v_cvt_pk_bf16_f32 v231, v234, v235
	s_add_u32 s66, s10, 0xb0000
	s_addc_u32 s67, s11, 0
	global_store_dwordx4 v147, v[228:231], s[66:67]
	s_waitcnt vmcnt(7)
	v_pk_fma_f32 v[236:237], v[236:237], s[14:15], v[6:7] op_sel_hi:[1,0,1]
	v_pk_fma_f32 v[238:239], v[238:239], s[14:15], v[8:9] op_sel_hi:[1,0,1]
	v_pk_fma_f32 v[240:241], v[240:241], s[14:15], v[2:3] op_sel_hi:[1,0,1]
	v_pk_fma_f32 v[242:243], v[242:243], s[14:15], v[4:5] op_sel_hi:[1,0,1]
	v_cvt_pk_bf16_f32 v236, v236, v237
	v_cvt_pk_bf16_f32 v237, v238, v239
	v_cvt_pk_bf16_f32 v238, v240, v241
	v_cvt_pk_bf16_f32 v239, v242, v243
	s_add_u32 s66, s10, 0xb0100
	s_addc_u32 s67, s11, 0
	global_store_dwordx4 v147, v[236:239], s[66:67]
	s_and_b64 vcc, exec, s[6:7]
	s_mov_b32 s40, s28
	s_mov_b32 s38, s30
	s_mov_b64 s[44:45], s[36:37]
	s_mov_b64 s[42:43], s[34:35]
	s_cbranch_vccz .LBB0_843
	s_waitcnt vmcnt(0)
	s_cmpk_gt_u32 s3, 0xff
	s_cbranch_scc1 .LBB0_854
	s_barrier

.LBB0_1019:
	s_add_u32 s44, s68, 0xfff80080
	s_addc_u32 s45, s69, -1
	s_add_i32 s48, 0, 0x10000
	v_add_u32_e32 v144, s48, v141
	ds_read_b128 v[158:161], v144
	ds_read_b128 v[162:165], v144 offset:1024
	ds_read_b128 v[166:169], v144 offset:2048
	ds_read_b128 v[170:173], v144 offset:3072
	s_cmp_eq_u32 s47, 28
	s_cselect_b32 s95, s11, s45
	s_cselect_b32 s94, s43, s44
	s_cselect_b32 s45, s13, s7
	s_cselect_b32 s44, s46, s6
	v_lshl_add_u64 v[144:145], s[68:69], 0, v[136:137]
	s_add_i32 m0, s23, 0xc000
	ds_read_b128 v[174:177], v143
	ds_read_b128 v[178:181], v143 offset:1024
	ds_read_b128 v[182:185], v143 offset:2048
	ds_read_b128 v[186:189], v143 offset:3072
	ds_read_b128 v[206:209], v143 offset:4096
	ds_read_b128 v[210:213], v143 offset:5120
	ds_read_b128 v[214:217], v143 offset:6144
	ds_read_b128 v[218:221], v143 offset:7168
	global_load_lds_dwordx4 v[144:145], off
	v_lshl_add_u64 v[144:145], s[68:69], 0, v[138:139]
	s_add_i32 m0, s23, 0xe000
	s_nop 0
	global_load_lds_dwordx4 v[144:145], off
	s_waitcnt lgkmcnt(8)
	s_barrier
	s_waitcnt lgkmcnt(0)
	s_setprio 1
	s_waitcnt lgkmcnt(0)
	v_mfma_f32_16x16x32_bf16 v[126:129], v[158:161], v[174:177], v[126:129]
	v_mfma_f32_16x16x32_bf16 v[122:125], v[166:169], v[174:177], v[122:125]
	v_mfma_f32_16x16x32_bf16 v[118:121], v[158:161], v[182:185], v[118:121]
	v_mfma_f32_16x16x32_bf16 v[114:117], v[166:169], v[182:185], v[114:117]
	v_mfma_f32_16x16x32_bf16 v[102:105], v[158:161], v[206:209], v[102:105]
	v_mfma_f32_16x16x32_bf16 v[98:101], v[166:169], v[206:209], v[98:101]
	v_mfma_f32_16x16x32_bf16 v[86:89], v[158:161], v[214:217], v[86:89]
	v_mfma_f32_16x16x32_bf16 v[82:85], v[166:169], v[214:217], v[82:85]
	v_mfma_f32_16x16x32_bf16 v[126:129], v[162:165], v[178:181], v[126:129]
	v_mfma_f32_16x16x32_bf16 v[122:125], v[170:173], v[178:181], v[122:125]
	v_mfma_f32_16x16x32_bf16 v[118:121], v[162:165], v[186:189], v[118:121]
	v_mfma_f32_16x16x32_bf16 v[114:117], v[170:173], v[186:189], v[114:117]
	v_mfma_f32_16x16x32_bf16 v[102:105], v[162:165], v[210:213], v[102:105]
	v_mfma_f32_16x16x32_bf16 v[98:101], v[170:173], v[210:213], v[98:101]
	v_mfma_f32_16x16x32_bf16 v[86:89], v[162:165], v[218:221], v[86:89]
	s_setprio 2
	s_barrier
	v_mfma_f32_16x16x32_bf16 v[82:85], v[170:173], v[218:221], v[82:85]
	s_setprio 0
	s_add_i32 s50, 0, 0x14000
	v_add_u32_e32 v144, s50, v141
	s_add_i32 s48, s48, s22
	ds_read_b128 v[222:225], v144
	ds_read_b128 v[226:229], v144 offset:1024
	ds_read_b128 v[230:233], v144 offset:2048
	ds_read_b128 v[234:237], v144 offset:3072
	v_lshl_add_u64 v[144:145], s[44:45], 0, v[0:1]
	s_mov_b32 m0, s48
	v_lshl_add_u64 v[238:239], s[44:45], 0, v[130:131]
	global_load_lds_dwordx4 v[144:145], off
	s_add_i32 m0, s48, 0x2000
	s_nop 0
	global_load_lds_dwordx4 v[238:239], off
	s_barrier
	s_waitcnt lgkmcnt(0)
	s_setprio 1
	s_waitcnt lgkmcnt(0)
	v_mfma_f32_16x16x32_bf16 v[110:113], v[222:225], v[174:177], v[110:113]
	v_mfma_f32_16x16x32_bf16 v[106:109], v[230:233], v[174:177], v[106:109]
	v_mfma_f32_16x16x32_bf16 v[94:97], v[222:225], v[182:185], v[94:97]
	v_mfma_f32_16x16x32_bf16 v[90:93], v[230:233], v[182:185], v[90:93]
	v_mfma_f32_16x16x32_bf16 v[78:81], v[222:225], v[206:209], v[78:81]
	v_mfma_f32_16x16x32_bf16 v[74:77], v[230:233], v[206:209], v[74:77]
	v_mfma_f32_16x16x32_bf16 v[70:73], v[222:225], v[214:217], v[70:73]
	v_mfma_f32_16x16x32_bf16 v[66:69], v[230:233], v[214:217], v[66:69]
	v_mfma_f32_16x16x32_bf16 v[110:113], v[226:229], v[178:181], v[110:113]
	v_mfma_f32_16x16x32_bf16 v[106:109], v[234:237], v[178:181], v[106:109]
	v_mfma_f32_16x16x32_bf16 v[94:97], v[226:229], v[186:189], v[94:97]
	v_mfma_f32_16x16x32_bf16 v[90:93], v[234:237], v[186:189], v[90:93]
	v_mfma_f32_16x16x32_bf16 v[78:81], v[226:229], v[210:213], v[78:81]
	v_mfma_f32_16x16x32_bf16 v[74:77], v[234:237], v[210:213], v[74:77]
	v_mfma_f32_16x16x32_bf16 v[70:73], v[226:229], v[218:221], v[70:73]
	s_setprio 2
	s_mov_b32 m0, s23
	v_lshl_add_u64 v[240:241], s[94:95], 0, v[134:135]
	s_barrier
	v_mfma_f32_16x16x32_bf16 v[66:69], v[234:237], v[218:221], v[66:69]
	s_setprio 0
	ds_read_b128 v[174:177], v143 offset:16384
	ds_read_b128 v[178:181], v143 offset:17408
	ds_read_b128 v[182:185], v143 offset:18432
	ds_read_b128 v[186:189], v143 offset:19456
	ds_read_b128 v[206:209], v143 offset:20480
	ds_read_b128 v[210:213], v143 offset:21504
	ds_read_b128 v[214:217], v143 offset:22528
	ds_read_b128 v[218:221], v143 offset:23552
	global_load_lds_dwordx4 v[240:241], off
	v_lshl_add_u64 v[242:243], s[94:95], 0, v[132:133]
	s_mov_b32 m0, s26
	s_nop 0
	global_load_lds_dwordx4 v[242:243], off
	s_barrier
	s_waitcnt lgkmcnt(0)
	s_setprio 1
	s_waitcnt lgkmcnt(0)
	v_mfma_f32_16x16x32_bf16 v[62:65], v[158:161], v[174:177], v[62:65]
	v_mfma_f32_16x16x32_bf16 v[58:61], v[166:169], v[174:177], v[58:61]
	v_mfma_f32_16x16x32_bf16 v[54:57], v[158:161], v[182:185], v[54:57]
	v_mfma_f32_16x16x32_bf16 v[50:53], v[166:169], v[182:185], v[50:53]
	v_mfma_f32_16x16x32_bf16 v[38:41], v[158:161], v[206:209], v[38:41]
	v_mfma_f32_16x16x32_bf16 v[34:37], v[166:169], v[206:209], v[34:37]
	v_mfma_f32_16x16x32_bf16 v[22:25], v[158:161], v[214:217], v[22:25]
	v_mfma_f32_16x16x32_bf16 v[18:21], v[166:169], v[214:217], v[18:21]
	v_mfma_f32_16x16x32_bf16 v[62:65], v[162:165], v[178:181], v[62:65]
	v_mfma_f32_16x16x32_bf16 v[58:61], v[170:173], v[178:181], v[58:61]
	v_mfma_f32_16x16x32_bf16 v[54:57], v[162:165], v[186:189], v[54:57]
	v_mfma_f32_16x16x32_bf16 v[50:53], v[170:173], v[186:189], v[50:53]
	v_mfma_f32_16x16x32_bf16 v[38:41], v[162:165], v[210:213], v[38:41]
	v_mfma_f32_16x16x32_bf16 v[34:37], v[170:173], v[210:213], v[34:37]
	v_mfma_f32_16x16x32_bf16 v[22:25], v[162:165], v[218:221], v[22:25]
	s_setprio 2
	s_barrier
	v_mfma_f32_16x16x32_bf16 v[18:21], v[170:173], v[218:221], v[18:21]
	s_setprio 0
	s_add_u32 s48, s44, 0x80000
	s_addc_u32 s49, s45, 0
	s_add_i32 s50, s50, s22
	v_lshl_add_u64 v[158:159], s[48:49], 0, v[0:1]
	s_mov_b32 m0, s50
	s_nop 0
	global_load_lds_dwordx4 v[158:159], off
	v_lshl_add_u64 v[158:159], s[48:49], 0, v[130:131]
	s_add_i32 m0, s50, 0x2000
	s_nop 0
	global_load_lds_dwordx4 v[158:159], off
	s_waitcnt vmcnt(6)
	s_barrier
	s_setprio 1
	v_mfma_f32_16x16x32_bf16 v[46:49], v[222:225], v[174:177], v[46:49]
	v_mfma_f32_16x16x32_bf16 v[42:45], v[230:233], v[174:177], v[42:45]
	v_mfma_f32_16x16x32_bf16 v[30:33], v[222:225], v[182:185], v[30:33]
	v_mfma_f32_16x16x32_bf16 v[26:29], v[230:233], v[182:185], v[26:29]
	v_mfma_f32_16x16x32_bf16 v[14:17], v[222:225], v[206:209], v[14:17]
	v_mfma_f32_16x16x32_bf16 v[10:13], v[230:233], v[206:209], v[10:13]
	v_mfma_f32_16x16x32_bf16 v[6:9], v[222:225], v[214:217], v[6:9]
	v_mfma_f32_16x16x32_bf16 v[2:5], v[230:233], v[214:217], v[2:5]
	v_mfma_f32_16x16x32_bf16 v[46:49], v[226:229], v[178:181], v[46:49]
	v_mfma_f32_16x16x32_bf16 v[42:45], v[234:237], v[178:181], v[42:45]
	v_mfma_f32_16x16x32_bf16 v[30:33], v[226:229], v[186:189], v[30:33]
	v_mfma_f32_16x16x32_bf16 v[26:29], v[234:237], v[186:189], v[26:29]
	v_mfma_f32_16x16x32_bf16 v[14:17], v[226:229], v[210:213], v[14:17]
	v_mfma_f32_16x16x32_bf16 v[10:13], v[234:237], v[210:213], v[10:13]
	v_mfma_f32_16x16x32_bf16 v[6:9], v[226:229], v[218:221], v[6:9]
	s_setprio 2
	s_add_i32 s50, 0, 0x18000
	v_add_u32_e32 v170, s50, v141
	s_barrier
	v_mfma_f32_16x16x32_bf16 v[2:5], v[234:237], v[218:221], v[2:5]
	s_setprio 0
	ds_read_b128 v[158:161], v170
	ds_read_b128 v[162:165], v170 offset:1024
	ds_read_b128 v[166:169], v170 offset:2048
	ds_read_b128 v[170:173], v170 offset:3072
	s_add_u32 s48, s94, 0x80000
	s_addc_u32 s49, s95, 0
	s_mov_b32 m0, s27
	v_lshl_add_u64 v[222:223], s[48:49], 0, v[134:135]
	ds_read_b128 v[174:177], v143 offset:32768
	ds_read_b128 v[178:181], v143 offset:33792
	ds_read_b128 v[182:185], v143 offset:34816
	ds_read_b128 v[186:189], v143 offset:35840
	ds_read_b128 v[206:209], v143 offset:36864
	ds_read_b128 v[210:213], v143 offset:37888
	ds_read_b128 v[214:217], v143 offset:38912
	ds_read_b128 v[218:221], v143 offset:39936
	global_load_lds_dwordx4 v[222:223], off
	v_lshl_add_u64 v[222:223], s[48:49], 0, v[132:133]
	s_mov_b32 m0, s28
	s_nop 0
	global_load_lds_dwordx4 v[222:223], off
	s_waitcnt lgkmcnt(8)
	s_barrier
	s_waitcnt lgkmcnt(0)
	s_setprio 1
	s_waitcnt lgkmcnt(0)
	v_mfma_f32_16x16x32_bf16 v[126:129], v[158:161], v[174:177], v[126:129]
	v_mfma_f32_16x16x32_bf16 v[122:125], v[166:169], v[174:177], v[122:125]
	v_mfma_f32_16x16x32_bf16 v[118:121], v[158:161], v[182:185], v[118:121]
	v_mfma_f32_16x16x32_bf16 v[114:117], v[166:169], v[182:185], v[114:117]
	v_mfma_f32_16x16x32_bf16 v[102:105], v[158:161], v[206:209], v[102:105]
	v_mfma_f32_16x16x32_bf16 v[98:101], v[166:169], v[206:209], v[98:101]
	v_mfma_f32_16x16x32_bf16 v[86:89], v[158:161], v[214:217], v[86:89]
	v_mfma_f32_16x16x32_bf16 v[82:85], v[166:169], v[214:217], v[82:85]
	v_mfma_f32_16x16x32_bf16 v[126:129], v[162:165], v[178:181], v[126:129]
	v_mfma_f32_16x16x32_bf16 v[122:125], v[170:173], v[178:181], v[122:125]
	v_mfma_f32_16x16x32_bf16 v[118:121], v[162:165], v[186:189], v[118:121]
	v_mfma_f32_16x16x32_bf16 v[114:117], v[170:173], v[186:189], v[114:117]
	v_mfma_f32_16x16x32_bf16 v[102:105], v[162:165], v[210:213], v[102:105]
	v_mfma_f32_16x16x32_bf16 v[98:101], v[170:173], v[210:213], v[98:101]
	v_mfma_f32_16x16x32_bf16 v[86:89], v[162:165], v[218:221], v[86:89]
	s_setprio 2
	s_barrier
	v_mfma_f32_16x16x32_bf16 v[82:85], v[170:173], v[218:221], v[82:85]
	s_setprio 0
	s_add_i32 s48, 0, 0x1c000
	s_add_i32 s49, s50, s22
	v_add_u32_e32 v205, s48, v141
	v_lshl_add_u64 v[144:145], v[144:145], 0, s[62:63]
	s_mov_b32 m0, s49
	ds_read_b128 v[222:225], v205
	ds_read_b128 v[226:229], v205 offset:1024
	ds_read_b128 v[230:233], v205 offset:2048
	ds_read_b128 v[234:237], v205 offset:3072
	global_load_lds_dwordx4 v[144:145], off
	v_lshl_add_u64 v[144:145], v[238:239], 0, s[62:63]
	s_add_i32 m0, s49, 0x2000
	s_nop 0
	global_load_lds_dwordx4 v[144:145], off
	s_barrier
	s_waitcnt lgkmcnt(0)
	s_setprio 1
	s_waitcnt lgkmcnt(0)
	v_mfma_f32_16x16x32_bf16 v[110:113], v[222:225], v[174:177], v[110:113]
	v_mfma_f32_16x16x32_bf16 v[106:109], v[230:233], v[174:177], v[106:109]
	v_mfma_f32_16x16x32_bf16 v[94:97], v[222:225], v[182:185], v[94:97]
	v_mfma_f32_16x16x32_bf16 v[90:93], v[230:233], v[182:185], v[90:93]
	v_mfma_f32_16x16x32_bf16 v[78:81], v[222:225], v[206:209], v[78:81]
	v_mfma_f32_16x16x32_bf16 v[74:77], v[230:233], v[206:209], v[74:77]
	v_mfma_f32_16x16x32_bf16 v[70:73], v[222:225], v[214:217], v[70:73]
	v_mfma_f32_16x16x32_bf16 v[66:69], v[230:233], v[214:217], v[66:69]
	v_mfma_f32_16x16x32_bf16 v[110:113], v[226:229], v[178:181], v[110:113]
	v_mfma_f32_16x16x32_bf16 v[106:109], v[234:237], v[178:181], v[106:109]
	v_mfma_f32_16x16x32_bf16 v[94:97], v[226:229], v[186:189], v[94:97]
	v_mfma_f32_16x16x32_bf16 v[90:93], v[234:237], v[186:189], v[90:93]
	v_mfma_f32_16x16x32_bf16 v[78:81], v[226:229], v[210:213], v[78:81]
	v_mfma_f32_16x16x32_bf16 v[74:77], v[234:237], v[210:213], v[74:77]
	v_mfma_f32_16x16x32_bf16 v[70:73], v[226:229], v[218:221], v[70:73]
	s_setprio 2
	s_mov_b32 m0, s36
	v_lshl_add_u64 v[144:145], v[240:241], 0, s[62:63]
	s_barrier
	v_mfma_f32_16x16x32_bf16 v[66:69], v[234:237], v[218:221], v[66:69]
	s_setprio 0
	ds_read_b128 v[174:177], v143 offset:49152
	ds_read_b128 v[178:181], v143 offset:50176
	ds_read_b128 v[182:185], v143 offset:51200
	ds_read_b128 v[186:189], v143 offset:52224
	ds_read_b128 v[206:209], v143 offset:53248
	ds_read_b128 v[210:213], v143 offset:54272
	ds_read_b128 v[214:217], v143 offset:55296
	ds_read_b128 v[218:221], v143 offset:56320
	global_load_lds_dwordx4 v[144:145], off
	v_lshl_add_u64 v[144:145], v[242:243], 0, s[62:63]
	s_mov_b32 m0, s37
	s_nop 0
	global_load_lds_dwordx4 v[144:145], off
	s_barrier
	s_waitcnt lgkmcnt(0)
	s_setprio 1
	s_waitcnt lgkmcnt(0)
	v_mfma_f32_16x16x32_bf16 v[62:65], v[158:161], v[174:177], v[62:65]
	v_mfma_f32_16x16x32_bf16 v[58:61], v[166:169], v[174:177], v[58:61]
	v_mfma_f32_16x16x32_bf16 v[54:57], v[158:161], v[182:185], v[54:57]
	v_mfma_f32_16x16x32_bf16 v[50:53], v[166:169], v[182:185], v[50:53]
	v_mfma_f32_16x16x32_bf16 v[38:41], v[158:161], v[206:209], v[38:41]
	v_mfma_f32_16x16x32_bf16 v[34:37], v[166:169], v[206:209], v[34:37]
	v_mfma_f32_16x16x32_bf16 v[22:25], v[158:161], v[214:217], v[22:25]
	v_mfma_f32_16x16x32_bf16 v[18:21], v[166:169], v[214:217], v[18:21]
	v_mfma_f32_16x16x32_bf16 v[62:65], v[162:165], v[178:181], v[62:65]
	v_mfma_f32_16x16x32_bf16 v[58:61], v[170:173], v[178:181], v[58:61]
	v_mfma_f32_16x16x32_bf16 v[54:57], v[162:165], v[186:189], v[54:57]
	v_mfma_f32_16x16x32_bf16 v[50:53], v[170:173], v[186:189], v[50:53]
	v_mfma_f32_16x16x32_bf16 v[38:41], v[162:165], v[210:213], v[38:41]
	v_mfma_f32_16x16x32_bf16 v[34:37], v[170:173], v[210:213], v[34:37]
	v_mfma_f32_16x16x32_bf16 v[22:25], v[162:165], v[218:221], v[22:25]
	s_setprio 2
	s_barrier
	v_mfma_f32_16x16x32_bf16 v[18:21], v[170:173], v[218:221], v[18:21]
	s_setprio 0
	s_add_u32 s44, s44, 0x80080
	s_addc_u32 s45, s45, 0
	s_add_i32 s48, s48, s22
	v_lshl_add_u64 v[144:145], s[44:45], 0, v[0:1]
	s_mov_b32 m0, s48
	s_nop 0
	global_load_lds_dwordx4 v[144:145], off
	v_lshl_add_u64 v[144:145], s[44:45], 0, v[130:131]
	s_add_i32 m0, s48, 0x2000
	s_nop 0
	global_load_lds_dwordx4 v[144:145], off
	s_waitcnt vmcnt(6)
	s_barrier
	s_setprio 1
	v_mfma_f32_16x16x32_bf16 v[46:49], v[222:225], v[174:177], v[46:49]
	v_mfma_f32_16x16x32_bf16 v[42:45], v[230:233], v[174:177], v[42:45]
	v_mfma_f32_16x16x32_bf16 v[30:33], v[222:225], v[182:185], v[30:33]
	v_mfma_f32_16x16x32_bf16 v[26:29], v[230:233], v[182:185], v[26:29]
	v_mfma_f32_16x16x32_bf16 v[14:17], v[222:225], v[206:209], v[14:17]
	v_mfma_f32_16x16x32_bf16 v[10:13], v[230:233], v[206:209], v[10:13]
	v_mfma_f32_16x16x32_bf16 v[6:9], v[222:225], v[214:217], v[6:9]
	v_mfma_f32_16x16x32_bf16 v[2:5], v[230:233], v[214:217], v[2:5]
	v_mfma_f32_16x16x32_bf16 v[46:49], v[226:229], v[178:181], v[46:49]
	v_mfma_f32_16x16x32_bf16 v[42:45], v[234:237], v[178:181], v[42:45]
	v_mfma_f32_16x16x32_bf16 v[30:33], v[226:229], v[186:189], v[30:33]
	v_mfma_f32_16x16x32_bf16 v[26:29], v[234:237], v[186:189], v[26:29]
	v_mfma_f32_16x16x32_bf16 v[14:17], v[226:229], v[210:213], v[14:17]
	v_mfma_f32_16x16x32_bf16 v[10:13], v[234:237], v[210:213], v[10:13]
	v_mfma_f32_16x16x32_bf16 v[6:9], v[226:229], v[218:221], v[6:9]
	s_setprio 2
	s_add_i32 s47, s47, 2
	s_add_u32 s68, s68, 0x100
	s_addc_u32 s69, s69, 0
	s_add_u32 s6, s6, 0x100
	s_addc_u32 s7, s7, 0
	s_cmp_gt_u32 s47, 29
	s_barrier
	v_mfma_f32_16x16x32_bf16 v[2:5], v[234:237], v[218:221], v[2:5]
	s_setprio 0
	s_cbranch_scc0 .LBB0_1019
	s_lshl_b32 s6, s42, 8
	s_and_b32 s6, s6, 0x3f00
	v_add_u32_e32 v160, s6, v140
	s_mul_hi_i32 s6, s41, 0x2aaaaaab
	s_lshr_b32 s7, s6, 31
	s_lshr_b32 s6, s6, 2
	s_add_i32 s6, s6, s7
	s_mul_i32 s6, s6, 24
	s_sub_i32 s6, s41, s6
	v_lshl_or_b32 v144, s6, 8, v142
	v_ashrrev_i32_e32 v145, 31, v144
	v_lshl_add_u64 v[144:145], v[144:145], 1, s[84:85]
	v_cvt_pk_bf16_f32 v70, v70, v71
	v_cvt_pk_bf16_f32 v71, v72, v73
	v_cvt_pk_bf16_f32 v72, v66, v67
	v_add_u32_e32 v66, 0x80, v160
	v_mad_i64_i32 v[158:159], s[6:7], v160, s34, v[144:145]
	v_cvt_pk_bf16_f32 v110, v110, v111
	v_cvt_pk_bf16_f32 v111, v112, v113
	v_cvt_pk_bf16_f32 v112, v106, v107
	v_cvt_pk_bf16_f32 v113, v108, v109
	v_or_b32_e32 v106, 16, v160
	v_mad_i64_i32 v[66:67], s[6:7], v66, s34, v[144:145]
	v_cvt_pk_bf16_f32 v46, v46, v47
	v_cvt_pk_bf16_f32 v47, v48, v49
	v_cvt_pk_bf16_f32 v48, v42, v43
	v_cvt_pk_bf16_f32 v49, v44, v45
	v_add_u32_e32 v42, 0x90, v160
	global_store_dwordx4 v[158:159], v[110:113], off offset:256
	v_cvt_pk_bf16_f32 v94, v94, v95
	v_cvt_pk_bf16_f32 v95, v96, v97
	v_mad_i64_i32 v[110:111], s[6:7], v106, s34, v[144:145]
	v_cvt_pk_bf16_f32 v96, v90, v91
	v_cvt_pk_bf16_f32 v97, v92, v93
	v_or_b32_e32 v90, 32, v160
	global_store_dwordx4 v[66:67], v[46:49], off offset:256
	v_cvt_pk_bf16_f32 v30, v30, v31
	v_cvt_pk_bf16_f32 v31, v32, v33
	v_mad_i64_i32 v[46:47], s[6:7], v42, s34, v[144:145]
	v_cvt_pk_bf16_f32 v32, v26, v27
	v_cvt_pk_bf16_f32 v33, v28, v29
	v_add_u32_e32 v26, 0xa0, v160
	global_store_dwordx4 v[110:111], v[94:97], off offset:256
	v_cvt_pk_bf16_f32 v78, v78, v79
	v_cvt_pk_bf16_f32 v79, v80, v81
	v_mad_i64_i32 v[94:95], s[6:7], v90, s34, v[144:145]
	v_cvt_pk_bf16_f32 v80, v74, v75
	v_cvt_pk_bf16_f32 v81, v76, v77
	v_or_b32_e32 v74, 48, v160
	global_store_dwordx4 v[46:47], v[30:33], off offset:256
	v_cvt_pk_bf16_f32 v14, v14, v15
	v_cvt_pk_bf16_f32 v15, v16, v17
	v_mad_i64_i32 v[30:31], s[6:7], v26, s34, v[144:145]
	v_cvt_pk_bf16_f32 v16, v10, v11
	v_cvt_pk_bf16_f32 v17, v12, v13
	v_add_u32_e32 v10, 0xb0, v160
	global_store_dwordx4 v[94:95], v[78:81], off offset:256
	global_store_dwordx4 v[30:31], v[14:17], off offset:256
	v_cvt_pk_bf16_f32 v126, v126, v127
	v_mad_i64_i32 v[78:79], s[6:7], v74, s34, v[144:145]
	v_mad_i64_i32 v[14:15], s[6:7], v10, s34, v[144:145]
	v_cvt_pk_bf16_f32 v127, v128, v129
	v_cvt_pk_bf16_f32 v128, v122, v123
	v_cvt_pk_bf16_f32 v129, v124, v125
	v_cvt_pk_bf16_f32 v106, v118, v119
	v_cvt_pk_bf16_f32 v107, v120, v121
	v_cvt_pk_bf16_f32 v108, v114, v115
	v_cvt_pk_bf16_f32 v109, v116, v117
	v_cvt_pk_bf16_f32 v90, v102, v103
	v_cvt_pk_bf16_f32 v91, v104, v105
	v_cvt_pk_bf16_f32 v92, v98, v99
	v_cvt_pk_bf16_f32 v93, v100, v101
	v_cvt_pk_bf16_f32 v74, v86, v87
	v_cvt_pk_bf16_f32 v75, v88, v89
	v_cvt_pk_bf16_f32 v76, v82, v83
	v_cvt_pk_bf16_f32 v77, v84, v85
	v_cvt_pk_bf16_f32 v73, v68, v69
	v_cvt_pk_bf16_f32 v62, v62, v63
	v_cvt_pk_bf16_f32 v63, v64, v65
	v_cvt_pk_bf16_f32 v64, v58, v59
	v_cvt_pk_bf16_f32 v65, v60, v61
	v_cvt_pk_bf16_f32 v42, v54, v55
	v_cvt_pk_bf16_f32 v43, v56, v57
	v_cvt_pk_bf16_f32 v44, v50, v51
	v_cvt_pk_bf16_f32 v45, v52, v53
	v_cvt_pk_bf16_f32 v26, v38, v39
	v_cvt_pk_bf16_f32 v27, v40, v41
	v_cvt_pk_bf16_f32 v28, v34, v35
	v_cvt_pk_bf16_f32 v29, v36, v37
	v_cvt_pk_bf16_f32 v10, v22, v23
	v_cvt_pk_bf16_f32 v11, v24, v25
	v_cvt_pk_bf16_f32 v12, v18, v19
	v_cvt_pk_bf16_f32 v13, v20, v21
	v_cvt_pk_bf16_f32 v6, v6, v7
	v_cvt_pk_bf16_f32 v7, v8, v9
	v_cvt_pk_bf16_f32 v8, v2, v3
	v_cvt_pk_bf16_f32 v9, v4, v5
	s_and_b64 vcc, exec, s[8:9]
	s_mov_b32 s41, s12
	s_mov_b32 s42, s10
	s_mov_b64 s[94:95], s[64:65]
	s_mov_b64 s[6:7], s[14:15]
	global_store_dwordx4 v[158:159], v[126:129], off
	global_store_dwordx4 v[110:111], v[106:109], off
	global_store_dwordx4 v[94:95], v[90:93], off
	global_store_dwordx4 v[78:79], v[74:77], off
	global_store_dwordx4 v[78:79], v[70:73], off offset:256
	global_store_dwordx4 v[66:67], v[62:65], off
	global_store_dwordx4 v[46:47], v[42:45], off
	global_store_dwordx4 v[30:31], v[26:29], off
	global_store_dwordx4 v[14:15], v[10:13], off
	global_store_dwordx4 v[14:15], v[6:9], off offset:256
	s_cbranch_vccz .LBB0_1016
	s_waitcnt vmcnt(0)
	s_cmpk_gt_u32 s5, 0xff
	s_cbranch_scc1 .LBB0_1023
	s_barrier

.LBB0_1256:
	s_add_u32 s44, s64, 0xfff80080
	s_addc_u32 s45, s65, -1
	s_add_i32 s48, 0, 0x10000
	v_add_u32_e32 v102, s48, v187
	ds_read_b128 v[90:93], v102
	ds_read_b128 v[94:97], v102 offset:1024
	ds_read_b128 v[98:101], v102 offset:2048
	ds_read_b128 v[102:105], v102 offset:3072
	s_cmp_eq_u32 s47, 28
	s_cselect_b32 s69, s4, s45
	s_cselect_b32 s68, s5, s44
	s_cselect_b32 s45, s6, s19
	s_cselect_b32 s44, s7, s18
	v_lshl_add_u64 v[184:185], s[64:65], 0, v[164:165]
	s_add_i32 m0, s27, 0xc000
	ds_read_b128 v[168:171], v189
	ds_read_b128 v[172:175], v189 offset:1024
	ds_read_b128 v[176:179], v189 offset:2048
	ds_read_b128 v[180:183], v189 offset:3072
	ds_read_b128 v[206:209], v189 offset:4096
	ds_read_b128 v[210:213], v189 offset:5120
	ds_read_b128 v[214:217], v189 offset:6144
	ds_read_b128 v[218:221], v189 offset:7168
	global_load_lds_dwordx4 v[184:185], off
	v_lshl_add_u64 v[184:185], s[64:65], 0, v[166:167]
	s_add_i32 m0, s27, 0xe000
	s_nop 0
	global_load_lds_dwordx4 v[184:185], off
	s_waitcnt lgkmcnt(8)
	s_barrier
	s_waitcnt lgkmcnt(0)
	s_setprio 1
	s_waitcnt lgkmcnt(0)
	v_mfma_f32_16x16x32_bf16 v[142:145], v[90:93], v[168:171], v[142:145]
	v_mfma_f32_16x16x32_bf16 v[138:141], v[98:101], v[168:171], v[138:141]
	v_mfma_f32_16x16x32_bf16 v[134:137], v[90:93], v[176:179], v[134:137]
	v_mfma_f32_16x16x32_bf16 v[130:133], v[98:101], v[176:179], v[130:133]
	v_mfma_f32_16x16x32_bf16 v[126:129], v[90:93], v[206:209], v[126:129]
	v_mfma_f32_16x16x32_bf16 v[122:125], v[98:101], v[206:209], v[122:125]
	v_mfma_f32_16x16x32_bf16 v[118:121], v[90:93], v[214:217], v[118:121]
	v_mfma_f32_16x16x32_bf16 v[114:117], v[98:101], v[214:217], v[114:117]
	v_mfma_f32_16x16x32_bf16 v[142:145], v[94:97], v[172:175], v[142:145]
	v_mfma_f32_16x16x32_bf16 v[138:141], v[102:105], v[172:175], v[138:141]
	v_mfma_f32_16x16x32_bf16 v[134:137], v[94:97], v[180:183], v[134:137]
	v_mfma_f32_16x16x32_bf16 v[130:133], v[102:105], v[180:183], v[130:133]
	v_mfma_f32_16x16x32_bf16 v[126:129], v[94:97], v[210:213], v[126:129]
	v_mfma_f32_16x16x32_bf16 v[122:125], v[102:105], v[210:213], v[122:125]
	v_mfma_f32_16x16x32_bf16 v[118:121], v[94:97], v[218:221], v[118:121]
	s_setprio 2
	s_barrier
	v_mfma_f32_16x16x32_bf16 v[114:117], v[102:105], v[218:221], v[114:117]
	s_setprio 0
	s_add_i32 s50, 0, 0x14000
	v_add_u32_e32 v184, s50, v187
	s_add_i32 s48, s48, s22
	ds_read_b128 v[222:225], v184
	ds_read_b128 v[226:229], v184 offset:1024
	ds_read_b128 v[230:233], v184 offset:2048
	ds_read_b128 v[234:237], v184 offset:3072
	v_lshl_add_u64 v[184:185], s[44:45], 0, v[0:1]
	s_mov_b32 m0, s48
	v_lshl_add_u64 v[238:239], s[44:45], 0, v[158:159]
	global_load_lds_dwordx4 v[184:185], off
	s_add_i32 m0, s48, 0x2000
	s_nop 0
	global_load_lds_dwordx4 v[238:239], off
	s_barrier
	s_waitcnt lgkmcnt(0)
	s_setprio 1
	s_waitcnt lgkmcnt(0)
	v_mfma_f32_16x16x32_bf16 v[62:65], v[222:225], v[168:171], v[62:65]
	v_mfma_f32_16x16x32_bf16 v[58:61], v[230:233], v[168:171], v[58:61]
	v_mfma_f32_16x16x32_bf16 v[54:57], v[222:225], v[176:179], v[54:57]
	v_mfma_f32_16x16x32_bf16 v[50:53], v[230:233], v[176:179], v[50:53]
	v_mfma_f32_16x16x32_bf16 v[46:49], v[222:225], v[206:209], v[46:49]
	v_mfma_f32_16x16x32_bf16 v[42:45], v[230:233], v[206:209], v[42:45]
	v_mfma_f32_16x16x32_bf16 v[38:41], v[222:225], v[214:217], v[38:41]
	v_mfma_f32_16x16x32_bf16 v[34:37], v[230:233], v[214:217], v[34:37]
	v_mfma_f32_16x16x32_bf16 v[62:65], v[226:229], v[172:175], v[62:65]
	v_mfma_f32_16x16x32_bf16 v[58:61], v[234:237], v[172:175], v[58:61]
	v_mfma_f32_16x16x32_bf16 v[54:57], v[226:229], v[180:183], v[54:57]
	v_mfma_f32_16x16x32_bf16 v[50:53], v[234:237], v[180:183], v[50:53]
	v_mfma_f32_16x16x32_bf16 v[46:49], v[226:229], v[210:213], v[46:49]
	v_mfma_f32_16x16x32_bf16 v[42:45], v[234:237], v[210:213], v[42:45]
	v_mfma_f32_16x16x32_bf16 v[38:41], v[226:229], v[218:221], v[38:41]
	s_setprio 2
	s_mov_b32 m0, s27
	v_lshl_add_u64 v[240:241], s[68:69], 0, v[162:163]
	s_barrier
	v_mfma_f32_16x16x32_bf16 v[34:37], v[234:237], v[218:221], v[34:37]
	s_setprio 0
	ds_read_b128 v[168:171], v189 offset:16384
	ds_read_b128 v[172:175], v189 offset:17408
	ds_read_b128 v[176:179], v189 offset:18432
	ds_read_b128 v[180:183], v189 offset:19456
	ds_read_b128 v[206:209], v189 offset:20480
	ds_read_b128 v[210:213], v189 offset:21504
	ds_read_b128 v[214:217], v189 offset:22528
	ds_read_b128 v[218:221], v189 offset:23552
	global_load_lds_dwordx4 v[240:241], off
	v_lshl_add_u64 v[242:243], s[68:69], 0, v[160:161]
	s_mov_b32 m0, s28
	s_nop 0
	global_load_lds_dwordx4 v[242:243], off
	s_barrier
	s_waitcnt lgkmcnt(0)
	s_setprio 1
	s_waitcnt lgkmcnt(0)
	v_mfma_f32_16x16x32_bf16 v[110:113], v[90:93], v[168:171], v[110:113]
	v_mfma_f32_16x16x32_bf16 v[106:109], v[98:101], v[168:171], v[106:109]
	v_mfma_f32_16x16x32_bf16 v[86:89], v[90:93], v[176:179], v[86:89]
	v_mfma_f32_16x16x32_bf16 v[82:85], v[98:101], v[176:179], v[82:85]
	v_mfma_f32_16x16x32_bf16 v[78:81], v[90:93], v[206:209], v[78:81]
	v_mfma_f32_16x16x32_bf16 v[74:77], v[98:101], v[206:209], v[74:77]
	v_mfma_f32_16x16x32_bf16 v[70:73], v[90:93], v[214:217], v[70:73]
	v_mfma_f32_16x16x32_bf16 v[66:69], v[98:101], v[214:217], v[66:69]
	v_mfma_f32_16x16x32_bf16 v[110:113], v[94:97], v[172:175], v[110:113]
	v_mfma_f32_16x16x32_bf16 v[106:109], v[102:105], v[172:175], v[106:109]
	v_mfma_f32_16x16x32_bf16 v[86:89], v[94:97], v[180:183], v[86:89]
	v_mfma_f32_16x16x32_bf16 v[82:85], v[102:105], v[180:183], v[82:85]
	v_mfma_f32_16x16x32_bf16 v[78:81], v[94:97], v[210:213], v[78:81]
	v_mfma_f32_16x16x32_bf16 v[74:77], v[102:105], v[210:213], v[74:77]
	v_mfma_f32_16x16x32_bf16 v[70:73], v[94:97], v[218:221], v[70:73]
	s_setprio 2
	s_barrier
	v_mfma_f32_16x16x32_bf16 v[66:69], v[102:105], v[218:221], v[66:69]
	s_setprio 0
	s_add_u32 s48, s44, 0x80000
	s_addc_u32 s49, s45, 0
	s_add_i32 s50, s50, s22
	v_lshl_add_u64 v[90:91], s[48:49], 0, v[0:1]
	s_mov_b32 m0, s50
	s_nop 0
	global_load_lds_dwordx4 v[90:91], off
	v_lshl_add_u64 v[90:91], s[48:49], 0, v[158:159]
	s_add_i32 m0, s50, 0x2000
	s_nop 0
	global_load_lds_dwordx4 v[90:91], off
	s_waitcnt vmcnt(6)
	s_barrier
	s_setprio 1
	v_mfma_f32_16x16x32_bf16 v[30:33], v[222:225], v[168:171], v[30:33]
	v_mfma_f32_16x16x32_bf16 v[26:29], v[230:233], v[168:171], v[26:29]
	v_mfma_f32_16x16x32_bf16 v[22:25], v[222:225], v[176:179], v[22:25]
	v_mfma_f32_16x16x32_bf16 v[18:21], v[230:233], v[176:179], v[18:21]
	v_mfma_f32_16x16x32_bf16 v[14:17], v[222:225], v[206:209], v[14:17]
	v_mfma_f32_16x16x32_bf16 v[10:13], v[230:233], v[206:209], v[10:13]
	v_mfma_f32_16x16x32_bf16 v[6:9], v[222:225], v[214:217], v[6:9]
	v_mfma_f32_16x16x32_bf16 v[2:5], v[230:233], v[214:217], v[2:5]
	v_mfma_f32_16x16x32_bf16 v[30:33], v[226:229], v[172:175], v[30:33]
	v_mfma_f32_16x16x32_bf16 v[26:29], v[234:237], v[172:175], v[26:29]
	v_mfma_f32_16x16x32_bf16 v[22:25], v[226:229], v[180:183], v[22:25]
	v_mfma_f32_16x16x32_bf16 v[18:21], v[234:237], v[180:183], v[18:21]
	v_mfma_f32_16x16x32_bf16 v[14:17], v[226:229], v[210:213], v[14:17]
	v_mfma_f32_16x16x32_bf16 v[10:13], v[234:237], v[210:213], v[10:13]
	v_mfma_f32_16x16x32_bf16 v[6:9], v[226:229], v[218:221], v[6:9]
	s_setprio 2
	s_add_i32 s50, 0, 0x18000
	v_add_u32_e32 v102, s50, v187
	s_barrier
	v_mfma_f32_16x16x32_bf16 v[2:5], v[234:237], v[218:221], v[2:5]
	s_setprio 0
	ds_read_b128 v[90:93], v102
	ds_read_b128 v[94:97], v102 offset:1024
	ds_read_b128 v[98:101], v102 offset:2048
	ds_read_b128 v[102:105], v102 offset:3072
	s_add_u32 s48, s68, 0x80000
	s_addc_u32 s49, s69, 0
	s_mov_b32 m0, s36
	v_lshl_add_u64 v[222:223], s[48:49], 0, v[162:163]
	ds_read_b128 v[168:171], v189 offset:32768
	ds_read_b128 v[172:175], v189 offset:33792
	ds_read_b128 v[176:179], v189 offset:34816
	ds_read_b128 v[180:183], v189 offset:35840
	ds_read_b128 v[206:209], v189 offset:36864
	ds_read_b128 v[210:213], v189 offset:37888
	ds_read_b128 v[214:217], v189 offset:38912
	ds_read_b128 v[218:221], v189 offset:39936
	global_load_lds_dwordx4 v[222:223], off
	v_lshl_add_u64 v[222:223], s[48:49], 0, v[160:161]
	s_mov_b32 m0, s37
	s_nop 0
	global_load_lds_dwordx4 v[222:223], off
	s_waitcnt lgkmcnt(8)
	s_barrier
	s_waitcnt lgkmcnt(0)
	s_setprio 1
	s_waitcnt lgkmcnt(0)
	v_mfma_f32_16x16x32_bf16 v[142:145], v[90:93], v[168:171], v[142:145]
	v_mfma_f32_16x16x32_bf16 v[138:141], v[98:101], v[168:171], v[138:141]
	v_mfma_f32_16x16x32_bf16 v[134:137], v[90:93], v[176:179], v[134:137]
	v_mfma_f32_16x16x32_bf16 v[130:133], v[98:101], v[176:179], v[130:133]
	v_mfma_f32_16x16x32_bf16 v[126:129], v[90:93], v[206:209], v[126:129]
	v_mfma_f32_16x16x32_bf16 v[122:125], v[98:101], v[206:209], v[122:125]
	v_mfma_f32_16x16x32_bf16 v[118:121], v[90:93], v[214:217], v[118:121]
	v_mfma_f32_16x16x32_bf16 v[114:117], v[98:101], v[214:217], v[114:117]
	v_mfma_f32_16x16x32_bf16 v[142:145], v[94:97], v[172:175], v[142:145]
	v_mfma_f32_16x16x32_bf16 v[138:141], v[102:105], v[172:175], v[138:141]
	v_mfma_f32_16x16x32_bf16 v[134:137], v[94:97], v[180:183], v[134:137]
	v_mfma_f32_16x16x32_bf16 v[130:133], v[102:105], v[180:183], v[130:133]
	v_mfma_f32_16x16x32_bf16 v[126:129], v[94:97], v[210:213], v[126:129]
	v_mfma_f32_16x16x32_bf16 v[122:125], v[102:105], v[210:213], v[122:125]
	v_mfma_f32_16x16x32_bf16 v[118:121], v[94:97], v[218:221], v[118:121]
	s_setprio 2
	s_barrier
	v_mfma_f32_16x16x32_bf16 v[114:117], v[102:105], v[218:221], v[114:117]
	s_setprio 0
	s_add_i32 s48, 0, 0x1c000
	s_add_i32 s49, s50, s22
	v_add_u32_e32 v205, s48, v187
	v_lshl_add_u64 v[184:185], v[184:185], 0, s[62:63]
	s_mov_b32 m0, s49
	ds_read_b128 v[222:225], v205
	ds_read_b128 v[226:229], v205 offset:1024
	ds_read_b128 v[230:233], v205 offset:2048
	ds_read_b128 v[234:237], v205 offset:3072
	global_load_lds_dwordx4 v[184:185], off
	v_lshl_add_u64 v[184:185], v[238:239], 0, s[62:63]
	s_add_i32 m0, s49, 0x2000
	s_nop 0
	global_load_lds_dwordx4 v[184:185], off
	s_barrier
	s_waitcnt lgkmcnt(0)
	s_setprio 1
	s_waitcnt lgkmcnt(0)
	v_mfma_f32_16x16x32_bf16 v[62:65], v[222:225], v[168:171], v[62:65]
	v_mfma_f32_16x16x32_bf16 v[58:61], v[230:233], v[168:171], v[58:61]
	v_mfma_f32_16x16x32_bf16 v[54:57], v[222:225], v[176:179], v[54:57]
	v_mfma_f32_16x16x32_bf16 v[50:53], v[230:233], v[176:179], v[50:53]
	v_mfma_f32_16x16x32_bf16 v[46:49], v[222:225], v[206:209], v[46:49]
	v_mfma_f32_16x16x32_bf16 v[42:45], v[230:233], v[206:209], v[42:45]
	v_mfma_f32_16x16x32_bf16 v[38:41], v[222:225], v[214:217], v[38:41]
	v_mfma_f32_16x16x32_bf16 v[34:37], v[230:233], v[214:217], v[34:37]
	v_mfma_f32_16x16x32_bf16 v[62:65], v[226:229], v[172:175], v[62:65]
	v_mfma_f32_16x16x32_bf16 v[58:61], v[234:237], v[172:175], v[58:61]
	v_mfma_f32_16x16x32_bf16 v[54:57], v[226:229], v[180:183], v[54:57]
	v_mfma_f32_16x16x32_bf16 v[50:53], v[234:237], v[180:183], v[50:53]
	v_mfma_f32_16x16x32_bf16 v[46:49], v[226:229], v[210:213], v[46:49]
	v_mfma_f32_16x16x32_bf16 v[42:45], v[234:237], v[210:213], v[42:45]
	v_mfma_f32_16x16x32_bf16 v[38:41], v[226:229], v[218:221], v[38:41]
	s_setprio 2
	s_mov_b32 m0, s40
	v_lshl_add_u64 v[184:185], v[240:241], 0, s[62:63]
	s_barrier
	v_mfma_f32_16x16x32_bf16 v[34:37], v[234:237], v[218:221], v[34:37]
	s_setprio 0
	ds_read_b128 v[168:171], v189 offset:49152
	ds_read_b128 v[172:175], v189 offset:50176
	ds_read_b128 v[176:179], v189 offset:51200
	ds_read_b128 v[180:183], v189 offset:52224
	ds_read_b128 v[206:209], v189 offset:53248
	ds_read_b128 v[210:213], v189 offset:54272
	ds_read_b128 v[214:217], v189 offset:55296
	ds_read_b128 v[218:221], v189 offset:56320
	global_load_lds_dwordx4 v[184:185], off
	v_lshl_add_u64 v[184:185], v[242:243], 0, s[62:63]
	s_mov_b32 m0, s41
	s_nop 0
	global_load_lds_dwordx4 v[184:185], off
	s_barrier
	s_waitcnt lgkmcnt(0)
	s_setprio 1
	s_waitcnt lgkmcnt(0)
	v_mfma_f32_16x16x32_bf16 v[110:113], v[90:93], v[168:171], v[110:113]
	v_mfma_f32_16x16x32_bf16 v[106:109], v[98:101], v[168:171], v[106:109]
	v_mfma_f32_16x16x32_bf16 v[86:89], v[90:93], v[176:179], v[86:89]
	v_mfma_f32_16x16x32_bf16 v[82:85], v[98:101], v[176:179], v[82:85]
	v_mfma_f32_16x16x32_bf16 v[78:81], v[90:93], v[206:209], v[78:81]
	v_mfma_f32_16x16x32_bf16 v[74:77], v[98:101], v[206:209], v[74:77]
	v_mfma_f32_16x16x32_bf16 v[70:73], v[90:93], v[214:217], v[70:73]
	v_mfma_f32_16x16x32_bf16 v[66:69], v[98:101], v[214:217], v[66:69]
	v_mfma_f32_16x16x32_bf16 v[110:113], v[94:97], v[172:175], v[110:113]
	v_mfma_f32_16x16x32_bf16 v[106:109], v[102:105], v[172:175], v[106:109]
	v_mfma_f32_16x16x32_bf16 v[86:89], v[94:97], v[180:183], v[86:89]
	v_mfma_f32_16x16x32_bf16 v[82:85], v[102:105], v[180:183], v[82:85]
	v_mfma_f32_16x16x32_bf16 v[78:81], v[94:97], v[210:213], v[78:81]
	v_mfma_f32_16x16x32_bf16 v[74:77], v[102:105], v[210:213], v[74:77]
	v_mfma_f32_16x16x32_bf16 v[70:73], v[94:97], v[218:221], v[70:73]
	s_setprio 2
	s_barrier
	v_mfma_f32_16x16x32_bf16 v[66:69], v[102:105], v[218:221], v[66:69]
	s_setprio 0
	s_add_u32 s44, s44, 0x80080
	s_addc_u32 s45, s45, 0
	s_add_i32 s48, s48, s22
	v_lshl_add_u64 v[90:91], s[44:45], 0, v[0:1]
	s_mov_b32 m0, s48
	s_nop 0
	global_load_lds_dwordx4 v[90:91], off
	v_lshl_add_u64 v[90:91], s[44:45], 0, v[158:159]
	s_add_i32 m0, s48, 0x2000
	s_nop 0
	global_load_lds_dwordx4 v[90:91], off
	s_waitcnt vmcnt(6)
	s_barrier
	s_setprio 1
	v_mfma_f32_16x16x32_bf16 v[30:33], v[222:225], v[168:171], v[30:33]
	v_mfma_f32_16x16x32_bf16 v[26:29], v[230:233], v[168:171], v[26:29]
	v_mfma_f32_16x16x32_bf16 v[22:25], v[222:225], v[176:179], v[22:25]
	v_mfma_f32_16x16x32_bf16 v[18:21], v[230:233], v[176:179], v[18:21]
	v_mfma_f32_16x16x32_bf16 v[14:17], v[222:225], v[206:209], v[14:17]
	v_mfma_f32_16x16x32_bf16 v[10:13], v[230:233], v[206:209], v[10:13]
	v_mfma_f32_16x16x32_bf16 v[6:9], v[222:225], v[214:217], v[6:9]
	v_mfma_f32_16x16x32_bf16 v[2:5], v[230:233], v[214:217], v[2:5]
	v_mfma_f32_16x16x32_bf16 v[30:33], v[226:229], v[172:175], v[30:33]
	v_mfma_f32_16x16x32_bf16 v[26:29], v[234:237], v[172:175], v[26:29]
	v_mfma_f32_16x16x32_bf16 v[22:25], v[226:229], v[180:183], v[22:25]
	v_mfma_f32_16x16x32_bf16 v[18:21], v[234:237], v[180:183], v[18:21]
	v_mfma_f32_16x16x32_bf16 v[14:17], v[226:229], v[210:213], v[14:17]
	v_mfma_f32_16x16x32_bf16 v[10:13], v[234:237], v[210:213], v[10:13]
	v_mfma_f32_16x16x32_bf16 v[6:9], v[226:229], v[218:221], v[6:9]
	s_setprio 2
	s_add_i32 s47, s47, 2
	s_add_u32 s64, s64, 0x100
	s_addc_u32 s65, s65, 0
	s_add_u32 s18, s18, 0x100
	s_addc_u32 s19, s19, 0
	s_cmp_gt_u32 s47, 29
	s_barrier
	v_mfma_f32_16x16x32_bf16 v[2:5], v[234:237], v[218:221], v[2:5]
	s_setprio 0
	s_cbranch_scc0 .LBB0_1256
	s_lshl_b32 s4, s46, 8
	s_and_b32 s4, s4, 0x3f00
	v_add_u32_e32 v178, s4, v186
	s_ashr_i32 s4, s43, 31
	s_lshr_b32 s4, s4, 29
	s_add_i32 s4, s43, s4
	s_and_b32 s4, s4, 0xfffff8
	s_sub_i32 s4, s43, s4
	v_lshl_or_b32 v172, s4, 8, v188
	v_ashrrev_i32_e32 v173, 31, v172
	v_ashrrev_i32_e32 v179, 31, v178
	v_lshlrev_b32_e32 v170, 12, v178
	v_lshl_add_u32 v170, v172, 1, v170
	v_lshlrev_b32_e32 v171, 3, v178
	v_lshlrev_b32_e32 v174, 2, v172
	global_load_dwordx4 v[98:101], v174, s[12:13]
	global_load_dwordx4 v[90:93], v174, s[12:13] offset:16
	global_load_dwordx4 v[102:105], v174, s[14:15]
	global_load_dwordx4 v[94:97], v174, s[14:15] offset:16
	s_add_u32 s48, s82, 0x0
	s_addc_u32 s49, s83, 0
	global_load_dwordx4 v[220:223], v170, s[48:49]
	s_add_u32 s50, s10, 0x0
	s_addc_u32 s51, s11, 0
	global_load_dwordx2 v[176:177], v171, s[50:51]
	s_add_u32 s48, s82, 0x10000
	s_addc_u32 s49, s83, 0
	global_load_dwordx4 v[224:227], v170, s[48:49]
	s_add_u32 s50, s10, 0x80
	s_addc_u32 s51, s11, 0
	global_load_dwordx2 v[180:181], v171, s[50:51]
	s_add_u32 s48, s82, 0x20000
	s_addc_u32 s49, s83, 0
	global_load_dwordx4 v[228:231], v170, s[48:49]
	s_add_u32 s50, s10, 0x100
	s_addc_u32 s51, s11, 0
	global_load_dwordx2 v[182:183], v171, s[50:51]
	s_add_u32 s48, s82, 0x30000
	s_addc_u32 s49, s83, 0
	global_load_dwordx4 v[232:235], v170, s[48:49]
	s_add_u32 s50, s10, 0x180
	s_addc_u32 s51, s11, 0
	global_load_dwordx2 v[184:185], v171, s[50:51]
	s_add_u32 s48, s82, 0x80000
	s_addc_u32 s49, s83, 0
	global_load_dwordx4 v[236:239], v170, s[48:49]
	s_add_u32 s50, s10, 0x400
	s_addc_u32 s51, s11, 0
	global_load_dwordx2 v[168:169], v171, s[50:51]
	s_add_u32 s48, s82, 0x90000
	s_addc_u32 s49, s83, 0
	global_load_dwordx4 v[240:243], v170, s[48:49]
	s_add_u32 s50, s10, 0x480
	s_addc_u32 s51, s11, 0
	global_load_dwordx2 v[252:253], v171, s[50:51]
	s_add_u32 s48, s82, 0xa0000
	s_addc_u32 s49, s83, 0
	global_load_dwordx4 v[244:247], v170, s[48:49]
	s_add_u32 s50, s10, 0x500
	s_addc_u32 s51, s11, 0
	global_load_dwordx2 v[214:215], v171, s[50:51]
	s_add_u32 s48, s82, 0xb0000
	s_addc_u32 s49, s83, 0
	global_load_dwordx4 v[248:251], v170, s[48:49]
	s_add_u32 s50, s10, 0x580
	s_addc_u32 s51, s11, 0
	global_load_dwordx2 v[216:217], v171, s[50:51]
	s_waitcnt vmcnt(14)
	v_lshlrev_b32_e32 v206, 16, v220
	v_and_b32_e32 v207, 0xffff0000, v220
	v_lshlrev_b32_e32 v208, 16, v221
	v_and_b32_e32 v209, 0xffff0000, v221
	v_lshlrev_b32_e32 v210, 16, v222
	v_and_b32_e32 v211, 0xffff0000, v222
	v_lshlrev_b32_e32 v212, 16, v223
	v_and_b32_e32 v213, 0xffff0000, v223
	v_sub_f32_e32 v206, v206, v176
	v_sub_f32_e32 v207, v207, v176
	v_sub_f32_e32 v208, v208, v176
	v_sub_f32_e32 v209, v209, v176
	v_sub_f32_e32 v210, v210, v176
	v_sub_f32_e32 v211, v211, v176
	v_sub_f32_e32 v212, v212, v176
	v_sub_f32_e32 v213, v213, v176
	v_pk_mul_f32 v[206:207], v[176:177], v[206:207] op_sel:[1,0]
	v_pk_mul_f32 v[208:209], v[176:177], v[208:209] op_sel:[1,0]
	v_pk_mul_f32 v[210:211], v[176:177], v[210:211] op_sel:[1,0]
	v_pk_mul_f32 v[212:213], v[176:177], v[212:213] op_sel:[1,0]
	v_pk_fma_f32 v[206:207], v[98:99], v[206:207], v[102:103]
	v_pk_fma_f32 v[208:209], v[100:101], v[208:209], v[104:105]
	v_pk_fma_f32 v[210:211], v[90:91], v[210:211], v[94:95]
	v_pk_fma_f32 v[212:213], v[92:93], v[212:213], v[96:97]
	v_pk_fma_f32 v[206:207], v[206:207], s[66:67], v[142:143] op_sel_hi:[1,0,1]
	v_pk_fma_f32 v[208:209], v[208:209], s[66:67], v[144:145] op_sel_hi:[1,0,1]
	v_pk_fma_f32 v[210:211], v[210:211], s[66:67], v[138:139] op_sel_hi:[1,0,1]
	v_pk_fma_f32 v[212:213], v[212:213], s[66:67], v[140:141] op_sel_hi:[1,0,1]
	v_cvt_pk_bf16_f32 v220, v206, v207
	v_cvt_pk_bf16_f32 v221, v208, v209
	v_cvt_pk_bf16_f32 v222, v210, v211
	v_cvt_pk_bf16_f32 v223, v212, v213
	s_add_u32 s48, s82, 0x0
	s_addc_u32 s49, s83, 0
	global_store_dwordx4 v170, v[220:223], s[48:49]
	s_waitcnt vmcnt(13)
	v_lshlrev_b32_e32 v206, 16, v224
	v_and_b32_e32 v207, 0xffff0000, v224
	v_lshlrev_b32_e32 v208, 16, v225
	v_and_b32_e32 v209, 0xffff0000, v225
	v_lshlrev_b32_e32 v210, 16, v226
	v_and_b32_e32 v211, 0xffff0000, v226
	v_lshlrev_b32_e32 v212, 16, v227
	v_and_b32_e32 v213, 0xffff0000, v227
	v_sub_f32_e32 v206, v206, v180
	v_sub_f32_e32 v207, v207, v180
	v_sub_f32_e32 v208, v208, v180
	v_sub_f32_e32 v209, v209, v180
	v_sub_f32_e32 v210, v210, v180
	v_sub_f32_e32 v211, v211, v180
	v_sub_f32_e32 v212, v212, v180
	v_sub_f32_e32 v213, v213, v180
	v_pk_mul_f32 v[206:207], v[180:181], v[206:207] op_sel:[1,0]
	v_pk_mul_f32 v[208:209], v[180:181], v[208:209] op_sel:[1,0]
	v_pk_mul_f32 v[210:211], v[180:181], v[210:211] op_sel:[1,0]
	v_pk_mul_f32 v[212:213], v[180:181], v[212:213] op_sel:[1,0]
	v_pk_fma_f32 v[206:207], v[98:99], v[206:207], v[102:103]
	v_pk_fma_f32 v[208:209], v[100:101], v[208:209], v[104:105]
	v_pk_fma_f32 v[210:211], v[90:91], v[210:211], v[94:95]
	v_pk_fma_f32 v[212:213], v[92:93], v[212:213], v[96:97]
	v_pk_fma_f32 v[206:207], v[206:207], s[66:67], v[134:135] op_sel_hi:[1,0,1]
	v_pk_fma_f32 v[208:209], v[208:209], s[66:67], v[136:137] op_sel_hi:[1,0,1]
	v_pk_fma_f32 v[210:211], v[210:211], s[66:67], v[130:131] op_sel_hi:[1,0,1]
	v_pk_fma_f32 v[212:213], v[212:213], s[66:67], v[132:133] op_sel_hi:[1,0,1]
	v_cvt_pk_bf16_f32 v224, v206, v207
	v_cvt_pk_bf16_f32 v225, v208, v209
	v_cvt_pk_bf16_f32 v226, v210, v211
	v_cvt_pk_bf16_f32 v227, v212, v213
	s_add_u32 s48, s82, 0x10000
	s_addc_u32 s49, s83, 0
	global_store_dwordx4 v170, v[224:227], s[48:49]
	s_waitcnt vmcnt(12)
	v_lshlrev_b32_e32 v206, 16, v228
	v_and_b32_e32 v207, 0xffff0000, v228
	v_lshlrev_b32_e32 v208, 16, v229
	v_and_b32_e32 v209, 0xffff0000, v229
	v_lshlrev_b32_e32 v210, 16, v230
	v_and_b32_e32 v211, 0xffff0000, v230
	v_lshlrev_b32_e32 v212, 16, v231
	v_and_b32_e32 v213, 0xffff0000, v231
	v_sub_f32_e32 v206, v206, v182
	v_sub_f32_e32 v207, v207, v182
	v_sub_f32_e32 v208, v208, v182
	v_sub_f32_e32 v209, v209, v182
	v_sub_f32_e32 v210, v210, v182
	v_sub_f32_e32 v211, v211, v182
	v_sub_f32_e32 v212, v212, v182
	v_sub_f32_e32 v213, v213, v182
	v_pk_mul_f32 v[206:207], v[182:183], v[206:207] op_sel:[1,0]
	v_pk_mul_f32 v[208:209], v[182:183], v[208:209] op_sel:[1,0]
	v_pk_mul_f32 v[210:211], v[182:183], v[210:211] op_sel:[1,0]
	v_pk_mul_f32 v[212:213], v[182:183], v[212:213] op_sel:[1,0]
	v_pk_fma_f32 v[206:207], v[98:99], v[206:207], v[102:103]
	v_pk_fma_f32 v[208:209], v[100:101], v[208:209], v[104:105]
	v_pk_fma_f32 v[210:211], v[90:91], v[210:211], v[94:95]
	v_pk_fma_f32 v[212:213], v[92:93], v[212:213], v[96:97]
	v_pk_fma_f32 v[206:207], v[206:207], s[66:67], v[126:127] op_sel_hi:[1,0,1]
	v_pk_fma_f32 v[208:209], v[208:209], s[66:67], v[128:129] op_sel_hi:[1,0,1]
	v_pk_fma_f32 v[210:211], v[210:211], s[66:67], v[122:123] op_sel_hi:[1,0,1]
	v_pk_fma_f32 v[212:213], v[212:213], s[66:67], v[124:125] op_sel_hi:[1,0,1]
	v_cvt_pk_bf16_f32 v228, v206, v207
	v_cvt_pk_bf16_f32 v229, v208, v209
	v_cvt_pk_bf16_f32 v230, v210, v211
	v_cvt_pk_bf16_f32 v231, v212, v213
	s_add_u32 s48, s82, 0x20000
	s_addc_u32 s49, s83, 0
	global_store_dwordx4 v170, v[228:231], s[48:49]
	s_waitcnt vmcnt(11)
	v_lshlrev_b32_e32 v206, 16, v232
	v_and_b32_e32 v207, 0xffff0000, v232
	v_lshlrev_b32_e32 v208, 16, v233
	v_and_b32_e32 v209, 0xffff0000, v233
	v_lshlrev_b32_e32 v210, 16, v234
	v_and_b32_e32 v211, 0xffff0000, v234
	v_lshlrev_b32_e32 v212, 16, v235
	v_and_b32_e32 v213, 0xffff0000, v235
	v_sub_f32_e32 v206, v206, v184
	v_sub_f32_e32 v207, v207, v184
	v_sub_f32_e32 v208, v208, v184
	v_sub_f32_e32 v209, v209, v184
	v_sub_f32_e32 v210, v210, v184
	v_sub_f32_e32 v211, v211, v184
	v_sub_f32_e32 v212, v212, v184
	v_sub_f32_e32 v213, v213, v184
	v_pk_mul_f32 v[206:207], v[184:185], v[206:207] op_sel:[1,0]
	v_pk_mul_f32 v[208:209], v[184:185], v[208:209] op_sel:[1,0]
	v_pk_mul_f32 v[210:211], v[184:185], v[210:211] op_sel:[1,0]
	v_pk_mul_f32 v[212:213], v[184:185], v[212:213] op_sel:[1,0]
	v_pk_fma_f32 v[206:207], v[98:99], v[206:207], v[102:103]
	v_pk_fma_f32 v[208:209], v[100:101], v[208:209], v[104:105]
	v_pk_fma_f32 v[210:211], v[90:91], v[210:211], v[94:95]
	v_pk_fma_f32 v[212:213], v[92:93], v[212:213], v[96:97]
	v_pk_fma_f32 v[206:207], v[206:207], s[66:67], v[118:119] op_sel_hi:[1,0,1]
	v_pk_fma_f32 v[208:209], v[208:209], s[66:67], v[120:121] op_sel_hi:[1,0,1]
	v_pk_fma_f32 v[210:211], v[210:211], s[66:67], v[114:115] op_sel_hi:[1,0,1]
	v_pk_fma_f32 v[212:213], v[212:213], s[66:67], v[116:117] op_sel_hi:[1,0,1]
	v_cvt_pk_bf16_f32 v232, v206, v207
	v_cvt_pk_bf16_f32 v233, v208, v209
	v_cvt_pk_bf16_f32 v234, v210, v211
	v_cvt_pk_bf16_f32 v235, v212, v213
	s_add_u32 s48, s82, 0x30000
	s_addc_u32 s49, s83, 0
	global_store_dwordx4 v170, v[232:235], s[48:49]
	s_waitcnt vmcnt(10)
	v_lshlrev_b32_e32 v206, 16, v236
	v_and_b32_e32 v207, 0xffff0000, v236
	v_lshlrev_b32_e32 v208, 16, v237
	v_and_b32_e32 v209, 0xffff0000, v237
	v_lshlrev_b32_e32 v210, 16, v238
	v_and_b32_e32 v211, 0xffff0000, v238
	v_lshlrev_b32_e32 v212, 16, v239
	v_and_b32_e32 v213, 0xffff0000, v239
	v_sub_f32_e32 v206, v206, v168
	v_sub_f32_e32 v207, v207, v168
	v_sub_f32_e32 v208, v208, v168
	v_sub_f32_e32 v209, v209, v168
	v_sub_f32_e32 v210, v210, v168
	v_sub_f32_e32 v211, v211, v168
	v_sub_f32_e32 v212, v212, v168
	v_sub_f32_e32 v213, v213, v168
	v_pk_mul_f32 v[206:207], v[168:169], v[206:207] op_sel:[1,0]
	v_pk_mul_f32 v[208:209], v[168:169], v[208:209] op_sel:[1,0]
	v_pk_mul_f32 v[210:211], v[168:169], v[210:211] op_sel:[1,0]
	v_pk_mul_f32 v[212:213], v[168:169], v[212:213] op_sel:[1,0]
	v_pk_fma_f32 v[206:207], v[98:99], v[206:207], v[102:103]
	v_pk_fma_f32 v[208:209], v[100:101], v[208:209], v[104:105]
	v_pk_fma_f32 v[210:211], v[90:91], v[210:211], v[94:95]
	v_pk_fma_f32 v[212:213], v[92:93], v[212:213], v[96:97]
	v_pk_fma_f32 v[206:207], v[206:207], s[66:67], v[110:111] op_sel_hi:[1,0,1]
	v_pk_fma_f32 v[208:209], v[208:209], s[66:67], v[112:113] op_sel_hi:[1,0,1]
	v_pk_fma_f32 v[210:211], v[210:211], s[66:67], v[106:107] op_sel_hi:[1,0,1]
	v_pk_fma_f32 v[212:213], v[212:213], s[66:67], v[108:109] op_sel_hi:[1,0,1]
	v_cvt_pk_bf16_f32 v236, v206, v207
	v_cvt_pk_bf16_f32 v237, v208, v209
	v_cvt_pk_bf16_f32 v238, v210, v211
	v_cvt_pk_bf16_f32 v239, v212, v213
	s_add_u32 s48, s82, 0x80000
	s_addc_u32 s49, s83, 0
	global_store_dwordx4 v170, v[236:239], s[48:49]
	s_waitcnt vmcnt(9)
	v_lshlrev_b32_e32 v206, 16, v240
	v_and_b32_e32 v207, 0xffff0000, v240
	v_lshlrev_b32_e32 v208, 16, v241
	v_and_b32_e32 v209, 0xffff0000, v241
	v_lshlrev_b32_e32 v210, 16, v242
	v_and_b32_e32 v211, 0xffff0000, v242
	v_lshlrev_b32_e32 v212, 16, v243
	v_and_b32_e32 v213, 0xffff0000, v243
	v_sub_f32_e32 v206, v206, v252
	v_sub_f32_e32 v207, v207, v252
	v_sub_f32_e32 v208, v208, v252
	v_sub_f32_e32 v209, v209, v252
	v_sub_f32_e32 v210, v210, v252
	v_sub_f32_e32 v211, v211, v252
	v_sub_f32_e32 v212, v212, v252
	v_sub_f32_e32 v213, v213, v252
	v_pk_mul_f32 v[206:207], v[252:253], v[206:207] op_sel:[1,0]
	v_pk_mul_f32 v[208:209], v[252:253], v[208:209] op_sel:[1,0]
	v_pk_mul_f32 v[210:211], v[252:253], v[210:211] op_sel:[1,0]
	v_pk_mul_f32 v[212:213], v[252:253], v[212:213] op_sel:[1,0]
	v_pk_fma_f32 v[206:207], v[98:99], v[206:207], v[102:103]
	v_pk_fma_f32 v[208:209], v[100:101], v[208:209], v[104:105]
	v_pk_fma_f32 v[210:211], v[90:91], v[210:211], v[94:95]
	v_pk_fma_f32 v[212:213], v[92:93], v[212:213], v[96:97]
	v_pk_fma_f32 v[206:207], v[206:207], s[66:67], v[86:87] op_sel_hi:[1,0,1]
	v_pk_fma_f32 v[208:209], v[208:209], s[66:67], v[88:89] op_sel_hi:[1,0,1]
	v_pk_fma_f32 v[210:211], v[210:211], s[66:67], v[82:83] op_sel_hi:[1,0,1]
	v_pk_fma_f32 v[212:213], v[212:213], s[66:67], v[84:85] op_sel_hi:[1,0,1]
	v_cvt_pk_bf16_f32 v240, v206, v207
	v_cvt_pk_bf16_f32 v241, v208, v209
	v_cvt_pk_bf16_f32 v242, v210, v211
	v_cvt_pk_bf16_f32 v243, v212, v213
	s_add_u32 s48, s82, 0x90000
	s_addc_u32 s49, s83, 0
	global_store_dwordx4 v170, v[240:243], s[48:49]
	s_waitcnt vmcnt(8)
	v_lshlrev_b32_e32 v206, 16, v244
	v_and_b32_e32 v207, 0xffff0000, v244
	v_lshlrev_b32_e32 v208, 16, v245
	v_and_b32_e32 v209, 0xffff0000, v245
	v_lshlrev_b32_e32 v210, 16, v246
	v_and_b32_e32 v211, 0xffff0000, v246
	v_lshlrev_b32_e32 v212, 16, v247
	v_and_b32_e32 v213, 0xffff0000, v247
	v_sub_f32_e32 v206, v206, v214
	v_sub_f32_e32 v207, v207, v214
	v_sub_f32_e32 v208, v208, v214
	v_sub_f32_e32 v209, v209, v214
	v_sub_f32_e32 v210, v210, v214
	v_sub_f32_e32 v211, v211, v214
	v_sub_f32_e32 v212, v212, v214
	v_sub_f32_e32 v213, v213, v214
	v_pk_mul_f32 v[206:207], v[214:215], v[206:207] op_sel:[1,0]
	v_pk_mul_f32 v[208:209], v[214:215], v[208:209] op_sel:[1,0]
	v_pk_mul_f32 v[210:211], v[214:215], v[210:211] op_sel:[1,0]
	v_pk_mul_f32 v[212:213], v[214:215], v[212:213] op_sel:[1,0]
	v_pk_fma_f32 v[206:207], v[98:99], v[206:207], v[102:103]
	v_pk_fma_f32 v[208:209], v[100:101], v[208:209], v[104:105]
	v_pk_fma_f32 v[210:211], v[90:91], v[210:211], v[94:95]
	v_pk_fma_f32 v[212:213], v[92:93], v[212:213], v[96:97]
	v_pk_fma_f32 v[206:207], v[206:207], s[66:67], v[78:79] op_sel_hi:[1,0,1]
	v_pk_fma_f32 v[208:209], v[208:209], s[66:67], v[80:81] op_sel_hi:[1,0,1]
	v_pk_fma_f32 v[210:211], v[210:211], s[66:67], v[74:75] op_sel_hi:[1,0,1]
	v_pk_fma_f32 v[212:213], v[212:213], s[66:67], v[76:77] op_sel_hi:[1,0,1]
	v_cvt_pk_bf16_f32 v244, v206, v207
	v_cvt_pk_bf16_f32 v245, v208, v209
	v_cvt_pk_bf16_f32 v246, v210, v211
	v_cvt_pk_bf16_f32 v247, v212, v213
	s_add_u32 s48, s82, 0xa0000
	s_addc_u32 s49, s83, 0
	global_store_dwordx4 v170, v[244:247], s[48:49]
	s_waitcnt vmcnt(7)
	v_lshlrev_b32_e32 v206, 16, v248
	v_and_b32_e32 v207, 0xffff0000, v248
	v_lshlrev_b32_e32 v208, 16, v249
	v_and_b32_e32 v209, 0xffff0000, v249
	v_lshlrev_b32_e32 v210, 16, v250
	v_and_b32_e32 v211, 0xffff0000, v250
	v_lshlrev_b32_e32 v212, 16, v251
	v_and_b32_e32 v213, 0xffff0000, v251
	v_sub_f32_e32 v206, v206, v216
	v_sub_f32_e32 v207, v207, v216
	v_sub_f32_e32 v208, v208, v216
	v_sub_f32_e32 v209, v209, v216
	v_sub_f32_e32 v210, v210, v216
	v_sub_f32_e32 v211, v211, v216
	v_sub_f32_e32 v212, v212, v216
	v_sub_f32_e32 v213, v213, v216
	v_pk_mul_f32 v[206:207], v[216:217], v[206:207] op_sel:[1,0]
	v_pk_mul_f32 v[208:209], v[216:217], v[208:209] op_sel:[1,0]
	v_pk_mul_f32 v[210:211], v[216:217], v[210:211] op_sel:[1,0]
	v_pk_mul_f32 v[212:213], v[216:217], v[212:213] op_sel:[1,0]
	v_pk_fma_f32 v[206:207], v[98:99], v[206:207], v[102:103]
	v_pk_fma_f32 v[208:209], v[100:101], v[208:209], v[104:105]
	v_pk_fma_f32 v[210:211], v[90:91], v[210:211], v[94:95]
	v_pk_fma_f32 v[212:213], v[92:93], v[212:213], v[96:97]
	v_pk_fma_f32 v[206:207], v[206:207], s[66:67], v[70:71] op_sel_hi:[1,0,1]
	v_pk_fma_f32 v[208:209], v[208:209], s[66:67], v[72:73] op_sel_hi:[1,0,1]
	v_pk_fma_f32 v[210:211], v[210:211], s[66:67], v[66:67] op_sel_hi:[1,0,1]
	v_pk_fma_f32 v[212:213], v[212:213], s[66:67], v[68:69] op_sel_hi:[1,0,1]
	v_cvt_pk_bf16_f32 v248, v206, v207
	v_cvt_pk_bf16_f32 v249, v208, v209
	v_cvt_pk_bf16_f32 v250, v210, v211
	v_cvt_pk_bf16_f32 v251, v212, v213
	s_add_u32 s48, s82, 0xb0000
	s_addc_u32 s49, s83, 0
	global_store_dwordx4 v170, v[248:251], s[48:49]
	global_load_dwordx4 v[98:101], v174, s[12:13] offset:512
	global_load_dwordx4 v[90:93], v174, s[12:13] offset:528
	global_load_dwordx4 v[102:105], v174, s[14:15] offset:512
	global_load_dwordx4 v[94:97], v174, s[14:15] offset:528
	s_add_u32 s48, s82, 0x100
	s_addc_u32 s49, s83, 0
	global_load_dwordx4 v[220:223], v170, s[48:49]
	s_add_u32 s50, s10, 0x0
	s_addc_u32 s51, s11, 0
	global_load_dwordx2 v[176:177], v171, s[50:51]
	s_add_u32 s48, s82, 0x10100
	s_addc_u32 s49, s83, 0
	global_load_dwordx4 v[224:227], v170, s[48:49]
	s_add_u32 s50, s10, 0x80
	s_addc_u32 s51, s11, 0
	global_load_dwordx2 v[180:181], v171, s[50:51]
	s_add_u32 s48, s82, 0x20100
	s_addc_u32 s49, s83, 0
	global_load_dwordx4 v[228:231], v170, s[48:49]
	s_add_u32 s50, s10, 0x100
	s_addc_u32 s51, s11, 0
	global_load_dwordx2 v[182:183], v171, s[50:51]
	s_add_u32 s48, s82, 0x30100
	s_addc_u32 s49, s83, 0
	global_load_dwordx4 v[232:235], v170, s[48:49]
	s_add_u32 s50, s10, 0x180
	s_addc_u32 s51, s11, 0
	global_load_dwordx2 v[184:185], v171, s[50:51]
	s_add_u32 s48, s82, 0x80100
	s_addc_u32 s49, s83, 0
	global_load_dwordx4 v[236:239], v170, s[48:49]
	s_add_u32 s50, s10, 0x400
	s_addc_u32 s51, s11, 0
	global_load_dwordx2 v[168:169], v171, s[50:51]
	s_add_u32 s48, s82, 0x90100
	s_addc_u32 s49, s83, 0
	global_load_dwordx4 v[240:243], v170, s[48:49]
	s_add_u32 s50, s10, 0x480
	s_addc_u32 s51, s11, 0
	global_load_dwordx2 v[252:253], v171, s[50:51]
	s_add_u32 s48, s82, 0xa0100
	s_addc_u32 s49, s83, 0
	global_load_dwordx4 v[244:247], v170, s[48:49]
	s_add_u32 s50, s10, 0x500
	s_addc_u32 s51, s11, 0
	global_load_dwordx2 v[214:215], v171, s[50:51]
	s_add_u32 s48, s82, 0xb0100
	s_addc_u32 s49, s83, 0
	global_load_dwordx4 v[248:251], v170, s[48:49]
	s_add_u32 s50, s10, 0x580
	s_addc_u32 s51, s11, 0
	global_load_dwordx2 v[216:217], v171, s[50:51]
	s_waitcnt vmcnt(14)
	v_lshlrev_b32_e32 v206, 16, v220
	v_and_b32_e32 v207, 0xffff0000, v220
	v_lshlrev_b32_e32 v208, 16, v221
	v_and_b32_e32 v209, 0xffff0000, v221
	v_lshlrev_b32_e32 v210, 16, v222
	v_and_b32_e32 v211, 0xffff0000, v222
	v_lshlrev_b32_e32 v212, 16, v223
	v_and_b32_e32 v213, 0xffff0000, v223
	v_sub_f32_e32 v206, v206, v176
	v_sub_f32_e32 v207, v207, v176
	v_sub_f32_e32 v208, v208, v176
	v_sub_f32_e32 v209, v209, v176
	v_sub_f32_e32 v210, v210, v176
	v_sub_f32_e32 v211, v211, v176
	v_sub_f32_e32 v212, v212, v176
	v_sub_f32_e32 v213, v213, v176
	v_pk_mul_f32 v[206:207], v[176:177], v[206:207] op_sel:[1,0]
	v_pk_mul_f32 v[208:209], v[176:177], v[208:209] op_sel:[1,0]
	v_pk_mul_f32 v[210:211], v[176:177], v[210:211] op_sel:[1,0]
	v_pk_mul_f32 v[212:213], v[176:177], v[212:213] op_sel:[1,0]
	v_pk_fma_f32 v[206:207], v[98:99], v[206:207], v[102:103]
	v_pk_fma_f32 v[208:209], v[100:101], v[208:209], v[104:105]
	v_pk_fma_f32 v[210:211], v[90:91], v[210:211], v[94:95]
	v_pk_fma_f32 v[212:213], v[92:93], v[212:213], v[96:97]
	v_pk_fma_f32 v[206:207], v[206:207], s[66:67], v[62:63] op_sel_hi:[1,0,1]
	v_pk_fma_f32 v[208:209], v[208:209], s[66:67], v[64:65] op_sel_hi:[1,0,1]
	v_pk_fma_f32 v[210:211], v[210:211], s[66:67], v[58:59] op_sel_hi:[1,0,1]
	v_pk_fma_f32 v[212:213], v[212:213], s[66:67], v[60:61] op_sel_hi:[1,0,1]
	v_cvt_pk_bf16_f32 v220, v206, v207
	v_cvt_pk_bf16_f32 v221, v208, v209
	v_cvt_pk_bf16_f32 v222, v210, v211
	v_cvt_pk_bf16_f32 v223, v212, v213
	s_add_u32 s48, s82, 0x100
	s_addc_u32 s49, s83, 0
	global_store_dwordx4 v170, v[220:223], s[48:49]
	s_waitcnt vmcnt(13)
	v_lshlrev_b32_e32 v206, 16, v224
	v_and_b32_e32 v207, 0xffff0000, v224
	v_lshlrev_b32_e32 v208, 16, v225
	v_and_b32_e32 v209, 0xffff0000, v225
	v_lshlrev_b32_e32 v210, 16, v226
	v_and_b32_e32 v211, 0xffff0000, v226
	v_lshlrev_b32_e32 v212, 16, v227
	v_and_b32_e32 v213, 0xffff0000, v227
	v_sub_f32_e32 v206, v206, v180
	v_sub_f32_e32 v207, v207, v180
	v_sub_f32_e32 v208, v208, v180
	v_sub_f32_e32 v209, v209, v180
	v_sub_f32_e32 v210, v210, v180
	v_sub_f32_e32 v211, v211, v180
	v_sub_f32_e32 v212, v212, v180
	v_sub_f32_e32 v213, v213, v180
	v_pk_mul_f32 v[206:207], v[180:181], v[206:207] op_sel:[1,0]
	v_pk_mul_f32 v[208:209], v[180:181], v[208:209] op_sel:[1,0]
	v_pk_mul_f32 v[210:211], v[180:181], v[210:211] op_sel:[1,0]
	v_pk_mul_f32 v[212:213], v[180:181], v[212:213] op_sel:[1,0]
	v_pk_fma_f32 v[206:207], v[98:99], v[206:207], v[102:103]
	v_pk_fma_f32 v[208:209], v[100:101], v[208:209], v[104:105]
	v_pk_fma_f32 v[210:211], v[90:91], v[210:211], v[94:95]
	v_pk_fma_f32 v[212:213], v[92:93], v[212:213], v[96:97]
	v_pk_fma_f32 v[206:207], v[206:207], s[66:67], v[54:55] op_sel_hi:[1,0,1]
	v_pk_fma_f32 v[208:209], v[208:209], s[66:67], v[56:57] op_sel_hi:[1,0,1]
	v_pk_fma_f32 v[210:211], v[210:211], s[66:67], v[50:51] op_sel_hi:[1,0,1]
	v_pk_fma_f32 v[212:213], v[212:213], s[66:67], v[52:53] op_sel_hi:[1,0,1]
	v_cvt_pk_bf16_f32 v224, v206, v207
	v_cvt_pk_bf16_f32 v225, v208, v209
	v_cvt_pk_bf16_f32 v226, v210, v211
	v_cvt_pk_bf16_f32 v227, v212, v213
	s_add_u32 s48, s82, 0x10100
	s_addc_u32 s49, s83, 0
	global_store_dwordx4 v170, v[224:227], s[48:49]
	s_waitcnt vmcnt(12)
	v_lshlrev_b32_e32 v206, 16, v228
	v_and_b32_e32 v207, 0xffff0000, v228
	v_lshlrev_b32_e32 v208, 16, v229
	v_and_b32_e32 v209, 0xffff0000, v229
	v_lshlrev_b32_e32 v210, 16, v230
	v_and_b32_e32 v211, 0xffff0000, v230
	v_lshlrev_b32_e32 v212, 16, v231
	v_and_b32_e32 v213, 0xffff0000, v231
	v_sub_f32_e32 v206, v206, v182
	v_sub_f32_e32 v207, v207, v182
	v_sub_f32_e32 v208, v208, v182
	v_sub_f32_e32 v209, v209, v182
	v_sub_f32_e32 v210, v210, v182
	v_sub_f32_e32 v211, v211, v182
	v_sub_f32_e32 v212, v212, v182
	v_sub_f32_e32 v213, v213, v182
	v_pk_mul_f32 v[206:207], v[182:183], v[206:207] op_sel:[1,0]
	v_pk_mul_f32 v[208:209], v[182:183], v[208:209] op_sel:[1,0]
	v_pk_mul_f32 v[210:211], v[182:183], v[210:211] op_sel:[1,0]
	v_pk_mul_f32 v[212:213], v[182:183], v[212:213] op_sel:[1,0]
	v_pk_fma_f32 v[206:207], v[98:99], v[206:207], v[102:103]
	v_pk_fma_f32 v[208:209], v[100:101], v[208:209], v[104:105]
	v_pk_fma_f32 v[210:211], v[90:91], v[210:211], v[94:95]
	v_pk_fma_f32 v[212:213], v[92:93], v[212:213], v[96:97]
	v_pk_fma_f32 v[206:207], v[206:207], s[66:67], v[46:47] op_sel_hi:[1,0,1]
	v_pk_fma_f32 v[208:209], v[208:209], s[66:67], v[48:49] op_sel_hi:[1,0,1]
	v_pk_fma_f32 v[210:211], v[210:211], s[66:67], v[42:43] op_sel_hi:[1,0,1]
	v_pk_fma_f32 v[212:213], v[212:213], s[66:67], v[44:45] op_sel_hi:[1,0,1]
	v_cvt_pk_bf16_f32 v228, v206, v207
	v_cvt_pk_bf16_f32 v229, v208, v209
	v_cvt_pk_bf16_f32 v230, v210, v211
	v_cvt_pk_bf16_f32 v231, v212, v213
	s_add_u32 s48, s82, 0x20100
	s_addc_u32 s49, s83, 0
	global_store_dwordx4 v170, v[228:231], s[48:49]
	s_waitcnt vmcnt(11)
	v_lshlrev_b32_e32 v206, 16, v232
	v_and_b32_e32 v207, 0xffff0000, v232
	v_lshlrev_b32_e32 v208, 16, v233
	v_and_b32_e32 v209, 0xffff0000, v233
	v_lshlrev_b32_e32 v210, 16, v234
	v_and_b32_e32 v211, 0xffff0000, v234
	v_lshlrev_b32_e32 v212, 16, v235
	v_and_b32_e32 v213, 0xffff0000, v235
	v_sub_f32_e32 v206, v206, v184
	v_sub_f32_e32 v207, v207, v184
	v_sub_f32_e32 v208, v208, v184
	v_sub_f32_e32 v209, v209, v184
	v_sub_f32_e32 v210, v210, v184
	v_sub_f32_e32 v211, v211, v184
	v_sub_f32_e32 v212, v212, v184
	v_sub_f32_e32 v213, v213, v184
	v_pk_mul_f32 v[206:207], v[184:185], v[206:207] op_sel:[1,0]
	v_pk_mul_f32 v[208:209], v[184:185], v[208:209] op_sel:[1,0]
	v_pk_mul_f32 v[210:211], v[184:185], v[210:211] op_sel:[1,0]
	v_pk_mul_f32 v[212:213], v[184:185], v[212:213] op_sel:[1,0]
	v_pk_fma_f32 v[206:207], v[98:99], v[206:207], v[102:103]
	v_pk_fma_f32 v[208:209], v[100:101], v[208:209], v[104:105]
	v_pk_fma_f32 v[210:211], v[90:91], v[210:211], v[94:95]
	v_pk_fma_f32 v[212:213], v[92:93], v[212:213], v[96:97]
	v_pk_fma_f32 v[206:207], v[206:207], s[66:67], v[38:39] op_sel_hi:[1,0,1]
	v_pk_fma_f32 v[208:209], v[208:209], s[66:67], v[40:41] op_sel_hi:[1,0,1]
	v_pk_fma_f32 v[210:211], v[210:211], s[66:67], v[34:35] op_sel_hi:[1,0,1]
	v_pk_fma_f32 v[212:213], v[212:213], s[66:67], v[36:37] op_sel_hi:[1,0,1]
	v_cvt_pk_bf16_f32 v232, v206, v207
	v_cvt_pk_bf16_f32 v233, v208, v209
	v_cvt_pk_bf16_f32 v234, v210, v211
	v_cvt_pk_bf16_f32 v235, v212, v213
	s_add_u32 s48, s82, 0x30100
	s_addc_u32 s49, s83, 0
	global_store_dwordx4 v170, v[232:235], s[48:49]
	s_waitcnt vmcnt(10)
	v_lshlrev_b32_e32 v206, 16, v236
	v_and_b32_e32 v207, 0xffff0000, v236
	v_lshlrev_b32_e32 v208, 16, v237
	v_and_b32_e32 v209, 0xffff0000, v237
	v_lshlrev_b32_e32 v210, 16, v238
	v_and_b32_e32 v211, 0xffff0000, v238
	v_lshlrev_b32_e32 v212, 16, v239
	v_and_b32_e32 v213, 0xffff0000, v239
	v_sub_f32_e32 v206, v206, v168
	v_sub_f32_e32 v207, v207, v168
	v_sub_f32_e32 v208, v208, v168
	v_sub_f32_e32 v209, v209, v168
	v_sub_f32_e32 v210, v210, v168
	v_sub_f32_e32 v211, v211, v168
	v_sub_f32_e32 v212, v212, v168
	v_sub_f32_e32 v213, v213, v168
	v_pk_mul_f32 v[206:207], v[168:169], v[206:207] op_sel:[1,0]
	v_pk_mul_f32 v[208:209], v[168:169], v[208:209] op_sel:[1,0]
	v_pk_mul_f32 v[210:211], v[168:169], v[210:211] op_sel:[1,0]
	v_pk_mul_f32 v[212:213], v[168:169], v[212:213] op_sel:[1,0]
	v_pk_fma_f32 v[206:207], v[98:99], v[206:207], v[102:103]
	v_pk_fma_f32 v[208:209], v[100:101], v[208:209], v[104:105]
	v_pk_fma_f32 v[210:211], v[90:91], v[210:211], v[94:95]
	v_pk_fma_f32 v[212:213], v[92:93], v[212:213], v[96:97]
	v_pk_fma_f32 v[206:207], v[206:207], s[66:67], v[30:31] op_sel_hi:[1,0,1]
	v_pk_fma_f32 v[208:209], v[208:209], s[66:67], v[32:33] op_sel_hi:[1,0,1]
	v_pk_fma_f32 v[210:211], v[210:211], s[66:67], v[26:27] op_sel_hi:[1,0,1]
	v_pk_fma_f32 v[212:213], v[212:213], s[66:67], v[28:29] op_sel_hi:[1,0,1]
	v_cvt_pk_bf16_f32 v236, v206, v207
	v_cvt_pk_bf16_f32 v237, v208, v209
	v_cvt_pk_bf16_f32 v238, v210, v211
	v_cvt_pk_bf16_f32 v239, v212, v213
	s_add_u32 s48, s82, 0x80100
	s_addc_u32 s49, s83, 0
	global_store_dwordx4 v170, v[236:239], s[48:49]
	s_waitcnt vmcnt(9)
	v_lshlrev_b32_e32 v206, 16, v240
	v_and_b32_e32 v207, 0xffff0000, v240
	v_lshlrev_b32_e32 v208, 16, v241
	v_and_b32_e32 v209, 0xffff0000, v241
	v_lshlrev_b32_e32 v210, 16, v242
	v_and_b32_e32 v211, 0xffff0000, v242
	v_lshlrev_b32_e32 v212, 16, v243
	v_and_b32_e32 v213, 0xffff0000, v243
	v_sub_f32_e32 v206, v206, v252
	v_sub_f32_e32 v207, v207, v252
	v_sub_f32_e32 v208, v208, v252
	v_sub_f32_e32 v209, v209, v252
	v_sub_f32_e32 v210, v210, v252
	v_sub_f32_e32 v211, v211, v252
	v_sub_f32_e32 v212, v212, v252
	v_sub_f32_e32 v213, v213, v252
	v_pk_mul_f32 v[206:207], v[252:253], v[206:207] op_sel:[1,0]
	v_pk_mul_f32 v[208:209], v[252:253], v[208:209] op_sel:[1,0]
	v_pk_mul_f32 v[210:211], v[252:253], v[210:211] op_sel:[1,0]
	v_pk_mul_f32 v[212:213], v[252:253], v[212:213] op_sel:[1,0]
	v_pk_fma_f32 v[206:207], v[98:99], v[206:207], v[102:103]
	v_pk_fma_f32 v[208:209], v[100:101], v[208:209], v[104:105]
	v_pk_fma_f32 v[210:211], v[90:91], v[210:211], v[94:95]
	v_pk_fma_f32 v[212:213], v[92:93], v[212:213], v[96:97]
	v_pk_fma_f32 v[206:207], v[206:207], s[66:67], v[22:23] op_sel_hi:[1,0,1]
	v_pk_fma_f32 v[208:209], v[208:209], s[66:67], v[24:25] op_sel_hi:[1,0,1]
	v_pk_fma_f32 v[210:211], v[210:211], s[66:67], v[18:19] op_sel_hi:[1,0,1]
	v_pk_fma_f32 v[212:213], v[212:213], s[66:67], v[20:21] op_sel_hi:[1,0,1]
	v_cvt_pk_bf16_f32 v240, v206, v207
	v_cvt_pk_bf16_f32 v241, v208, v209
	v_cvt_pk_bf16_f32 v242, v210, v211
	v_cvt_pk_bf16_f32 v243, v212, v213
	s_add_u32 s48, s82, 0x90100
	s_addc_u32 s49, s83, 0
	global_store_dwordx4 v170, v[240:243], s[48:49]
	s_waitcnt vmcnt(8)
	v_lshlrev_b32_e32 v206, 16, v244
	v_and_b32_e32 v207, 0xffff0000, v244
	v_lshlrev_b32_e32 v208, 16, v245
	v_and_b32_e32 v209, 0xffff0000, v245
	v_lshlrev_b32_e32 v210, 16, v246
	v_and_b32_e32 v211, 0xffff0000, v246
	v_lshlrev_b32_e32 v212, 16, v247
	v_and_b32_e32 v213, 0xffff0000, v247
	v_sub_f32_e32 v206, v206, v214
	v_sub_f32_e32 v207, v207, v214
	v_sub_f32_e32 v208, v208, v214
	v_sub_f32_e32 v209, v209, v214
	v_sub_f32_e32 v210, v210, v214
	v_sub_f32_e32 v211, v211, v214
	v_sub_f32_e32 v212, v212, v214
	v_sub_f32_e32 v213, v213, v214
	v_pk_mul_f32 v[206:207], v[214:215], v[206:207] op_sel:[1,0]
	v_pk_mul_f32 v[208:209], v[214:215], v[208:209] op_sel:[1,0]
	v_pk_mul_f32 v[210:211], v[214:215], v[210:211] op_sel:[1,0]
	v_pk_mul_f32 v[212:213], v[214:215], v[212:213] op_sel:[1,0]
	v_pk_fma_f32 v[206:207], v[98:99], v[206:207], v[102:103]
	v_pk_fma_f32 v[208:209], v[100:101], v[208:209], v[104:105]
	v_pk_fma_f32 v[210:211], v[90:91], v[210:211], v[94:95]
	v_pk_fma_f32 v[212:213], v[92:93], v[212:213], v[96:97]
	v_pk_fma_f32 v[206:207], v[206:207], s[66:67], v[14:15] op_sel_hi:[1,0,1]
	v_pk_fma_f32 v[208:209], v[208:209], s[66:67], v[16:17] op_sel_hi:[1,0,1]
	v_pk_fma_f32 v[210:211], v[210:211], s[66:67], v[10:11] op_sel_hi:[1,0,1]
	v_pk_fma_f32 v[212:213], v[212:213], s[66:67], v[12:13] op_sel_hi:[1,0,1]
	v_cvt_pk_bf16_f32 v244, v206, v207
	v_cvt_pk_bf16_f32 v245, v208, v209
	v_cvt_pk_bf16_f32 v246, v210, v211
	v_cvt_pk_bf16_f32 v247, v212, v213
	s_add_u32 s48, s82, 0xa0100
	s_addc_u32 s49, s83, 0
	global_store_dwordx4 v170, v[244:247], s[48:49]
	s_waitcnt vmcnt(7)
	v_lshlrev_b32_e32 v206, 16, v248
	v_and_b32_e32 v207, 0xffff0000, v248
	v_lshlrev_b32_e32 v208, 16, v249
	v_and_b32_e32 v209, 0xffff0000, v249
	v_lshlrev_b32_e32 v210, 16, v250
	v_and_b32_e32 v211, 0xffff0000, v250
	v_lshlrev_b32_e32 v212, 16, v251
	v_and_b32_e32 v213, 0xffff0000, v251
	v_sub_f32_e32 v206, v206, v216
	v_sub_f32_e32 v207, v207, v216
	v_sub_f32_e32 v208, v208, v216
	v_sub_f32_e32 v209, v209, v216
	v_sub_f32_e32 v210, v210, v216
	v_sub_f32_e32 v211, v211, v216
	v_sub_f32_e32 v212, v212, v216
	v_sub_f32_e32 v213, v213, v216
	v_pk_mul_f32 v[206:207], v[216:217], v[206:207] op_sel:[1,0]
	v_pk_mul_f32 v[208:209], v[216:217], v[208:209] op_sel:[1,0]
	v_pk_mul_f32 v[210:211], v[216:217], v[210:211] op_sel:[1,0]
	v_pk_mul_f32 v[212:213], v[216:217], v[212:213] op_sel:[1,0]
	v_pk_fma_f32 v[206:207], v[98:99], v[206:207], v[102:103]
	v_pk_fma_f32 v[208:209], v[100:101], v[208:209], v[104:105]
	v_pk_fma_f32 v[210:211], v[90:91], v[210:211], v[94:95]
	v_pk_fma_f32 v[212:213], v[92:93], v[212:213], v[96:97]
	v_pk_fma_f32 v[206:207], v[206:207], s[66:67], v[6:7] op_sel_hi:[1,0,1]
	v_pk_fma_f32 v[208:209], v[208:209], s[66:67], v[8:9] op_sel_hi:[1,0,1]
	v_pk_fma_f32 v[210:211], v[210:211], s[66:67], v[2:3] op_sel_hi:[1,0,1]
	v_pk_fma_f32 v[212:213], v[212:213], s[66:67], v[4:5] op_sel_hi:[1,0,1]
	v_cvt_pk_bf16_f32 v248, v206, v207
	v_cvt_pk_bf16_f32 v249, v208, v209
	v_cvt_pk_bf16_f32 v250, v210, v211
	v_cvt_pk_bf16_f32 v251, v212, v213
	s_add_u32 s48, s82, 0xb0100
	s_addc_u32 s49, s83, 0
	global_store_dwordx4 v170, v[248:251], s[48:49]
	s_and_b64 vcc, exec, s[8:9]
	s_mov_b32 s43, s86
	s_mov_b32 s46, s84
	s_mov_b64 s[68:69], s[90:91]
	s_mov_b64 s[64:65], s[88:89]
	s_cbranch_vccz .LBB0_1249
	s_waitcnt vmcnt(0)
	v_readlane_b32 s86, v254, 39
	s_cmpk_gt_u32 s21, 0xff
	s_mov_b32 s84, 0xf800000
	s_mov_b32 s85, 0x100000
	v_readlane_b32 s87, v254, 40
	s_cbranch_scc1 .LBB0_1260
	s_barrier

.LBB0_1420:
	s_add_u32 s44, s92, 0xfff80080
	s_addc_u32 s45, s93, -1
	s_add_i32 s52, 0, 0x10000
	v_add_u32_e32 v126, s52, v205
	ds_read_b128 v[114:117], v126
	ds_read_b128 v[118:121], v126 offset:1024
	ds_read_b128 v[122:125], v126 offset:2048
	ds_read_b128 v[126:129], v126 offset:3072
	s_cmp_eq_u32 s51, 28
	s_cselect_b32 s95, s6, s45
	s_cselect_b32 s94, s7, s44
	s_cselect_b32 s45, s18, s50
	s_cselect_b32 s44, s19, s49
	v_lshl_add_u64 v[188:189], s[92:93], 0, v[168:169]
	s_add_i32 m0, s37, 0xc000
	ds_read_b128 v[172:175], v206
	ds_read_b128 v[176:179], v206 offset:1024
	ds_read_b128 v[180:183], v206 offset:2048
	ds_read_b128 v[184:187], v206 offset:3072
	ds_read_b128 v[208:211], v206 offset:4096
	ds_read_b128 v[212:215], v206 offset:5120
	ds_read_b128 v[216:219], v206 offset:6144
	ds_read_b128 v[220:223], v206 offset:7168
	global_load_lds_dwordx4 v[188:189], off
	v_lshl_add_u64 v[188:189], s[92:93], 0, v[170:171]
	s_add_i32 m0, s37, 0xe000
	s_nop 0
	global_load_lds_dwordx4 v[188:189], off
	s_waitcnt lgkmcnt(8)
	s_barrier
	s_waitcnt lgkmcnt(0)
	s_setprio 1
	s_waitcnt lgkmcnt(0)
	v_mfma_f32_16x16x32_bf16 v[138:141], v[114:117], v[172:175], v[138:141]
	v_mfma_f32_16x16x32_bf16 v[58:61], v[122:125], v[172:175], v[58:61]
	v_mfma_f32_16x16x32_bf16 v[134:137], v[114:117], v[180:183], v[134:137]
	v_mfma_f32_16x16x32_bf16 v[54:57], v[122:125], v[180:183], v[54:57]
	v_mfma_f32_16x16x32_bf16 v[110:113], v[114:117], v[208:211], v[110:113]
	v_mfma_f32_16x16x32_bf16 v[46:49], v[122:125], v[208:211], v[46:49]
	v_mfma_f32_16x16x32_bf16 v[102:105], v[114:117], v[216:219], v[102:105]
	v_mfma_f32_16x16x32_bf16 v[38:41], v[122:125], v[216:219], v[38:41]
	v_mfma_f32_16x16x32_bf16 v[138:141], v[118:121], v[176:179], v[138:141]
	v_mfma_f32_16x16x32_bf16 v[58:61], v[126:129], v[176:179], v[58:61]
	v_mfma_f32_16x16x32_bf16 v[134:137], v[118:121], v[184:187], v[134:137]
	v_mfma_f32_16x16x32_bf16 v[54:57], v[126:129], v[184:187], v[54:57]
	v_mfma_f32_16x16x32_bf16 v[110:113], v[118:121], v[212:215], v[110:113]
	v_mfma_f32_16x16x32_bf16 v[46:49], v[126:129], v[212:215], v[46:49]
	v_mfma_f32_16x16x32_bf16 v[102:105], v[118:121], v[220:223], v[102:105]
	s_setprio 2
	s_barrier
	v_mfma_f32_16x16x32_bf16 v[38:41], v[126:129], v[220:223], v[38:41]
	s_setprio 0
	s_add_i32 s54, 0, 0x14000
	v_add_u32_e32 v188, s54, v205
	s_add_i32 s52, s52, s23
	ds_read_b128 v[224:227], v188
	ds_read_b128 v[228:231], v188 offset:1024
	ds_read_b128 v[232:235], v188 offset:2048
	ds_read_b128 v[236:239], v188 offset:3072
	v_lshl_add_u64 v[188:189], s[44:45], 0, v[0:1]
	s_mov_b32 m0, s52
	v_lshl_add_u64 v[240:241], s[44:45], 0, v[158:159]
	global_load_lds_dwordx4 v[188:189], off
	s_add_i32 m0, s52, 0x2000
	s_nop 0
	global_load_lds_dwordx4 v[240:241], off
	s_barrier
	s_waitcnt lgkmcnt(0)
	s_setprio 1
	s_waitcnt lgkmcnt(0)
	v_mfma_f32_16x16x32_bf16 v[142:145], v[224:227], v[172:175], v[142:145]
	v_mfma_f32_16x16x32_bf16 v[62:65], v[232:235], v[172:175], v[62:65]
	v_mfma_f32_16x16x32_bf16 v[130:133], v[224:227], v[180:183], v[130:133]
	v_mfma_f32_16x16x32_bf16 v[50:53], v[232:235], v[180:183], v[50:53]
	v_mfma_f32_16x16x32_bf16 v[106:109], v[224:227], v[208:211], v[106:109]
	v_mfma_f32_16x16x32_bf16 v[42:45], v[232:235], v[208:211], v[42:45]
	v_mfma_f32_16x16x32_bf16 v[98:101], v[224:227], v[216:219], v[98:101]
	v_mfma_f32_16x16x32_bf16 v[34:37], v[232:235], v[216:219], v[34:37]
	v_mfma_f32_16x16x32_bf16 v[142:145], v[228:231], v[176:179], v[142:145]
	v_mfma_f32_16x16x32_bf16 v[62:65], v[236:239], v[176:179], v[62:65]
	v_mfma_f32_16x16x32_bf16 v[130:133], v[228:231], v[184:187], v[130:133]
	v_mfma_f32_16x16x32_bf16 v[50:53], v[236:239], v[184:187], v[50:53]
	v_mfma_f32_16x16x32_bf16 v[106:109], v[228:231], v[212:215], v[106:109]
	v_mfma_f32_16x16x32_bf16 v[42:45], v[236:239], v[212:215], v[42:45]
	v_mfma_f32_16x16x32_bf16 v[98:101], v[228:231], v[220:223], v[98:101]
	s_setprio 2
	s_mov_b32 m0, s37
	v_lshl_add_u64 v[242:243], s[94:95], 0, v[162:163]
	s_barrier
	v_mfma_f32_16x16x32_bf16 v[34:37], v[236:239], v[220:223], v[34:37]
	s_setprio 0
	ds_read_b128 v[172:175], v206 offset:16384
	ds_read_b128 v[176:179], v206 offset:17408
	ds_read_b128 v[180:183], v206 offset:18432
	ds_read_b128 v[184:187], v206 offset:19456
	ds_read_b128 v[208:211], v206 offset:20480
	ds_read_b128 v[212:215], v206 offset:21504
	ds_read_b128 v[216:219], v206 offset:22528
	ds_read_b128 v[220:223], v206 offset:23552
	global_load_lds_dwordx4 v[242:243], off
	v_lshl_add_u64 v[244:245], s[94:95], 0, v[160:161]
	s_mov_b32 m0, s40
	s_nop 0
	global_load_lds_dwordx4 v[244:245], off
	s_barrier
	s_waitcnt lgkmcnt(0)
	s_setprio 1
	s_waitcnt lgkmcnt(0)
	v_mfma_f32_16x16x32_bf16 v[94:97], v[114:117], v[172:175], v[94:97]
	v_mfma_f32_16x16x32_bf16 v[30:33], v[122:125], v[172:175], v[30:33]
	v_mfma_f32_16x16x32_bf16 v[86:89], v[114:117], v[180:183], v[86:89]
	v_mfma_f32_16x16x32_bf16 v[22:25], v[122:125], v[180:183], v[22:25]
	v_mfma_f32_16x16x32_bf16 v[78:81], v[114:117], v[208:211], v[78:81]
	v_mfma_f32_16x16x32_bf16 v[14:17], v[122:125], v[208:211], v[14:17]
	v_mfma_f32_16x16x32_bf16 v[70:73], v[114:117], v[216:219], v[70:73]
	v_mfma_f32_16x16x32_bf16 v[6:9], v[122:125], v[216:219], v[6:9]
	v_mfma_f32_16x16x32_bf16 v[94:97], v[118:121], v[176:179], v[94:97]
	v_mfma_f32_16x16x32_bf16 v[30:33], v[126:129], v[176:179], v[30:33]
	v_mfma_f32_16x16x32_bf16 v[86:89], v[118:121], v[184:187], v[86:89]
	v_mfma_f32_16x16x32_bf16 v[22:25], v[126:129], v[184:187], v[22:25]
	v_mfma_f32_16x16x32_bf16 v[78:81], v[118:121], v[212:215], v[78:81]
	v_mfma_f32_16x16x32_bf16 v[14:17], v[126:129], v[212:215], v[14:17]
	v_mfma_f32_16x16x32_bf16 v[70:73], v[118:121], v[220:223], v[70:73]
	s_setprio 2
	s_barrier
	v_mfma_f32_16x16x32_bf16 v[6:9], v[126:129], v[220:223], v[6:9]
	s_setprio 0
	s_add_u32 s52, s44, 0x80000
	s_addc_u32 s53, s45, 0
	s_add_i32 s54, s54, s23
	v_lshl_add_u64 v[114:115], s[52:53], 0, v[0:1]
	s_mov_b32 m0, s54
	s_nop 0
	global_load_lds_dwordx4 v[114:115], off
	v_lshl_add_u64 v[114:115], s[52:53], 0, v[158:159]
	s_add_i32 m0, s54, 0x2000
	s_nop 0
	global_load_lds_dwordx4 v[114:115], off
	s_waitcnt vmcnt(6)
	s_barrier
	s_setprio 1
	v_mfma_f32_16x16x32_bf16 v[90:93], v[224:227], v[172:175], v[90:93]
	v_mfma_f32_16x16x32_bf16 v[26:29], v[232:235], v[172:175], v[26:29]
	v_mfma_f32_16x16x32_bf16 v[82:85], v[224:227], v[180:183], v[82:85]
	v_mfma_f32_16x16x32_bf16 v[18:21], v[232:235], v[180:183], v[18:21]
	v_mfma_f32_16x16x32_bf16 v[74:77], v[224:227], v[208:211], v[74:77]
	v_mfma_f32_16x16x32_bf16 v[10:13], v[232:235], v[208:211], v[10:13]
	v_mfma_f32_16x16x32_bf16 v[66:69], v[224:227], v[216:219], v[66:69]
	v_mfma_f32_16x16x32_bf16 v[2:5], v[232:235], v[216:219], v[2:5]
	v_mfma_f32_16x16x32_bf16 v[90:93], v[228:231], v[176:179], v[90:93]
	v_mfma_f32_16x16x32_bf16 v[26:29], v[236:239], v[176:179], v[26:29]
	v_mfma_f32_16x16x32_bf16 v[82:85], v[228:231], v[184:187], v[82:85]
	v_mfma_f32_16x16x32_bf16 v[18:21], v[236:239], v[184:187], v[18:21]
	v_mfma_f32_16x16x32_bf16 v[74:77], v[228:231], v[212:215], v[74:77]
	v_mfma_f32_16x16x32_bf16 v[10:13], v[236:239], v[212:215], v[10:13]
	v_mfma_f32_16x16x32_bf16 v[66:69], v[228:231], v[220:223], v[66:69]
	s_setprio 2
	s_add_i32 s54, 0, 0x18000
	v_add_u32_e32 v126, s54, v205
	s_barrier
	v_mfma_f32_16x16x32_bf16 v[2:5], v[236:239], v[220:223], v[2:5]
	s_setprio 0
	ds_read_b128 v[114:117], v126
	ds_read_b128 v[118:121], v126 offset:1024
	ds_read_b128 v[122:125], v126 offset:2048
	ds_read_b128 v[126:129], v126 offset:3072
	s_add_u32 s52, s94, 0x80000
	s_addc_u32 s53, s95, 0
	s_mov_b32 m0, s41
	v_lshl_add_u64 v[224:225], s[52:53], 0, v[162:163]
	ds_read_b128 v[172:175], v206 offset:32768
	ds_read_b128 v[176:179], v206 offset:33792
	ds_read_b128 v[180:183], v206 offset:34816
	ds_read_b128 v[184:187], v206 offset:35840
	ds_read_b128 v[208:211], v206 offset:36864
	ds_read_b128 v[212:215], v206 offset:37888
	ds_read_b128 v[216:219], v206 offset:38912
	ds_read_b128 v[220:223], v206 offset:39936
	global_load_lds_dwordx4 v[224:225], off
	v_lshl_add_u64 v[224:225], s[52:53], 0, v[160:161]
	s_mov_b32 m0, s42
	s_nop 0
	global_load_lds_dwordx4 v[224:225], off
	s_waitcnt lgkmcnt(8)
	s_barrier
	s_waitcnt lgkmcnt(0)
	s_setprio 1
	s_waitcnt lgkmcnt(0)
	v_mfma_f32_16x16x32_bf16 v[138:141], v[114:117], v[172:175], v[138:141]
	v_mfma_f32_16x16x32_bf16 v[58:61], v[122:125], v[172:175], v[58:61]
	v_mfma_f32_16x16x32_bf16 v[134:137], v[114:117], v[180:183], v[134:137]
	v_mfma_f32_16x16x32_bf16 v[54:57], v[122:125], v[180:183], v[54:57]
	v_mfma_f32_16x16x32_bf16 v[110:113], v[114:117], v[208:211], v[110:113]
	v_mfma_f32_16x16x32_bf16 v[46:49], v[122:125], v[208:211], v[46:49]
	v_mfma_f32_16x16x32_bf16 v[102:105], v[114:117], v[216:219], v[102:105]
	v_mfma_f32_16x16x32_bf16 v[38:41], v[122:125], v[216:219], v[38:41]
	v_mfma_f32_16x16x32_bf16 v[138:141], v[118:121], v[176:179], v[138:141]
	v_mfma_f32_16x16x32_bf16 v[58:61], v[126:129], v[176:179], v[58:61]
	v_mfma_f32_16x16x32_bf16 v[134:137], v[118:121], v[184:187], v[134:137]
	v_mfma_f32_16x16x32_bf16 v[54:57], v[126:129], v[184:187], v[54:57]
	v_mfma_f32_16x16x32_bf16 v[110:113], v[118:121], v[212:215], v[110:113]
	v_mfma_f32_16x16x32_bf16 v[46:49], v[126:129], v[212:215], v[46:49]
	v_mfma_f32_16x16x32_bf16 v[102:105], v[118:121], v[220:223], v[102:105]
	s_setprio 2
	s_barrier
	v_mfma_f32_16x16x32_bf16 v[38:41], v[126:129], v[220:223], v[38:41]
	s_setprio 0
	s_add_i32 s52, 0, 0x1c000
	s_add_i32 s53, s54, s23
	v_add_u32_e32 v207, s52, v205
	v_lshl_add_u64 v[188:189], v[188:189], 0, s[62:63]
	s_mov_b32 m0, s53
	ds_read_b128 v[224:227], v207
	ds_read_b128 v[228:231], v207 offset:1024
	ds_read_b128 v[232:235], v207 offset:2048
	ds_read_b128 v[236:239], v207 offset:3072
	global_load_lds_dwordx4 v[188:189], off
	v_lshl_add_u64 v[188:189], v[240:241], 0, s[62:63]
	s_add_i32 m0, s53, 0x2000
	s_nop 0
	global_load_lds_dwordx4 v[188:189], off
	s_barrier
	s_waitcnt lgkmcnt(0)
	s_setprio 1
	s_waitcnt lgkmcnt(0)
	v_mfma_f32_16x16x32_bf16 v[142:145], v[224:227], v[172:175], v[142:145]
	v_mfma_f32_16x16x32_bf16 v[62:65], v[232:235], v[172:175], v[62:65]
	v_mfma_f32_16x16x32_bf16 v[130:133], v[224:227], v[180:183], v[130:133]
	v_mfma_f32_16x16x32_bf16 v[50:53], v[232:235], v[180:183], v[50:53]
	v_mfma_f32_16x16x32_bf16 v[106:109], v[224:227], v[208:211], v[106:109]
	v_mfma_f32_16x16x32_bf16 v[42:45], v[232:235], v[208:211], v[42:45]
	v_mfma_f32_16x16x32_bf16 v[98:101], v[224:227], v[216:219], v[98:101]
	v_mfma_f32_16x16x32_bf16 v[34:37], v[232:235], v[216:219], v[34:37]
	v_mfma_f32_16x16x32_bf16 v[142:145], v[228:231], v[176:179], v[142:145]
	v_mfma_f32_16x16x32_bf16 v[62:65], v[236:239], v[176:179], v[62:65]
	v_mfma_f32_16x16x32_bf16 v[130:133], v[228:231], v[184:187], v[130:133]
	v_mfma_f32_16x16x32_bf16 v[50:53], v[236:239], v[184:187], v[50:53]
	v_mfma_f32_16x16x32_bf16 v[106:109], v[228:231], v[212:215], v[106:109]
	v_mfma_f32_16x16x32_bf16 v[42:45], v[236:239], v[212:215], v[42:45]
	v_mfma_f32_16x16x32_bf16 v[98:101], v[228:231], v[220:223], v[98:101]
	s_setprio 2
	s_mov_b32 m0, s46
	v_lshl_add_u64 v[188:189], v[242:243], 0, s[62:63]
	s_barrier
	v_mfma_f32_16x16x32_bf16 v[34:37], v[236:239], v[220:223], v[34:37]
	s_setprio 0
	ds_read_b128 v[172:175], v206 offset:49152
	ds_read_b128 v[176:179], v206 offset:50176
	ds_read_b128 v[180:183], v206 offset:51200
	ds_read_b128 v[184:187], v206 offset:52224
	ds_read_b128 v[208:211], v206 offset:53248
	ds_read_b128 v[212:215], v206 offset:54272
	ds_read_b128 v[216:219], v206 offset:55296
	ds_read_b128 v[220:223], v206 offset:56320
	global_load_lds_dwordx4 v[188:189], off
	v_lshl_add_u64 v[188:189], v[244:245], 0, s[62:63]
	s_mov_b32 m0, s47
	s_nop 0
	global_load_lds_dwordx4 v[188:189], off
	s_barrier
	s_waitcnt lgkmcnt(0)
	s_setprio 1
	s_waitcnt lgkmcnt(0)
	v_mfma_f32_16x16x32_bf16 v[94:97], v[114:117], v[172:175], v[94:97]
	v_mfma_f32_16x16x32_bf16 v[30:33], v[122:125], v[172:175], v[30:33]
	v_mfma_f32_16x16x32_bf16 v[86:89], v[114:117], v[180:183], v[86:89]
	v_mfma_f32_16x16x32_bf16 v[22:25], v[122:125], v[180:183], v[22:25]
	v_mfma_f32_16x16x32_bf16 v[78:81], v[114:117], v[208:211], v[78:81]
	v_mfma_f32_16x16x32_bf16 v[14:17], v[122:125], v[208:211], v[14:17]
	v_mfma_f32_16x16x32_bf16 v[70:73], v[114:117], v[216:219], v[70:73]
	v_mfma_f32_16x16x32_bf16 v[6:9], v[122:125], v[216:219], v[6:9]
	v_mfma_f32_16x16x32_bf16 v[94:97], v[118:121], v[176:179], v[94:97]
	v_mfma_f32_16x16x32_bf16 v[30:33], v[126:129], v[176:179], v[30:33]
	v_mfma_f32_16x16x32_bf16 v[86:89], v[118:121], v[184:187], v[86:89]
	v_mfma_f32_16x16x32_bf16 v[22:25], v[126:129], v[184:187], v[22:25]
	v_mfma_f32_16x16x32_bf16 v[78:81], v[118:121], v[212:215], v[78:81]
	v_mfma_f32_16x16x32_bf16 v[14:17], v[126:129], v[212:215], v[14:17]
	v_mfma_f32_16x16x32_bf16 v[70:73], v[118:121], v[220:223], v[70:73]
	s_setprio 2
	s_barrier
	v_mfma_f32_16x16x32_bf16 v[6:9], v[126:129], v[220:223], v[6:9]
	s_setprio 0
	s_add_u32 s44, s44, 0x80080
	s_addc_u32 s45, s45, 0
	s_add_i32 s52, s52, s23
	v_lshl_add_u64 v[114:115], s[44:45], 0, v[0:1]
	s_mov_b32 m0, s52
	s_nop 0
	global_load_lds_dwordx4 v[114:115], off
	v_lshl_add_u64 v[114:115], s[44:45], 0, v[158:159]
	s_add_i32 m0, s52, 0x2000
	s_nop 0
	global_load_lds_dwordx4 v[114:115], off
	s_waitcnt vmcnt(6)
	s_barrier
	s_setprio 1
	v_mfma_f32_16x16x32_bf16 v[90:93], v[224:227], v[172:175], v[90:93]
	v_mfma_f32_16x16x32_bf16 v[26:29], v[232:235], v[172:175], v[26:29]
	v_mfma_f32_16x16x32_bf16 v[82:85], v[224:227], v[180:183], v[82:85]
	v_mfma_f32_16x16x32_bf16 v[18:21], v[232:235], v[180:183], v[18:21]
	v_mfma_f32_16x16x32_bf16 v[74:77], v[224:227], v[208:211], v[74:77]
	v_mfma_f32_16x16x32_bf16 v[10:13], v[232:235], v[208:211], v[10:13]
	v_mfma_f32_16x16x32_bf16 v[66:69], v[224:227], v[216:219], v[66:69]
	v_mfma_f32_16x16x32_bf16 v[2:5], v[232:235], v[216:219], v[2:5]
	v_mfma_f32_16x16x32_bf16 v[90:93], v[228:231], v[176:179], v[90:93]
	v_mfma_f32_16x16x32_bf16 v[26:29], v[236:239], v[176:179], v[26:29]
	v_mfma_f32_16x16x32_bf16 v[82:85], v[228:231], v[184:187], v[82:85]
	v_mfma_f32_16x16x32_bf16 v[18:21], v[236:239], v[184:187], v[18:21]
	v_mfma_f32_16x16x32_bf16 v[74:77], v[228:231], v[212:215], v[74:77]
	v_mfma_f32_16x16x32_bf16 v[10:13], v[236:239], v[212:215], v[10:13]
	v_mfma_f32_16x16x32_bf16 v[66:69], v[228:231], v[220:223], v[66:69]
	s_setprio 2
	s_add_i32 s51, s51, 2
	s_add_u32 s92, s92, 0x100
	s_addc_u32 s93, s93, 0
	s_add_u32 s49, s49, 0x100
	s_addc_u32 s50, s50, 0
	s_cmp_gt_u32 s51, 29
	s_barrier
	v_mfma_f32_16x16x32_bf16 v[2:5], v[236:239], v[220:223], v[2:5]
	s_setprio 0
	s_cbranch_scc0 .LBB0_1420
	v_lshl_or_b32 v174, s5, 7, v167
	v_ashrrev_i32_e32 v175, 31, v174
	v_lshlrev_b64 v[180:181], 2, v[174:175]
	v_lshl_add_u64 v[176:177], s[76:77], 0, v[180:181]
	v_lshl_add_u64 v[118:119], s[82:83], 0, v[180:181]
	v_lshl_add_u64 v[120:121], s[84:85], 0, v[180:181]
	v_lshl_add_u64 v[178:179], s[80:81], 0, v[180:181]
	global_load_dwordx4 v[114:117], v[176:177], off
	global_load_dwordx4 v[220:223], v[176:177], off offset:16
	global_load_dwordx4 v[122:125], v[118:119], off
	global_load_dwordx4 v[224:227], v[118:119], off offset:16
	global_load_dwordx4 v[228:231], v[120:121], off offset:16
	global_load_dwordx4 v[118:121], v[120:121], off
	s_lshl_b32 s4, s4, 8
	global_load_dwordx4 v[126:129], v[178:179], off
	global_load_dwordx4 v[232:235], v[178:179], off offset:16
	s_and_b32 s4, s4, 0x3f00
	s_add_i32 s4, s4, s43
	v_or_b32_e32 v207, s4, v164
	v_lshl_add_u64 v[172:173], v[174:175], 1, s[78:79]
	v_mov_b32_dpp v186, v138 row_shr:1 row_mask:0xf bank_mask:0xf bound_ctrl:1
	v_mov_b32_dpp v188, v138 row_shr:2 row_mask:0xf bank_mask:0xf bound_ctrl:1
	v_mov_b32_dpp v187, v139 row_shr:1 row_mask:0xf bank_mask:0xf bound_ctrl:1
	v_mov_b32_dpp v189, v139 row_shr:2 row_mask:0xf bank_mask:0xf bound_ctrl:1
	v_mov_b32_dpp v182, v140 row_shr:1 row_mask:0xf bank_mask:0xf bound_ctrl:1
	v_mov_b32_dpp v184, v140 row_shr:2 row_mask:0xf bank_mask:0xf bound_ctrl:1
	v_mov_b32_dpp v183, v141 row_shr:1 row_mask:0xf bank_mask:0xf bound_ctrl:1
	v_mov_b32_dpp v185, v141 row_shr:2 row_mask:0xf bank_mask:0xf bound_ctrl:1
	s_and_saveexec_b64 s[6:7], s[10:11]
	s_xor_b64 s[6:7], exec, s[6:7]
	s_cbranch_execz .LBB0_1423
	s_waitcnt vmcnt(0)
	v_pk_fma_f32 v[188:189], v[114:115], v[188:189], v[126:127]
	v_pk_fma_f32 v[184:185], v[116:117], v[184:185], v[128:129]
	v_pk_fma_f32 v[186:187], v[122:123], v[186:187], v[188:189]
	v_pk_fma_f32 v[182:183], v[124:125], v[182:183], v[184:185]
	v_pk_fma_f32 v[186:187], v[138:139], v[118:119], v[186:187]
	v_pk_fma_f32 v[182:183], v[140:141], v[120:121], v[182:183]
	v_mul_f32_e32 v175, 0xbfb8aa3b, v186
	v_exp_f32_e32 v175, v175
	v_mul_f32_e32 v188, 0xbfb8aa3b, v187
	v_exp_f32_e32 v188, v188
	v_mul_f32_e32 v184, 0xbfb8aa3b, v183
	v_add_f32_e32 v175, 1.0, v175
	v_exp_f32_e32 v185, v184
	v_add_f32_e32 v189, 1.0, v188
	v_rcp_f32_e32 v188, v175
	v_mul_f32_e32 v175, 0xbfb8aa3b, v182
	v_exp_f32_e32 v175, v175
	v_rcp_f32_e32 v189, v189
	v_add_f32_e32 v175, 1.0, v175
	v_rcp_f32_e32 v184, v175
	v_add_f32_e32 v175, 1.0, v185
	v_rcp_f32_e32 v185, v175
	v_pk_mul_f32 v[186:187], v[186:187], v[188:189]
	v_pk_mul_f32 v[182:183], v[182:183], v[184:185]
	v_pk_mul_f32 v[186:187], v[142:143], v[186:187]
	v_pk_mul_f32 v[182:183], v[144:145], v[182:183]
	v_cvt_pk_bf16_f32 v184, v186, v187
	v_cvt_pk_bf16_f32 v185, v182, v183
	v_mad_i64_i32 v[182:183], s[18:19], v207, s39, v[172:173]
	global_store_dwordx2 v[182:183], v[184:185], off

.LBB0_1617:
	s_add_u32 s68, s64, 0x100
	s_addc_u32 s69, s65, 0
	s_add_i32 s48, 0, 0x10000
	v_add_u32_e32 v102, s48, v187
	ds_read_b128 v[90:93], v102
	ds_read_b128 v[94:97], v102 offset:1024
	ds_read_b128 v[98:101], v102 offset:2048
	ds_read_b128 v[102:105], v102 offset:3072
	s_cmpk_eq_i32 s47, 0x54
	s_cselect_b32 s81, s11, s69
	s_cselect_b32 s80, s10, s68
	s_cselect_b32 s45, s13, s5
	s_cselect_b32 s44, s12, s4
	v_lshl_add_u64 v[184:185], s[64:65], 0, v[164:165]
	s_add_i32 m0, s27, 0xc000
	ds_read_b128 v[168:171], v189
	ds_read_b128 v[172:175], v189 offset:1024
	ds_read_b128 v[176:179], v189 offset:2048
	ds_read_b128 v[180:183], v189 offset:3072
	ds_read_b128 v[206:209], v189 offset:4096
	ds_read_b128 v[210:213], v189 offset:5120
	ds_read_b128 v[214:217], v189 offset:6144
	ds_read_b128 v[218:221], v189 offset:7168
	global_load_lds_dwordx4 v[184:185], off
	v_lshl_add_u64 v[184:185], s[64:65], 0, v[166:167]
	s_add_i32 m0, s27, 0xe000
	s_nop 0
	global_load_lds_dwordx4 v[184:185], off
	s_waitcnt lgkmcnt(8)
	s_barrier
	s_waitcnt lgkmcnt(0)
	s_setprio 1
	s_waitcnt lgkmcnt(0)
	v_mfma_f32_16x16x32_bf16 v[142:145], v[90:93], v[168:171], v[142:145]
	v_mfma_f32_16x16x32_bf16 v[138:141], v[98:101], v[168:171], v[138:141]
	v_mfma_f32_16x16x32_bf16 v[134:137], v[90:93], v[176:179], v[134:137]
	v_mfma_f32_16x16x32_bf16 v[130:133], v[98:101], v[176:179], v[130:133]
	v_mfma_f32_16x16x32_bf16 v[126:129], v[90:93], v[206:209], v[126:129]
	v_mfma_f32_16x16x32_bf16 v[122:125], v[98:101], v[206:209], v[122:125]
	v_mfma_f32_16x16x32_bf16 v[118:121], v[90:93], v[214:217], v[118:121]
	v_mfma_f32_16x16x32_bf16 v[114:117], v[98:101], v[214:217], v[114:117]
	v_mfma_f32_16x16x32_bf16 v[142:145], v[94:97], v[172:175], v[142:145]
	v_mfma_f32_16x16x32_bf16 v[138:141], v[102:105], v[172:175], v[138:141]
	v_mfma_f32_16x16x32_bf16 v[134:137], v[94:97], v[180:183], v[134:137]
	v_mfma_f32_16x16x32_bf16 v[130:133], v[102:105], v[180:183], v[130:133]
	v_mfma_f32_16x16x32_bf16 v[126:129], v[94:97], v[210:213], v[126:129]
	v_mfma_f32_16x16x32_bf16 v[122:125], v[102:105], v[210:213], v[122:125]
	v_mfma_f32_16x16x32_bf16 v[118:121], v[94:97], v[218:221], v[118:121]
	s_setprio 2
	s_barrier
	v_mfma_f32_16x16x32_bf16 v[114:117], v[102:105], v[218:221], v[114:117]
	s_setprio 0
	s_add_i32 s50, 0, 0x14000
	v_add_u32_e32 v184, s50, v187
	s_add_i32 s48, s48, s22
	ds_read_b128 v[222:225], v184
	ds_read_b128 v[226:229], v184 offset:1024
	ds_read_b128 v[230:233], v184 offset:2048
	ds_read_b128 v[234:237], v184 offset:3072
	v_lshl_add_u64 v[184:185], s[44:45], 0, v[0:1]
	s_mov_b32 m0, s48
	v_lshl_add_u64 v[238:239], s[44:45], 0, v[158:159]
	global_load_lds_dwordx4 v[184:185], off
	s_add_i32 m0, s48, 0x2000
	s_nop 0
	global_load_lds_dwordx4 v[238:239], off
	s_barrier
	s_waitcnt lgkmcnt(0)
	s_setprio 1
	s_waitcnt lgkmcnt(0)
	v_mfma_f32_16x16x32_bf16 v[62:65], v[222:225], v[168:171], v[62:65]
	v_mfma_f32_16x16x32_bf16 v[58:61], v[230:233], v[168:171], v[58:61]
	v_mfma_f32_16x16x32_bf16 v[54:57], v[222:225], v[176:179], v[54:57]
	v_mfma_f32_16x16x32_bf16 v[50:53], v[230:233], v[176:179], v[50:53]
	v_mfma_f32_16x16x32_bf16 v[46:49], v[222:225], v[206:209], v[46:49]
	v_mfma_f32_16x16x32_bf16 v[42:45], v[230:233], v[206:209], v[42:45]
	v_mfma_f32_16x16x32_bf16 v[38:41], v[222:225], v[214:217], v[38:41]
	v_mfma_f32_16x16x32_bf16 v[34:37], v[230:233], v[214:217], v[34:37]
	v_mfma_f32_16x16x32_bf16 v[62:65], v[226:229], v[172:175], v[62:65]
	v_mfma_f32_16x16x32_bf16 v[58:61], v[234:237], v[172:175], v[58:61]
	v_mfma_f32_16x16x32_bf16 v[54:57], v[226:229], v[180:183], v[54:57]
	v_mfma_f32_16x16x32_bf16 v[50:53], v[234:237], v[180:183], v[50:53]
	v_mfma_f32_16x16x32_bf16 v[46:49], v[226:229], v[210:213], v[46:49]
	v_mfma_f32_16x16x32_bf16 v[42:45], v[234:237], v[210:213], v[42:45]
	v_mfma_f32_16x16x32_bf16 v[38:41], v[226:229], v[218:221], v[38:41]
	s_setprio 2
	s_mov_b32 m0, s27
	v_lshl_add_u64 v[240:241], s[80:81], 0, v[162:163]
	s_barrier
	v_mfma_f32_16x16x32_bf16 v[34:37], v[234:237], v[218:221], v[34:37]
	s_setprio 0
	ds_read_b128 v[168:171], v189 offset:16384
	ds_read_b128 v[172:175], v189 offset:17408
	ds_read_b128 v[176:179], v189 offset:18432
	ds_read_b128 v[180:183], v189 offset:19456
	ds_read_b128 v[206:209], v189 offset:20480
	ds_read_b128 v[210:213], v189 offset:21504
	ds_read_b128 v[214:217], v189 offset:22528
	ds_read_b128 v[218:221], v189 offset:23552
	global_load_lds_dwordx4 v[240:241], off
	v_lshl_add_u64 v[242:243], s[80:81], 0, v[160:161]
	s_mov_b32 m0, s36
	s_nop 0
	global_load_lds_dwordx4 v[242:243], off
	s_barrier
	s_waitcnt lgkmcnt(0)
	s_setprio 1
	s_waitcnt lgkmcnt(0)
	v_mfma_f32_16x16x32_bf16 v[110:113], v[90:93], v[168:171], v[110:113]
	v_mfma_f32_16x16x32_bf16 v[106:109], v[98:101], v[168:171], v[106:109]
	v_mfma_f32_16x16x32_bf16 v[86:89], v[90:93], v[176:179], v[86:89]
	v_mfma_f32_16x16x32_bf16 v[82:85], v[98:101], v[176:179], v[82:85]
	v_mfma_f32_16x16x32_bf16 v[78:81], v[90:93], v[206:209], v[78:81]
	v_mfma_f32_16x16x32_bf16 v[74:77], v[98:101], v[206:209], v[74:77]
	v_mfma_f32_16x16x32_bf16 v[70:73], v[90:93], v[214:217], v[70:73]
	v_mfma_f32_16x16x32_bf16 v[66:69], v[98:101], v[214:217], v[66:69]
	v_mfma_f32_16x16x32_bf16 v[110:113], v[94:97], v[172:175], v[110:113]
	v_mfma_f32_16x16x32_bf16 v[106:109], v[102:105], v[172:175], v[106:109]
	v_mfma_f32_16x16x32_bf16 v[86:89], v[94:97], v[180:183], v[86:89]
	v_mfma_f32_16x16x32_bf16 v[82:85], v[102:105], v[180:183], v[82:85]
	v_mfma_f32_16x16x32_bf16 v[78:81], v[94:97], v[210:213], v[78:81]
	v_mfma_f32_16x16x32_bf16 v[74:77], v[102:105], v[210:213], v[74:77]
	v_mfma_f32_16x16x32_bf16 v[70:73], v[94:97], v[218:221], v[70:73]
	s_setprio 2
	s_barrier
	v_mfma_f32_16x16x32_bf16 v[66:69], v[102:105], v[218:221], v[66:69]
	s_setprio 0
	s_add_u32 s48, s44, 0x160000
	s_addc_u32 s49, s45, 0
	s_add_i32 s50, s50, s22
	v_lshl_add_u64 v[90:91], s[48:49], 0, v[0:1]
	s_mov_b32 m0, s50
	s_nop 0
	global_load_lds_dwordx4 v[90:91], off
	v_lshl_add_u64 v[90:91], s[48:49], 0, v[158:159]
	s_add_i32 m0, s50, 0x2000
	s_nop 0
	global_load_lds_dwordx4 v[90:91], off
	s_waitcnt vmcnt(6)
	s_barrier
	s_setprio 1
	v_mfma_f32_16x16x32_bf16 v[30:33], v[222:225], v[168:171], v[30:33]
	v_mfma_f32_16x16x32_bf16 v[26:29], v[230:233], v[168:171], v[26:29]
	v_mfma_f32_16x16x32_bf16 v[22:25], v[222:225], v[176:179], v[22:25]
	v_mfma_f32_16x16x32_bf16 v[18:21], v[230:233], v[176:179], v[18:21]
	v_mfma_f32_16x16x32_bf16 v[14:17], v[222:225], v[206:209], v[14:17]
	v_mfma_f32_16x16x32_bf16 v[10:13], v[230:233], v[206:209], v[10:13]
	v_mfma_f32_16x16x32_bf16 v[6:9], v[222:225], v[214:217], v[6:9]
	v_mfma_f32_16x16x32_bf16 v[2:5], v[230:233], v[214:217], v[2:5]
	v_mfma_f32_16x16x32_bf16 v[30:33], v[226:229], v[172:175], v[30:33]
	v_mfma_f32_16x16x32_bf16 v[26:29], v[234:237], v[172:175], v[26:29]
	v_mfma_f32_16x16x32_bf16 v[22:25], v[226:229], v[180:183], v[22:25]
	v_mfma_f32_16x16x32_bf16 v[18:21], v[234:237], v[180:183], v[18:21]
	v_mfma_f32_16x16x32_bf16 v[14:17], v[226:229], v[210:213], v[14:17]
	v_mfma_f32_16x16x32_bf16 v[10:13], v[234:237], v[210:213], v[10:13]
	v_mfma_f32_16x16x32_bf16 v[6:9], v[226:229], v[218:221], v[6:9]
	s_setprio 2
	s_add_i32 s50, 0, 0x18000
	v_add_u32_e32 v102, s50, v187
	s_barrier
	v_mfma_f32_16x16x32_bf16 v[2:5], v[234:237], v[218:221], v[2:5]
	s_setprio 0
	ds_read_b128 v[90:93], v102
	ds_read_b128 v[94:97], v102 offset:1024
	ds_read_b128 v[98:101], v102 offset:2048
	ds_read_b128 v[102:105], v102 offset:3072
	s_add_u32 s48, s80, 0x160000
	s_addc_u32 s49, s81, 0
	s_mov_b32 m0, s37
	v_lshl_add_u64 v[222:223], s[48:49], 0, v[162:163]
	ds_read_b128 v[168:171], v189 offset:32768
	ds_read_b128 v[172:175], v189 offset:33792
	ds_read_b128 v[176:179], v189 offset:34816
	ds_read_b128 v[180:183], v189 offset:35840
	ds_read_b128 v[206:209], v189 offset:36864
	ds_read_b128 v[210:213], v189 offset:37888
	ds_read_b128 v[214:217], v189 offset:38912
	ds_read_b128 v[218:221], v189 offset:39936
	global_load_lds_dwordx4 v[222:223], off
	v_lshl_add_u64 v[222:223], s[48:49], 0, v[160:161]
	s_mov_b32 m0, s40
	s_nop 0
	global_load_lds_dwordx4 v[222:223], off
	s_waitcnt lgkmcnt(8)
	s_barrier
	s_waitcnt lgkmcnt(0)
	s_setprio 1
	s_waitcnt lgkmcnt(0)
	v_mfma_f32_16x16x32_bf16 v[142:145], v[90:93], v[168:171], v[142:145]
	v_mfma_f32_16x16x32_bf16 v[138:141], v[98:101], v[168:171], v[138:141]
	v_mfma_f32_16x16x32_bf16 v[134:137], v[90:93], v[176:179], v[134:137]
	v_mfma_f32_16x16x32_bf16 v[130:133], v[98:101], v[176:179], v[130:133]
	v_mfma_f32_16x16x32_bf16 v[126:129], v[90:93], v[206:209], v[126:129]
	v_mfma_f32_16x16x32_bf16 v[122:125], v[98:101], v[206:209], v[122:125]
	v_mfma_f32_16x16x32_bf16 v[118:121], v[90:93], v[214:217], v[118:121]
	v_mfma_f32_16x16x32_bf16 v[114:117], v[98:101], v[214:217], v[114:117]
	v_mfma_f32_16x16x32_bf16 v[142:145], v[94:97], v[172:175], v[142:145]
	v_mfma_f32_16x16x32_bf16 v[138:141], v[102:105], v[172:175], v[138:141]
	v_mfma_f32_16x16x32_bf16 v[134:137], v[94:97], v[180:183], v[134:137]
	v_mfma_f32_16x16x32_bf16 v[130:133], v[102:105], v[180:183], v[130:133]
	v_mfma_f32_16x16x32_bf16 v[126:129], v[94:97], v[210:213], v[126:129]
	v_mfma_f32_16x16x32_bf16 v[122:125], v[102:105], v[210:213], v[122:125]
	v_mfma_f32_16x16x32_bf16 v[118:121], v[94:97], v[218:221], v[118:121]
	s_setprio 2
	s_barrier
	v_mfma_f32_16x16x32_bf16 v[114:117], v[102:105], v[218:221], v[114:117]
	s_setprio 0
	s_add_i32 s48, 0, 0x1c000
	s_add_i32 s49, s50, s22
	v_add_u32_e32 v205, s48, v187
	v_lshl_add_u64 v[184:185], v[184:185], 0, s[62:63]
	s_mov_b32 m0, s49
	ds_read_b128 v[222:225], v205
	ds_read_b128 v[226:229], v205 offset:1024
	ds_read_b128 v[230:233], v205 offset:2048
	ds_read_b128 v[234:237], v205 offset:3072
	global_load_lds_dwordx4 v[184:185], off
	v_lshl_add_u64 v[184:185], v[238:239], 0, s[62:63]
	s_add_i32 m0, s49, 0x2000
	s_nop 0
	global_load_lds_dwordx4 v[184:185], off
	s_barrier
	s_waitcnt lgkmcnt(0)
	s_setprio 1
	s_waitcnt lgkmcnt(0)
	v_mfma_f32_16x16x32_bf16 v[62:65], v[222:225], v[168:171], v[62:65]
	v_mfma_f32_16x16x32_bf16 v[58:61], v[230:233], v[168:171], v[58:61]
	v_mfma_f32_16x16x32_bf16 v[54:57], v[222:225], v[176:179], v[54:57]
	v_mfma_f32_16x16x32_bf16 v[50:53], v[230:233], v[176:179], v[50:53]
	v_mfma_f32_16x16x32_bf16 v[46:49], v[222:225], v[206:209], v[46:49]
	v_mfma_f32_16x16x32_bf16 v[42:45], v[230:233], v[206:209], v[42:45]
	v_mfma_f32_16x16x32_bf16 v[38:41], v[222:225], v[214:217], v[38:41]
	v_mfma_f32_16x16x32_bf16 v[34:37], v[230:233], v[214:217], v[34:37]
	v_mfma_f32_16x16x32_bf16 v[62:65], v[226:229], v[172:175], v[62:65]
	v_mfma_f32_16x16x32_bf16 v[58:61], v[234:237], v[172:175], v[58:61]
	v_mfma_f32_16x16x32_bf16 v[54:57], v[226:229], v[180:183], v[54:57]
	v_mfma_f32_16x16x32_bf16 v[50:53], v[234:237], v[180:183], v[50:53]
	v_mfma_f32_16x16x32_bf16 v[46:49], v[226:229], v[210:213], v[46:49]
	v_mfma_f32_16x16x32_bf16 v[42:45], v[234:237], v[210:213], v[42:45]
	v_mfma_f32_16x16x32_bf16 v[38:41], v[226:229], v[218:221], v[38:41]
	s_setprio 2
	s_mov_b32 m0, s28
	v_lshl_add_u64 v[184:185], v[240:241], 0, s[62:63]
	s_barrier
	v_mfma_f32_16x16x32_bf16 v[34:37], v[234:237], v[218:221], v[34:37]
	s_setprio 0
	ds_read_b128 v[168:171], v189 offset:49152
	ds_read_b128 v[172:175], v189 offset:50176
	ds_read_b128 v[176:179], v189 offset:51200
	ds_read_b128 v[180:183], v189 offset:52224
	ds_read_b128 v[206:209], v189 offset:53248
	ds_read_b128 v[210:213], v189 offset:54272
	ds_read_b128 v[214:217], v189 offset:55296
	ds_read_b128 v[218:221], v189 offset:56320
	global_load_lds_dwordx4 v[184:185], off
	v_lshl_add_u64 v[184:185], v[242:243], 0, s[62:63]
	s_mov_b32 m0, s41
	s_nop 0
	global_load_lds_dwordx4 v[184:185], off
	s_barrier
	s_waitcnt lgkmcnt(0)
	s_setprio 1
	s_waitcnt lgkmcnt(0)
	v_mfma_f32_16x16x32_bf16 v[110:113], v[90:93], v[168:171], v[110:113]
	v_mfma_f32_16x16x32_bf16 v[106:109], v[98:101], v[168:171], v[106:109]
	v_mfma_f32_16x16x32_bf16 v[86:89], v[90:93], v[176:179], v[86:89]
	v_mfma_f32_16x16x32_bf16 v[82:85], v[98:101], v[176:179], v[82:85]
	v_mfma_f32_16x16x32_bf16 v[78:81], v[90:93], v[206:209], v[78:81]
	v_mfma_f32_16x16x32_bf16 v[74:77], v[98:101], v[206:209], v[74:77]
	v_mfma_f32_16x16x32_bf16 v[70:73], v[90:93], v[214:217], v[70:73]
	v_mfma_f32_16x16x32_bf16 v[66:69], v[98:101], v[214:217], v[66:69]
	v_mfma_f32_16x16x32_bf16 v[110:113], v[94:97], v[172:175], v[110:113]
	v_mfma_f32_16x16x32_bf16 v[106:109], v[102:105], v[172:175], v[106:109]
	v_mfma_f32_16x16x32_bf16 v[86:89], v[94:97], v[180:183], v[86:89]
	v_mfma_f32_16x16x32_bf16 v[82:85], v[102:105], v[180:183], v[82:85]
	v_mfma_f32_16x16x32_bf16 v[78:81], v[94:97], v[210:213], v[78:81]
	v_mfma_f32_16x16x32_bf16 v[74:77], v[102:105], v[210:213], v[74:77]
	v_mfma_f32_16x16x32_bf16 v[70:73], v[94:97], v[218:221], v[70:73]
	s_setprio 2
	s_barrier
	v_mfma_f32_16x16x32_bf16 v[66:69], v[102:105], v[218:221], v[66:69]
	s_setprio 0
	s_add_u32 s44, s44, 0x160080
	s_addc_u32 s45, s45, 0
	s_add_i32 s48, s48, s22
	v_lshl_add_u64 v[90:91], s[44:45], 0, v[0:1]
	s_mov_b32 m0, s48
	s_nop 0
	global_load_lds_dwordx4 v[90:91], off
	v_lshl_add_u64 v[90:91], s[44:45], 0, v[158:159]
	s_add_i32 m0, s48, 0x2000
	s_nop 0
	global_load_lds_dwordx4 v[90:91], off
	s_waitcnt vmcnt(6)
	s_barrier
	s_setprio 1
	v_mfma_f32_16x16x32_bf16 v[30:33], v[222:225], v[168:171], v[30:33]
	v_mfma_f32_16x16x32_bf16 v[26:29], v[230:233], v[168:171], v[26:29]
	v_mfma_f32_16x16x32_bf16 v[22:25], v[222:225], v[176:179], v[22:25]
	v_mfma_f32_16x16x32_bf16 v[18:21], v[230:233], v[176:179], v[18:21]
	v_mfma_f32_16x16x32_bf16 v[14:17], v[222:225], v[206:209], v[14:17]
	v_mfma_f32_16x16x32_bf16 v[10:13], v[230:233], v[206:209], v[10:13]
	v_mfma_f32_16x16x32_bf16 v[6:9], v[222:225], v[214:217], v[6:9]
	v_mfma_f32_16x16x32_bf16 v[2:5], v[230:233], v[214:217], v[2:5]
	v_mfma_f32_16x16x32_bf16 v[30:33], v[226:229], v[172:175], v[30:33]
	v_mfma_f32_16x16x32_bf16 v[26:29], v[234:237], v[172:175], v[26:29]
	v_mfma_f32_16x16x32_bf16 v[22:25], v[226:229], v[180:183], v[22:25]
	v_mfma_f32_16x16x32_bf16 v[18:21], v[234:237], v[180:183], v[18:21]
	v_mfma_f32_16x16x32_bf16 v[14:17], v[226:229], v[210:213], v[14:17]
	v_mfma_f32_16x16x32_bf16 v[10:13], v[234:237], v[210:213], v[10:13]
	v_mfma_f32_16x16x32_bf16 v[6:9], v[226:229], v[218:221], v[6:9]
	s_setprio 2
	s_add_i32 s47, s47, 2
	s_add_u32 s4, s4, 0x100
	s_addc_u32 s5, s5, 0
	s_cmpk_gt_u32 s47, 0x55
	s_mov_b64 s[64:65], s[68:69]
	s_barrier
	v_mfma_f32_16x16x32_bf16 v[2:5], v[234:237], v[218:221], v[2:5]
	s_setprio 0
	s_cbranch_scc0 .LBB0_1617
	s_lshl_b32 s4, s46, 8
	s_and_b32 s4, s4, 0x3f00
	v_add_u32_e32 v178, s4, v186
	s_ashr_i32 s4, s43, 31
	s_lshr_b32 s4, s4, 29
	s_add_i32 s4, s43, s4
	s_and_b32 s4, s4, 0xfffff8
	s_sub_i32 s4, s43, s4
	v_lshl_or_b32 v172, s4, 8, v188
	v_ashrrev_i32_e32 v173, 31, v172
	v_ashrrev_i32_e32 v179, 31, v178
	v_lshlrev_b32_e32 v170, 12, v178
	v_lshl_add_u32 v170, v172, 1, v170
	v_lshlrev_b32_e32 v171, 3, v178
	v_lshlrev_b32_e32 v174, 2, v172
	global_load_dwordx4 v[98:101], v174, s[74:75]
	global_load_dwordx4 v[90:93], v174, s[74:75] offset:16
	global_load_dwordx4 v[102:105], v174, s[76:77]
	global_load_dwordx4 v[94:97], v174, s[76:77] offset:16
	s_add_u32 s48, s72, 0x0
	s_addc_u32 s49, s73, 0
	global_load_dwordx4 v[220:223], v170, s[48:49]
	s_add_u32 s50, s14, 0x0
	s_addc_u32 s51, s15, 0
	global_load_dwordx2 v[176:177], v171, s[50:51]
	s_add_u32 s48, s72, 0x10000
	s_addc_u32 s49, s73, 0
	global_load_dwordx4 v[224:227], v170, s[48:49]
	s_add_u32 s50, s14, 0x80
	s_addc_u32 s51, s15, 0
	global_load_dwordx2 v[180:181], v171, s[50:51]
	s_add_u32 s48, s72, 0x20000
	s_addc_u32 s49, s73, 0
	global_load_dwordx4 v[228:231], v170, s[48:49]
	s_add_u32 s50, s14, 0x100
	s_addc_u32 s51, s15, 0
	global_load_dwordx2 v[182:183], v171, s[50:51]
	s_add_u32 s48, s72, 0x30000
	s_addc_u32 s49, s73, 0
	global_load_dwordx4 v[232:235], v170, s[48:49]
	s_add_u32 s50, s14, 0x180
	s_addc_u32 s51, s15, 0
	global_load_dwordx2 v[184:185], v171, s[50:51]
	s_add_u32 s48, s72, 0x80000
	s_addc_u32 s49, s73, 0
	global_load_dwordx4 v[236:239], v170, s[48:49]
	s_add_u32 s50, s14, 0x400
	s_addc_u32 s51, s15, 0
	global_load_dwordx2 v[168:169], v171, s[50:51]
	s_add_u32 s48, s72, 0x90000
	s_addc_u32 s49, s73, 0
	global_load_dwordx4 v[240:243], v170, s[48:49]
	s_add_u32 s50, s14, 0x480
	s_addc_u32 s51, s15, 0
	global_load_dwordx2 v[252:253], v171, s[50:51]
	s_add_u32 s48, s72, 0xa0000
	s_addc_u32 s49, s73, 0
	global_load_dwordx4 v[244:247], v170, s[48:49]
	s_add_u32 s50, s14, 0x500
	s_addc_u32 s51, s15, 0
	global_load_dwordx2 v[214:215], v171, s[50:51]
	s_add_u32 s48, s72, 0xb0000
	s_addc_u32 s49, s73, 0
	global_load_dwordx4 v[248:251], v170, s[48:49]
	s_add_u32 s50, s14, 0x580
	s_addc_u32 s51, s15, 0
	global_load_dwordx2 v[216:217], v171, s[50:51]
	s_waitcnt vmcnt(14)
	v_lshlrev_b32_e32 v206, 16, v220
	v_and_b32_e32 v207, 0xffff0000, v220
	v_lshlrev_b32_e32 v208, 16, v221
	v_and_b32_e32 v209, 0xffff0000, v221
	v_lshlrev_b32_e32 v210, 16, v222
	v_and_b32_e32 v211, 0xffff0000, v222
	v_lshlrev_b32_e32 v212, 16, v223
	v_and_b32_e32 v213, 0xffff0000, v223
	v_sub_f32_e32 v206, v206, v176
	v_sub_f32_e32 v207, v207, v176
	v_sub_f32_e32 v208, v208, v176
	v_sub_f32_e32 v209, v209, v176
	v_sub_f32_e32 v210, v210, v176
	v_sub_f32_e32 v211, v211, v176
	v_sub_f32_e32 v212, v212, v176
	v_sub_f32_e32 v213, v213, v176
	v_pk_mul_f32 v[206:207], v[176:177], v[206:207] op_sel:[1,0]
	v_pk_mul_f32 v[208:209], v[176:177], v[208:209] op_sel:[1,0]
	v_pk_mul_f32 v[210:211], v[176:177], v[210:211] op_sel:[1,0]
	v_pk_mul_f32 v[212:213], v[176:177], v[212:213] op_sel:[1,0]
	v_pk_fma_f32 v[206:207], v[98:99], v[206:207], v[102:103]
	v_pk_fma_f32 v[208:209], v[100:101], v[208:209], v[104:105]
	v_pk_fma_f32 v[210:211], v[90:91], v[210:211], v[94:95]
	v_pk_fma_f32 v[212:213], v[92:93], v[212:213], v[96:97]
	v_pk_fma_f32 v[206:207], v[206:207], s[66:67], v[142:143] op_sel_hi:[1,0,1]
	v_pk_fma_f32 v[208:209], v[208:209], s[66:67], v[144:145] op_sel_hi:[1,0,1]
	v_pk_fma_f32 v[210:211], v[210:211], s[66:67], v[138:139] op_sel_hi:[1,0,1]
	v_pk_fma_f32 v[212:213], v[212:213], s[66:67], v[140:141] op_sel_hi:[1,0,1]
	v_cvt_pk_bf16_f32 v220, v206, v207
	v_cvt_pk_bf16_f32 v221, v208, v209
	v_cvt_pk_bf16_f32 v222, v210, v211
	v_cvt_pk_bf16_f32 v223, v212, v213
	s_add_u32 s48, s72, 0x0
	s_addc_u32 s49, s73, 0
	global_store_dwordx4 v170, v[220:223], s[48:49]
	s_waitcnt vmcnt(13)
	v_lshlrev_b32_e32 v206, 16, v224
	v_and_b32_e32 v207, 0xffff0000, v224
	v_lshlrev_b32_e32 v208, 16, v225
	v_and_b32_e32 v209, 0xffff0000, v225
	v_lshlrev_b32_e32 v210, 16, v226
	v_and_b32_e32 v211, 0xffff0000, v226
	v_lshlrev_b32_e32 v212, 16, v227
	v_and_b32_e32 v213, 0xffff0000, v227
	v_sub_f32_e32 v206, v206, v180
	v_sub_f32_e32 v207, v207, v180
	v_sub_f32_e32 v208, v208, v180
	v_sub_f32_e32 v209, v209, v180
	v_sub_f32_e32 v210, v210, v180
	v_sub_f32_e32 v211, v211, v180
	v_sub_f32_e32 v212, v212, v180
	v_sub_f32_e32 v213, v213, v180
	v_pk_mul_f32 v[206:207], v[180:181], v[206:207] op_sel:[1,0]
	v_pk_mul_f32 v[208:209], v[180:181], v[208:209] op_sel:[1,0]
	v_pk_mul_f32 v[210:211], v[180:181], v[210:211] op_sel:[1,0]
	v_pk_mul_f32 v[212:213], v[180:181], v[212:213] op_sel:[1,0]
	v_pk_fma_f32 v[206:207], v[98:99], v[206:207], v[102:103]
	v_pk_fma_f32 v[208:209], v[100:101], v[208:209], v[104:105]
	v_pk_fma_f32 v[210:211], v[90:91], v[210:211], v[94:95]
	v_pk_fma_f32 v[212:213], v[92:93], v[212:213], v[96:97]
	v_pk_fma_f32 v[206:207], v[206:207], s[66:67], v[134:135] op_sel_hi:[1,0,1]
	v_pk_fma_f32 v[208:209], v[208:209], s[66:67], v[136:137] op_sel_hi:[1,0,1]
	v_pk_fma_f32 v[210:211], v[210:211], s[66:67], v[130:131] op_sel_hi:[1,0,1]
	v_pk_fma_f32 v[212:213], v[212:213], s[66:67], v[132:133] op_sel_hi:[1,0,1]
	v_cvt_pk_bf16_f32 v224, v206, v207
	v_cvt_pk_bf16_f32 v225, v208, v209
	v_cvt_pk_bf16_f32 v226, v210, v211
	v_cvt_pk_bf16_f32 v227, v212, v213
	s_add_u32 s48, s72, 0x10000
	s_addc_u32 s49, s73, 0
	global_store_dwordx4 v170, v[224:227], s[48:49]
	s_waitcnt vmcnt(12)
	v_lshlrev_b32_e32 v206, 16, v228
	v_and_b32_e32 v207, 0xffff0000, v228
	v_lshlrev_b32_e32 v208, 16, v229
	v_and_b32_e32 v209, 0xffff0000, v229
	v_lshlrev_b32_e32 v210, 16, v230
	v_and_b32_e32 v211, 0xffff0000, v230
	v_lshlrev_b32_e32 v212, 16, v231
	v_and_b32_e32 v213, 0xffff0000, v231
	v_sub_f32_e32 v206, v206, v182
	v_sub_f32_e32 v207, v207, v182
	v_sub_f32_e32 v208, v208, v182
	v_sub_f32_e32 v209, v209, v182
	v_sub_f32_e32 v210, v210, v182
	v_sub_f32_e32 v211, v211, v182
	v_sub_f32_e32 v212, v212, v182
	v_sub_f32_e32 v213, v213, v182
	v_pk_mul_f32 v[206:207], v[182:183], v[206:207] op_sel:[1,0]
	v_pk_mul_f32 v[208:209], v[182:183], v[208:209] op_sel:[1,0]
	v_pk_mul_f32 v[210:211], v[182:183], v[210:211] op_sel:[1,0]
	v_pk_mul_f32 v[212:213], v[182:183], v[212:213] op_sel:[1,0]
	v_pk_fma_f32 v[206:207], v[98:99], v[206:207], v[102:103]
	v_pk_fma_f32 v[208:209], v[100:101], v[208:209], v[104:105]
	v_pk_fma_f32 v[210:211], v[90:91], v[210:211], v[94:95]
	v_pk_fma_f32 v[212:213], v[92:93], v[212:213], v[96:97]
	v_pk_fma_f32 v[206:207], v[206:207], s[66:67], v[126:127] op_sel_hi:[1,0,1]
	v_pk_fma_f32 v[208:209], v[208:209], s[66:67], v[128:129] op_sel_hi:[1,0,1]
	v_pk_fma_f32 v[210:211], v[210:211], s[66:67], v[122:123] op_sel_hi:[1,0,1]
	v_pk_fma_f32 v[212:213], v[212:213], s[66:67], v[124:125] op_sel_hi:[1,0,1]
	v_cvt_pk_bf16_f32 v228, v206, v207
	v_cvt_pk_bf16_f32 v229, v208, v209
	v_cvt_pk_bf16_f32 v230, v210, v211
	v_cvt_pk_bf16_f32 v231, v212, v213
	s_add_u32 s48, s72, 0x20000
	s_addc_u32 s49, s73, 0
	global_store_dwordx4 v170, v[228:231], s[48:49]
	s_waitcnt vmcnt(11)
	v_lshlrev_b32_e32 v206, 16, v232
	v_and_b32_e32 v207, 0xffff0000, v232
	v_lshlrev_b32_e32 v208, 16, v233
	v_and_b32_e32 v209, 0xffff0000, v233
	v_lshlrev_b32_e32 v210, 16, v234
	v_and_b32_e32 v211, 0xffff0000, v234
	v_lshlrev_b32_e32 v212, 16, v235
	v_and_b32_e32 v213, 0xffff0000, v235
	v_sub_f32_e32 v206, v206, v184
	v_sub_f32_e32 v207, v207, v184
	v_sub_f32_e32 v208, v208, v184
	v_sub_f32_e32 v209, v209, v184
	v_sub_f32_e32 v210, v210, v184
	v_sub_f32_e32 v211, v211, v184
	v_sub_f32_e32 v212, v212, v184
	v_sub_f32_e32 v213, v213, v184
	v_pk_mul_f32 v[206:207], v[184:185], v[206:207] op_sel:[1,0]
	v_pk_mul_f32 v[208:209], v[184:185], v[208:209] op_sel:[1,0]
	v_pk_mul_f32 v[210:211], v[184:185], v[210:211] op_sel:[1,0]
	v_pk_mul_f32 v[212:213], v[184:185], v[212:213] op_sel:[1,0]
	v_pk_fma_f32 v[206:207], v[98:99], v[206:207], v[102:103]
	v_pk_fma_f32 v[208:209], v[100:101], v[208:209], v[104:105]
	v_pk_fma_f32 v[210:211], v[90:91], v[210:211], v[94:95]
	v_pk_fma_f32 v[212:213], v[92:93], v[212:213], v[96:97]
	v_pk_fma_f32 v[206:207], v[206:207], s[66:67], v[118:119] op_sel_hi:[1,0,1]
	v_pk_fma_f32 v[208:209], v[208:209], s[66:67], v[120:121] op_sel_hi:[1,0,1]
	v_pk_fma_f32 v[210:211], v[210:211], s[66:67], v[114:115] op_sel_hi:[1,0,1]
	v_pk_fma_f32 v[212:213], v[212:213], s[66:67], v[116:117] op_sel_hi:[1,0,1]
	v_cvt_pk_bf16_f32 v232, v206, v207
	v_cvt_pk_bf16_f32 v233, v208, v209
	v_cvt_pk_bf16_f32 v234, v210, v211
	v_cvt_pk_bf16_f32 v235, v212, v213
	s_add_u32 s48, s72, 0x30000
	s_addc_u32 s49, s73, 0
	global_store_dwordx4 v170, v[232:235], s[48:49]
	s_waitcnt vmcnt(10)
	v_lshlrev_b32_e32 v206, 16, v236
	v_and_b32_e32 v207, 0xffff0000, v236
	v_lshlrev_b32_e32 v208, 16, v237
	v_and_b32_e32 v209, 0xffff0000, v237
	v_lshlrev_b32_e32 v210, 16, v238
	v_and_b32_e32 v211, 0xffff0000, v238
	v_lshlrev_b32_e32 v212, 16, v239
	v_and_b32_e32 v213, 0xffff0000, v239
	v_sub_f32_e32 v206, v206, v168
	v_sub_f32_e32 v207, v207, v168
	v_sub_f32_e32 v208, v208, v168
	v_sub_f32_e32 v209, v209, v168
	v_sub_f32_e32 v210, v210, v168
	v_sub_f32_e32 v211, v211, v168
	v_sub_f32_e32 v212, v212, v168
	v_sub_f32_e32 v213, v213, v168
	v_pk_mul_f32 v[206:207], v[168:169], v[206:207] op_sel:[1,0]
	v_pk_mul_f32 v[208:209], v[168:169], v[208:209] op_sel:[1,0]
	v_pk_mul_f32 v[210:211], v[168:169], v[210:211] op_sel:[1,0]
	v_pk_mul_f32 v[212:213], v[168:169], v[212:213] op_sel:[1,0]
	v_pk_fma_f32 v[206:207], v[98:99], v[206:207], v[102:103]
	v_pk_fma_f32 v[208:209], v[100:101], v[208:209], v[104:105]
	v_pk_fma_f32 v[210:211], v[90:91], v[210:211], v[94:95]
	v_pk_fma_f32 v[212:213], v[92:93], v[212:213], v[96:97]
	v_pk_fma_f32 v[206:207], v[206:207], s[66:67], v[110:111] op_sel_hi:[1,0,1]
	v_pk_fma_f32 v[208:209], v[208:209], s[66:67], v[112:113] op_sel_hi:[1,0,1]
	v_pk_fma_f32 v[210:211], v[210:211], s[66:67], v[106:107] op_sel_hi:[1,0,1]
	v_pk_fma_f32 v[212:213], v[212:213], s[66:67], v[108:109] op_sel_hi:[1,0,1]
	v_cvt_pk_bf16_f32 v236, v206, v207
	v_cvt_pk_bf16_f32 v237, v208, v209
	v_cvt_pk_bf16_f32 v238, v210, v211
	v_cvt_pk_bf16_f32 v239, v212, v213
	s_add_u32 s48, s72, 0x80000
	s_addc_u32 s49, s73, 0
	global_store_dwordx4 v170, v[236:239], s[48:49]
	s_waitcnt vmcnt(9)
	v_lshlrev_b32_e32 v206, 16, v240
	v_and_b32_e32 v207, 0xffff0000, v240
	v_lshlrev_b32_e32 v208, 16, v241
	v_and_b32_e32 v209, 0xffff0000, v241
	v_lshlrev_b32_e32 v210, 16, v242
	v_and_b32_e32 v211, 0xffff0000, v242
	v_lshlrev_b32_e32 v212, 16, v243
	v_and_b32_e32 v213, 0xffff0000, v243
	v_sub_f32_e32 v206, v206, v252
	v_sub_f32_e32 v207, v207, v252
	v_sub_f32_e32 v208, v208, v252
	v_sub_f32_e32 v209, v209, v252
	v_sub_f32_e32 v210, v210, v252
	v_sub_f32_e32 v211, v211, v252
	v_sub_f32_e32 v212, v212, v252
	v_sub_f32_e32 v213, v213, v252
	v_pk_mul_f32 v[206:207], v[252:253], v[206:207] op_sel:[1,0]
	v_pk_mul_f32 v[208:209], v[252:253], v[208:209] op_sel:[1,0]
	v_pk_mul_f32 v[210:211], v[252:253], v[210:211] op_sel:[1,0]
	v_pk_mul_f32 v[212:213], v[252:253], v[212:213] op_sel:[1,0]
	v_pk_fma_f32 v[206:207], v[98:99], v[206:207], v[102:103]
	v_pk_fma_f32 v[208:209], v[100:101], v[208:209], v[104:105]
	v_pk_fma_f32 v[210:211], v[90:91], v[210:211], v[94:95]
	v_pk_fma_f32 v[212:213], v[92:93], v[212:213], v[96:97]
	v_pk_fma_f32 v[206:207], v[206:207], s[66:67], v[86:87] op_sel_hi:[1,0,1]
	v_pk_fma_f32 v[208:209], v[208:209], s[66:67], v[88:89] op_sel_hi:[1,0,1]
	v_pk_fma_f32 v[210:211], v[210:211], s[66:67], v[82:83] op_sel_hi:[1,0,1]
	v_pk_fma_f32 v[212:213], v[212:213], s[66:67], v[84:85] op_sel_hi:[1,0,1]
	v_cvt_pk_bf16_f32 v240, v206, v207
	v_cvt_pk_bf16_f32 v241, v208, v209
	v_cvt_pk_bf16_f32 v242, v210, v211
	v_cvt_pk_bf16_f32 v243, v212, v213
	s_add_u32 s48, s72, 0x90000
	s_addc_u32 s49, s73, 0
	global_store_dwordx4 v170, v[240:243], s[48:49]
	s_waitcnt vmcnt(8)
	v_lshlrev_b32_e32 v206, 16, v244
	v_and_b32_e32 v207, 0xffff0000, v244
	v_lshlrev_b32_e32 v208, 16, v245
	v_and_b32_e32 v209, 0xffff0000, v245
	v_lshlrev_b32_e32 v210, 16, v246
	v_and_b32_e32 v211, 0xffff0000, v246
	v_lshlrev_b32_e32 v212, 16, v247
	v_and_b32_e32 v213, 0xffff0000, v247
	v_sub_f32_e32 v206, v206, v214
	v_sub_f32_e32 v207, v207, v214
	v_sub_f32_e32 v208, v208, v214
	v_sub_f32_e32 v209, v209, v214
	v_sub_f32_e32 v210, v210, v214
	v_sub_f32_e32 v211, v211, v214
	v_sub_f32_e32 v212, v212, v214
	v_sub_f32_e32 v213, v213, v214
	v_pk_mul_f32 v[206:207], v[214:215], v[206:207] op_sel:[1,0]
	v_pk_mul_f32 v[208:209], v[214:215], v[208:209] op_sel:[1,0]
	v_pk_mul_f32 v[210:211], v[214:215], v[210:211] op_sel:[1,0]
	v_pk_mul_f32 v[212:213], v[214:215], v[212:213] op_sel:[1,0]
	v_pk_fma_f32 v[206:207], v[98:99], v[206:207], v[102:103]
	v_pk_fma_f32 v[208:209], v[100:101], v[208:209], v[104:105]
	v_pk_fma_f32 v[210:211], v[90:91], v[210:211], v[94:95]
	v_pk_fma_f32 v[212:213], v[92:93], v[212:213], v[96:97]
	v_pk_fma_f32 v[206:207], v[206:207], s[66:67], v[78:79] op_sel_hi:[1,0,1]
	v_pk_fma_f32 v[208:209], v[208:209], s[66:67], v[80:81] op_sel_hi:[1,0,1]
	v_pk_fma_f32 v[210:211], v[210:211], s[66:67], v[74:75] op_sel_hi:[1,0,1]
	v_pk_fma_f32 v[212:213], v[212:213], s[66:67], v[76:77] op_sel_hi:[1,0,1]
	v_cvt_pk_bf16_f32 v244, v206, v207
	v_cvt_pk_bf16_f32 v245, v208, v209
	v_cvt_pk_bf16_f32 v246, v210, v211
	v_cvt_pk_bf16_f32 v247, v212, v213
	s_add_u32 s48, s72, 0xa0000
	s_addc_u32 s49, s73, 0
	global_store_dwordx4 v170, v[244:247], s[48:49]
	s_waitcnt vmcnt(7)
	v_lshlrev_b32_e32 v206, 16, v248
	v_and_b32_e32 v207, 0xffff0000, v248
	v_lshlrev_b32_e32 v208, 16, v249
	v_and_b32_e32 v209, 0xffff0000, v249
	v_lshlrev_b32_e32 v210, 16, v250
	v_and_b32_e32 v211, 0xffff0000, v250
	v_lshlrev_b32_e32 v212, 16, v251
	v_and_b32_e32 v213, 0xffff0000, v251
	v_sub_f32_e32 v206, v206, v216
	v_sub_f32_e32 v207, v207, v216
	v_sub_f32_e32 v208, v208, v216
	v_sub_f32_e32 v209, v209, v216
	v_sub_f32_e32 v210, v210, v216
	v_sub_f32_e32 v211, v211, v216
	v_sub_f32_e32 v212, v212, v216
	v_sub_f32_e32 v213, v213, v216
	v_pk_mul_f32 v[206:207], v[216:217], v[206:207] op_sel:[1,0]
	v_pk_mul_f32 v[208:209], v[216:217], v[208:209] op_sel:[1,0]
	v_pk_mul_f32 v[210:211], v[216:217], v[210:211] op_sel:[1,0]
	v_pk_mul_f32 v[212:213], v[216:217], v[212:213] op_sel:[1,0]
	v_pk_fma_f32 v[206:207], v[98:99], v[206:207], v[102:103]
	v_pk_fma_f32 v[208:209], v[100:101], v[208:209], v[104:105]
	v_pk_fma_f32 v[210:211], v[90:91], v[210:211], v[94:95]
	v_pk_fma_f32 v[212:213], v[92:93], v[212:213], v[96:97]
	v_pk_fma_f32 v[206:207], v[206:207], s[66:67], v[70:71] op_sel_hi:[1,0,1]
	v_pk_fma_f32 v[208:209], v[208:209], s[66:67], v[72:73] op_sel_hi:[1,0,1]
	v_pk_fma_f32 v[210:211], v[210:211], s[66:67], v[66:67] op_sel_hi:[1,0,1]
	v_pk_fma_f32 v[212:213], v[212:213], s[66:67], v[68:69] op_sel_hi:[1,0,1]
	v_cvt_pk_bf16_f32 v248, v206, v207
	v_cvt_pk_bf16_f32 v249, v208, v209
	v_cvt_pk_bf16_f32 v250, v210, v211
	v_cvt_pk_bf16_f32 v251, v212, v213
	s_add_u32 s48, s72, 0xb0000
	s_addc_u32 s49, s73, 0
	global_store_dwordx4 v170, v[248:251], s[48:49]
	global_load_dwordx4 v[98:101], v174, s[74:75] offset:512
	global_load_dwordx4 v[90:93], v174, s[74:75] offset:528
	global_load_dwordx4 v[102:105], v174, s[76:77] offset:512
	global_load_dwordx4 v[94:97], v174, s[76:77] offset:528
	s_add_u32 s48, s72, 0x100
	s_addc_u32 s49, s73, 0
	global_load_dwordx4 v[220:223], v170, s[48:49]
	s_add_u32 s50, s14, 0x0
	s_addc_u32 s51, s15, 0
	global_load_dwordx2 v[176:177], v171, s[50:51]
	s_add_u32 s48, s72, 0x10100
	s_addc_u32 s49, s73, 0
	global_load_dwordx4 v[224:227], v170, s[48:49]
	s_add_u32 s50, s14, 0x80
	s_addc_u32 s51, s15, 0
	global_load_dwordx2 v[180:181], v171, s[50:51]
	s_add_u32 s48, s72, 0x20100
	s_addc_u32 s49, s73, 0
	global_load_dwordx4 v[228:231], v170, s[48:49]
	s_add_u32 s50, s14, 0x100
	s_addc_u32 s51, s15, 0
	global_load_dwordx2 v[182:183], v171, s[50:51]
	s_add_u32 s48, s72, 0x30100
	s_addc_u32 s49, s73, 0
	global_load_dwordx4 v[232:235], v170, s[48:49]
	s_add_u32 s50, s14, 0x180
	s_addc_u32 s51, s15, 0
	global_load_dwordx2 v[184:185], v171, s[50:51]
	s_add_u32 s48, s72, 0x80100
	s_addc_u32 s49, s73, 0
	global_load_dwordx4 v[236:239], v170, s[48:49]
	s_add_u32 s50, s14, 0x400
	s_addc_u32 s51, s15, 0
	global_load_dwordx2 v[168:169], v171, s[50:51]
	s_add_u32 s48, s72, 0x90100
	s_addc_u32 s49, s73, 0
	global_load_dwordx4 v[240:243], v170, s[48:49]
	s_add_u32 s50, s14, 0x480
	s_addc_u32 s51, s15, 0
	global_load_dwordx2 v[252:253], v171, s[50:51]
	s_add_u32 s48, s72, 0xa0100
	s_addc_u32 s49, s73, 0
	global_load_dwordx4 v[244:247], v170, s[48:49]
	s_add_u32 s50, s14, 0x500
	s_addc_u32 s51, s15, 0
	global_load_dwordx2 v[214:215], v171, s[50:51]
	s_add_u32 s48, s72, 0xb0100
	s_addc_u32 s49, s73, 0
	global_load_dwordx4 v[248:251], v170, s[48:49]
	s_add_u32 s50, s14, 0x580
	s_addc_u32 s51, s15, 0
	global_load_dwordx2 v[216:217], v171, s[50:51]
	s_waitcnt vmcnt(14)
	v_lshlrev_b32_e32 v206, 16, v220
	v_and_b32_e32 v207, 0xffff0000, v220
	v_lshlrev_b32_e32 v208, 16, v221
	v_and_b32_e32 v209, 0xffff0000, v221
	v_lshlrev_b32_e32 v210, 16, v222
	v_and_b32_e32 v211, 0xffff0000, v222
	v_lshlrev_b32_e32 v212, 16, v223
	v_and_b32_e32 v213, 0xffff0000, v223
	v_sub_f32_e32 v206, v206, v176
	v_sub_f32_e32 v207, v207, v176
	v_sub_f32_e32 v208, v208, v176
	v_sub_f32_e32 v209, v209, v176
	v_sub_f32_e32 v210, v210, v176
	v_sub_f32_e32 v211, v211, v176
	v_sub_f32_e32 v212, v212, v176
	v_sub_f32_e32 v213, v213, v176
	v_pk_mul_f32 v[206:207], v[176:177], v[206:207] op_sel:[1,0]
	v_pk_mul_f32 v[208:209], v[176:177], v[208:209] op_sel:[1,0]
	v_pk_mul_f32 v[210:211], v[176:177], v[210:211] op_sel:[1,0]
	v_pk_mul_f32 v[212:213], v[176:177], v[212:213] op_sel:[1,0]
	v_pk_fma_f32 v[206:207], v[98:99], v[206:207], v[102:103]
	v_pk_fma_f32 v[208:209], v[100:101], v[208:209], v[104:105]
	v_pk_fma_f32 v[210:211], v[90:91], v[210:211], v[94:95]
	v_pk_fma_f32 v[212:213], v[92:93], v[212:213], v[96:97]
	v_pk_fma_f32 v[206:207], v[206:207], s[66:67], v[62:63] op_sel_hi:[1,0,1]
	v_pk_fma_f32 v[208:209], v[208:209], s[66:67], v[64:65] op_sel_hi:[1,0,1]
	v_pk_fma_f32 v[210:211], v[210:211], s[66:67], v[58:59] op_sel_hi:[1,0,1]
	v_pk_fma_f32 v[212:213], v[212:213], s[66:67], v[60:61] op_sel_hi:[1,0,1]
	v_cvt_pk_bf16_f32 v220, v206, v207
	v_cvt_pk_bf16_f32 v221, v208, v209
	v_cvt_pk_bf16_f32 v222, v210, v211
	v_cvt_pk_bf16_f32 v223, v212, v213
	s_add_u32 s48, s72, 0x100
	s_addc_u32 s49, s73, 0
	global_store_dwordx4 v170, v[220:223], s[48:49]
	s_waitcnt vmcnt(13)
	v_lshlrev_b32_e32 v206, 16, v224
	v_and_b32_e32 v207, 0xffff0000, v224
	v_lshlrev_b32_e32 v208, 16, v225
	v_and_b32_e32 v209, 0xffff0000, v225
	v_lshlrev_b32_e32 v210, 16, v226
	v_and_b32_e32 v211, 0xffff0000, v226
	v_lshlrev_b32_e32 v212, 16, v227
	v_and_b32_e32 v213, 0xffff0000, v227
	v_sub_f32_e32 v206, v206, v180
	v_sub_f32_e32 v207, v207, v180
	v_sub_f32_e32 v208, v208, v180
	v_sub_f32_e32 v209, v209, v180
	v_sub_f32_e32 v210, v210, v180
	v_sub_f32_e32 v211, v211, v180
	v_sub_f32_e32 v212, v212, v180
	v_sub_f32_e32 v213, v213, v180
	v_pk_mul_f32 v[206:207], v[180:181], v[206:207] op_sel:[1,0]
	v_pk_mul_f32 v[208:209], v[180:181], v[208:209] op_sel:[1,0]
	v_pk_mul_f32 v[210:211], v[180:181], v[210:211] op_sel:[1,0]
	v_pk_mul_f32 v[212:213], v[180:181], v[212:213] op_sel:[1,0]
	v_pk_fma_f32 v[206:207], v[98:99], v[206:207], v[102:103]
	v_pk_fma_f32 v[208:209], v[100:101], v[208:209], v[104:105]
	v_pk_fma_f32 v[210:211], v[90:91], v[210:211], v[94:95]
	v_pk_fma_f32 v[212:213], v[92:93], v[212:213], v[96:97]
	v_pk_fma_f32 v[206:207], v[206:207], s[66:67], v[54:55] op_sel_hi:[1,0,1]
	v_pk_fma_f32 v[208:209], v[208:209], s[66:67], v[56:57] op_sel_hi:[1,0,1]
	v_pk_fma_f32 v[210:211], v[210:211], s[66:67], v[50:51] op_sel_hi:[1,0,1]
	v_pk_fma_f32 v[212:213], v[212:213], s[66:67], v[52:53] op_sel_hi:[1,0,1]
	v_cvt_pk_bf16_f32 v224, v206, v207
	v_cvt_pk_bf16_f32 v225, v208, v209
	v_cvt_pk_bf16_f32 v226, v210, v211
	v_cvt_pk_bf16_f32 v227, v212, v213
	s_add_u32 s48, s72, 0x10100
	s_addc_u32 s49, s73, 0
	global_store_dwordx4 v170, v[224:227], s[48:49]
	s_waitcnt vmcnt(12)
	v_lshlrev_b32_e32 v206, 16, v228
	v_and_b32_e32 v207, 0xffff0000, v228
	v_lshlrev_b32_e32 v208, 16, v229
	v_and_b32_e32 v209, 0xffff0000, v229
	v_lshlrev_b32_e32 v210, 16, v230
	v_and_b32_e32 v211, 0xffff0000, v230
	v_lshlrev_b32_e32 v212, 16, v231
	v_and_b32_e32 v213, 0xffff0000, v231
	v_sub_f32_e32 v206, v206, v182
	v_sub_f32_e32 v207, v207, v182
	v_sub_f32_e32 v208, v208, v182
	v_sub_f32_e32 v209, v209, v182
	v_sub_f32_e32 v210, v210, v182
	v_sub_f32_e32 v211, v211, v182
	v_sub_f32_e32 v212, v212, v182
	v_sub_f32_e32 v213, v213, v182
	v_pk_mul_f32 v[206:207], v[182:183], v[206:207] op_sel:[1,0]
	v_pk_mul_f32 v[208:209], v[182:183], v[208:209] op_sel:[1,0]
	v_pk_mul_f32 v[210:211], v[182:183], v[210:211] op_sel:[1,0]
	v_pk_mul_f32 v[212:213], v[182:183], v[212:213] op_sel:[1,0]
	v_pk_fma_f32 v[206:207], v[98:99], v[206:207], v[102:103]
	v_pk_fma_f32 v[208:209], v[100:101], v[208:209], v[104:105]
	v_pk_fma_f32 v[210:211], v[90:91], v[210:211], v[94:95]
	v_pk_fma_f32 v[212:213], v[92:93], v[212:213], v[96:97]
	v_pk_fma_f32 v[206:207], v[206:207], s[66:67], v[46:47] op_sel_hi:[1,0,1]
	v_pk_fma_f32 v[208:209], v[208:209], s[66:67], v[48:49] op_sel_hi:[1,0,1]
	v_pk_fma_f32 v[210:211], v[210:211], s[66:67], v[42:43] op_sel_hi:[1,0,1]
	v_pk_fma_f32 v[212:213], v[212:213], s[66:67], v[44:45] op_sel_hi:[1,0,1]
	v_cvt_pk_bf16_f32 v228, v206, v207
	v_cvt_pk_bf16_f32 v229, v208, v209
	v_cvt_pk_bf16_f32 v230, v210, v211
	v_cvt_pk_bf16_f32 v231, v212, v213
	s_add_u32 s48, s72, 0x20100
	s_addc_u32 s49, s73, 0
	global_store_dwordx4 v170, v[228:231], s[48:49]
	s_waitcnt vmcnt(11)
	v_lshlrev_b32_e32 v206, 16, v232
	v_and_b32_e32 v207, 0xffff0000, v232
	v_lshlrev_b32_e32 v208, 16, v233
	v_and_b32_e32 v209, 0xffff0000, v233
	v_lshlrev_b32_e32 v210, 16, v234
	v_and_b32_e32 v211, 0xffff0000, v234
	v_lshlrev_b32_e32 v212, 16, v235
	v_and_b32_e32 v213, 0xffff0000, v235
	v_sub_f32_e32 v206, v206, v184
	v_sub_f32_e32 v207, v207, v184
	v_sub_f32_e32 v208, v208, v184
	v_sub_f32_e32 v209, v209, v184
	v_sub_f32_e32 v210, v210, v184
	v_sub_f32_e32 v211, v211, v184
	v_sub_f32_e32 v212, v212, v184
	v_sub_f32_e32 v213, v213, v184
	v_pk_mul_f32 v[206:207], v[184:185], v[206:207] op_sel:[1,0]
	v_pk_mul_f32 v[208:209], v[184:185], v[208:209] op_sel:[1,0]
	v_pk_mul_f32 v[210:211], v[184:185], v[210:211] op_sel:[1,0]
	v_pk_mul_f32 v[212:213], v[184:185], v[212:213] op_sel:[1,0]
	v_pk_fma_f32 v[206:207], v[98:99], v[206:207], v[102:103]
	v_pk_fma_f32 v[208:209], v[100:101], v[208:209], v[104:105]
	v_pk_fma_f32 v[210:211], v[90:91], v[210:211], v[94:95]
	v_pk_fma_f32 v[212:213], v[92:93], v[212:213], v[96:97]
	v_pk_fma_f32 v[206:207], v[206:207], s[66:67], v[38:39] op_sel_hi:[1,0,1]
	v_pk_fma_f32 v[208:209], v[208:209], s[66:67], v[40:41] op_sel_hi:[1,0,1]
	v_pk_fma_f32 v[210:211], v[210:211], s[66:67], v[34:35] op_sel_hi:[1,0,1]
	v_pk_fma_f32 v[212:213], v[212:213], s[66:67], v[36:37] op_sel_hi:[1,0,1]
	v_cvt_pk_bf16_f32 v232, v206, v207
	v_cvt_pk_bf16_f32 v233, v208, v209
	v_cvt_pk_bf16_f32 v234, v210, v211
	v_cvt_pk_bf16_f32 v235, v212, v213
	s_add_u32 s48, s72, 0x30100
	s_addc_u32 s49, s73, 0
	global_store_dwordx4 v170, v[232:235], s[48:49]
	s_waitcnt vmcnt(10)
	v_lshlrev_b32_e32 v206, 16, v236
	v_and_b32_e32 v207, 0xffff0000, v236
	v_lshlrev_b32_e32 v208, 16, v237
	v_and_b32_e32 v209, 0xffff0000, v237
	v_lshlrev_b32_e32 v210, 16, v238
	v_and_b32_e32 v211, 0xffff0000, v238
	v_lshlrev_b32_e32 v212, 16, v239
	v_and_b32_e32 v213, 0xffff0000, v239
	v_sub_f32_e32 v206, v206, v168
	v_sub_f32_e32 v207, v207, v168
	v_sub_f32_e32 v208, v208, v168
	v_sub_f32_e32 v209, v209, v168
	v_sub_f32_e32 v210, v210, v168
	v_sub_f32_e32 v211, v211, v168
	v_sub_f32_e32 v212, v212, v168
	v_sub_f32_e32 v213, v213, v168
	v_pk_mul_f32 v[206:207], v[168:169], v[206:207] op_sel:[1,0]
	v_pk_mul_f32 v[208:209], v[168:169], v[208:209] op_sel:[1,0]
	v_pk_mul_f32 v[210:211], v[168:169], v[210:211] op_sel:[1,0]
	v_pk_mul_f32 v[212:213], v[168:169], v[212:213] op_sel:[1,0]
	v_pk_fma_f32 v[206:207], v[98:99], v[206:207], v[102:103]
	v_pk_fma_f32 v[208:209], v[100:101], v[208:209], v[104:105]
	v_pk_fma_f32 v[210:211], v[90:91], v[210:211], v[94:95]
	v_pk_fma_f32 v[212:213], v[92:93], v[212:213], v[96:97]
	v_pk_fma_f32 v[206:207], v[206:207], s[66:67], v[30:31] op_sel_hi:[1,0,1]
	v_pk_fma_f32 v[208:209], v[208:209], s[66:67], v[32:33] op_sel_hi:[1,0,1]
	v_pk_fma_f32 v[210:211], v[210:211], s[66:67], v[26:27] op_sel_hi:[1,0,1]
	v_pk_fma_f32 v[212:213], v[212:213], s[66:67], v[28:29] op_sel_hi:[1,0,1]
	v_cvt_pk_bf16_f32 v236, v206, v207
	v_cvt_pk_bf16_f32 v237, v208, v209
	v_cvt_pk_bf16_f32 v238, v210, v211
	v_cvt_pk_bf16_f32 v239, v212, v213
	s_add_u32 s48, s72, 0x80100
	s_addc_u32 s49, s73, 0
	global_store_dwordx4 v170, v[236:239], s[48:49]
	s_waitcnt vmcnt(9)
	v_lshlrev_b32_e32 v206, 16, v240
	v_and_b32_e32 v207, 0xffff0000, v240
	v_lshlrev_b32_e32 v208, 16, v241
	v_and_b32_e32 v209, 0xffff0000, v241
	v_lshlrev_b32_e32 v210, 16, v242
	v_and_b32_e32 v211, 0xffff0000, v242
	v_lshlrev_b32_e32 v212, 16, v243
	v_and_b32_e32 v213, 0xffff0000, v243
	v_sub_f32_e32 v206, v206, v252
	v_sub_f32_e32 v207, v207, v252
	v_sub_f32_e32 v208, v208, v252
	v_sub_f32_e32 v209, v209, v252
	v_sub_f32_e32 v210, v210, v252
	v_sub_f32_e32 v211, v211, v252
	v_sub_f32_e32 v212, v212, v252
	v_sub_f32_e32 v213, v213, v252
	v_pk_mul_f32 v[206:207], v[252:253], v[206:207] op_sel:[1,0]
	v_pk_mul_f32 v[208:209], v[252:253], v[208:209] op_sel:[1,0]
	v_pk_mul_f32 v[210:211], v[252:253], v[210:211] op_sel:[1,0]
	v_pk_mul_f32 v[212:213], v[252:253], v[212:213] op_sel:[1,0]
	v_pk_fma_f32 v[206:207], v[98:99], v[206:207], v[102:103]
	v_pk_fma_f32 v[208:209], v[100:101], v[208:209], v[104:105]
	v_pk_fma_f32 v[210:211], v[90:91], v[210:211], v[94:95]
	v_pk_fma_f32 v[212:213], v[92:93], v[212:213], v[96:97]
	v_pk_fma_f32 v[206:207], v[206:207], s[66:67], v[22:23] op_sel_hi:[1,0,1]
	v_pk_fma_f32 v[208:209], v[208:209], s[66:67], v[24:25] op_sel_hi:[1,0,1]
	v_pk_fma_f32 v[210:211], v[210:211], s[66:67], v[18:19] op_sel_hi:[1,0,1]
	v_pk_fma_f32 v[212:213], v[212:213], s[66:67], v[20:21] op_sel_hi:[1,0,1]
	v_cvt_pk_bf16_f32 v240, v206, v207
	v_cvt_pk_bf16_f32 v241, v208, v209
	v_cvt_pk_bf16_f32 v242, v210, v211
	v_cvt_pk_bf16_f32 v243, v212, v213
	s_add_u32 s48, s72, 0x90100
	s_addc_u32 s49, s73, 0
	global_store_dwordx4 v170, v[240:243], s[48:49]
	s_waitcnt vmcnt(8)
	v_lshlrev_b32_e32 v206, 16, v244
	v_and_b32_e32 v207, 0xffff0000, v244
	v_lshlrev_b32_e32 v208, 16, v245
	v_and_b32_e32 v209, 0xffff0000, v245
	v_lshlrev_b32_e32 v210, 16, v246
	v_and_b32_e32 v211, 0xffff0000, v246
	v_lshlrev_b32_e32 v212, 16, v247
	v_and_b32_e32 v213, 0xffff0000, v247
	v_sub_f32_e32 v206, v206, v214
	v_sub_f32_e32 v207, v207, v214
	v_sub_f32_e32 v208, v208, v214
	v_sub_f32_e32 v209, v209, v214
	v_sub_f32_e32 v210, v210, v214
	v_sub_f32_e32 v211, v211, v214
	v_sub_f32_e32 v212, v212, v214
	v_sub_f32_e32 v213, v213, v214
	v_pk_mul_f32 v[206:207], v[214:215], v[206:207] op_sel:[1,0]
	v_pk_mul_f32 v[208:209], v[214:215], v[208:209] op_sel:[1,0]
	v_pk_mul_f32 v[210:211], v[214:215], v[210:211] op_sel:[1,0]
	v_pk_mul_f32 v[212:213], v[214:215], v[212:213] op_sel:[1,0]
	v_pk_fma_f32 v[206:207], v[98:99], v[206:207], v[102:103]
	v_pk_fma_f32 v[208:209], v[100:101], v[208:209], v[104:105]
	v_pk_fma_f32 v[210:211], v[90:91], v[210:211], v[94:95]
	v_pk_fma_f32 v[212:213], v[92:93], v[212:213], v[96:97]
	v_pk_fma_f32 v[206:207], v[206:207], s[66:67], v[14:15] op_sel_hi:[1,0,1]
	v_pk_fma_f32 v[208:209], v[208:209], s[66:67], v[16:17] op_sel_hi:[1,0,1]
	v_pk_fma_f32 v[210:211], v[210:211], s[66:67], v[10:11] op_sel_hi:[1,0,1]
	v_pk_fma_f32 v[212:213], v[212:213], s[66:67], v[12:13] op_sel_hi:[1,0,1]
	v_cvt_pk_bf16_f32 v244, v206, v207
	v_cvt_pk_bf16_f32 v245, v208, v209
	v_cvt_pk_bf16_f32 v246, v210, v211
	v_cvt_pk_bf16_f32 v247, v212, v213
	s_add_u32 s48, s72, 0xa0100
	s_addc_u32 s49, s73, 0
	global_store_dwordx4 v170, v[244:247], s[48:49]
	s_waitcnt vmcnt(7)
	v_lshlrev_b32_e32 v206, 16, v248
	v_and_b32_e32 v207, 0xffff0000, v248
	v_lshlrev_b32_e32 v208, 16, v249
	v_and_b32_e32 v209, 0xffff0000, v249
	v_lshlrev_b32_e32 v210, 16, v250
	v_and_b32_e32 v211, 0xffff0000, v250
	v_lshlrev_b32_e32 v212, 16, v251
	v_and_b32_e32 v213, 0xffff0000, v251
	v_sub_f32_e32 v206, v206, v216
	v_sub_f32_e32 v207, v207, v216
	v_sub_f32_e32 v208, v208, v216
	v_sub_f32_e32 v209, v209, v216
	v_sub_f32_e32 v210, v210, v216
	v_sub_f32_e32 v211, v211, v216
	v_sub_f32_e32 v212, v212, v216
	v_sub_f32_e32 v213, v213, v216
	v_pk_mul_f32 v[206:207], v[216:217], v[206:207] op_sel:[1,0]
	v_pk_mul_f32 v[208:209], v[216:217], v[208:209] op_sel:[1,0]
	v_pk_mul_f32 v[210:211], v[216:217], v[210:211] op_sel:[1,0]
	v_pk_mul_f32 v[212:213], v[216:217], v[212:213] op_sel:[1,0]
	v_pk_fma_f32 v[206:207], v[98:99], v[206:207], v[102:103]
	v_pk_fma_f32 v[208:209], v[100:101], v[208:209], v[104:105]
	v_pk_fma_f32 v[210:211], v[90:91], v[210:211], v[94:95]
	v_pk_fma_f32 v[212:213], v[92:93], v[212:213], v[96:97]
	v_pk_fma_f32 v[206:207], v[206:207], s[66:67], v[6:7] op_sel_hi:[1,0,1]
	v_pk_fma_f32 v[208:209], v[208:209], s[66:67], v[8:9] op_sel_hi:[1,0,1]
	v_pk_fma_f32 v[210:211], v[210:211], s[66:67], v[2:3] op_sel_hi:[1,0,1]
	v_pk_fma_f32 v[212:213], v[212:213], s[66:67], v[4:5] op_sel_hi:[1,0,1]
	v_cvt_pk_bf16_f32 v248, v206, v207
	v_cvt_pk_bf16_f32 v249, v208, v209
	v_cvt_pk_bf16_f32 v250, v210, v211
	v_cvt_pk_bf16_f32 v251, v212, v213
	s_add_u32 s48, s72, 0xb0100
	s_addc_u32 s49, s73, 0
	global_store_dwordx4 v170, v[248:251], s[48:49]
	s_and_b64 vcc, exec, s[8:9]
	s_mov_b32 s43, s6
	s_mov_b32 s46, s7
	s_mov_b64 s[68:69], s[12:13]
	s_mov_b64 s[64:65], s[10:11]
	s_cbranch_vccz .LBB0_1606
	s_waitcnt vmcnt(0)
	s_cmpk_gt_u32 s19, 0xff
	s_cbranch_scc1 .LBB0_1621
	s_barrier
